# P7 skinny remap + P2/P11 residual-epilogue stores remapped to 4 lanes per row
# baseline (speedup 1.0000x reference)
; __device__ __forceinline__ unsigned cvt_pk_bf16(float lo, float hi) { unsigned r; asm volatile("v_cvt_pk_bf16_f32 %0, %1, %2" : "=v"(r) : "v"(lo), "v"(hi)); return r; }
; __device__ __forceinline__ f32x2 ln_stats(f32x2 sm) { const float mu = sm[0] * (1.f / D); const float var = fmaxf(sm[1] * (1.f / D) - mu * mu, 0.f); return (f32x2){mu, 1.0f / sqrtf(var + LN_EPS)}; }
;     __device__ __forceinline__ void operator()(const f32x4 (&acc)[2][2][4][2], const Unit& u, int wr, int wc, int fr, int fq) const {
;     ...
;                 f32x4 xv[2][2][2]; f32x2 st[2];
; #pragma unroll
;                 for (int mm = 0; mm < 2; ++mm) {
;                     const int r = row0 + ai * HALF + (2 * m2 + mm) * 16;
;                     st[mm] = (f32x2){0.f, 1.f};
;                     if (rin) st[mm] = ln_stats(*(const f32x2*)(rin + 2 * (size_t)r));
; #pragma unroll
;                     for (int bj = 0; bj < 2; ++bj)
; #pragma unroll
;                         for (int n = 0; n < 2; ++n) { const f32x4* rp = (const f32x4*)(res + (size_t)r * D + col0 + bj * HALF + n * 16); xv[mm][bj][n] = stream ? __builtin_nontemporal_load(rp) : *rp; }
;                 }
; #pragma unroll
;                 for (int mm = 0; mm < 2; ++mm) {
;                     const int r = row0 + ai * HALF + (2 * m2 + mm) * 16;
;                     float ps = 0.f, pq = 0.f;
; #pragma unroll
;                     for (int bj = 0; bj < 2; ++bj)
; #pragma unroll
;                         for (int n = 0; n < 2; ++n) {
;                             const f32x4 x = (xv[mm][bj][n] - st[mm][0]) * (gg[bj][n] * st[mm][1]) + bb[bj][n];
;                             const f32x4 o = x * alpha + acc[ai][bj][2 * m2 + mm][n] * scale;
;                             const size_t off = (size_t)r * D + col0 + bj * HALF + n * 16;
;                             *(f32x4*)(Y + off) = o;
;                             if (yb) { u32x2 w; w.x = cvt_pk_bf16(o[0], o[1]); w.y = cvt_pk_bf16(o[2], o[3]); *(u32x2*)(yb + off) = w; }
.LBB0_246:
	v_mbcnt_lo_u32_b32 v246, -1, 0
	v_mbcnt_hi_u32_b32 v246, -1, v246
	v_lshrrev_b32_e32 v247, 2, v246
	v_and_b32_e32 v248, 3, v246
	v_lshl_add_u32 v238, v248, 4, v247
	v_lshlrev_b32_e32 v238, 2, v238
	v_and_b32_e32 v249, 15, v246
	v_sub_u32_e32 v247, v247, v249
	v_lshrrev_b32_e32 v249, 4, v246
	v_sub_u32_e32 v248, v248, v249
	v_mul_i32_i24_e32 v240, 0x2000, v247
	v_lshl_add_u32 v240, v248, 4, v240
	v_ashrrev_i32_e32 v241, 31, v240
	v_mul_i32_i24_e32 v242, 0x1000, v247
	v_lshl_add_u32 v242, v248, 3, v242
	v_ashrrev_i32_e32 v243, 31, v242
	v_lshl_or_b32 v156, s88, 8, v168
	v_lshl_add_u32 v158, s87, 8, v166
	v_readlane_b32 s60, v254, 45
	v_ashrrev_i32_e32 v157, 31, v156
	v_readlane_b32 s61, v254, 46
	v_ashrrev_i32_e32 v159, 31, v158
	v_lshlrev_b64 v[124:125], 13, v[158:159]
	v_lshl_add_u64 v[160:161], v[156:157], 2, s[60:61]
	v_lshl_add_u64 v[124:125], v[160:161], 0, v[124:125]
	global_load_dwordx4 v[182:185], v[124:125], off
	global_load_dwordx4 v[186:189], v[124:125], off offset:64
	global_load_dwordx4 v[190:193], v[124:125], off offset:512
	global_load_dwordx4 v[144:147], v[124:125], off offset:576
	v_or_b32_e32 v162, 16, v158
	v_ashrrev_i32_e32 v163, 31, v162
	v_lshlrev_b64 v[124:125], 13, v[162:163]
	v_lshl_add_u64 v[124:125], v[160:161], 0, v[124:125]
	global_load_dwordx4 v[140:143], v[124:125], off
	global_load_dwordx4 v[136:139], v[124:125], off offset:64
	global_load_dwordx4 v[132:135], v[124:125], off offset:512
	s_nop 0
	global_load_dwordx4 v[124:127], v[124:125], off offset:576
	v_lshlrev_b64 v[164:165], 11, v[158:159]
	v_lshl_add_u64 v[164:165], v[164:165], 0, v[156:157]
	v_readlane_b32 s62, v254, 47
	v_readlane_b32 s63, v254, 48
	v_readlane_b32 s64, v254, 49
	v_readlane_b32 s65, v254, 50
	v_readlane_b32 s66, v254, 51
	v_readlane_b32 s67, v254, 52
	v_readlane_b32 s68, v254, 53
	v_readlane_b32 s69, v254, 54
	v_readlane_b32 s70, v254, 55
	v_readlane_b32 s71, v254, 56
	v_readlane_b32 s72, v254, 57
	v_readlane_b32 s73, v254, 58
	v_readlane_b32 s74, v254, 59
	v_readlane_b32 s75, v254, 60
	s_waitcnt vmcnt(0)
	v_pk_add_f32 v[174:175], v[184:185], 0 op_sel_hi:[1,0]
	v_pk_add_f32 v[182:183], v[182:183], 0 op_sel_hi:[1,0]
	v_pk_mul_f32 v[174:175], v[174:175], s[12:13] op_sel_hi:[1,0]
	v_pk_mul_f32 v[182:183], v[182:183], s[12:13] op_sel_hi:[1,0]
	v_pk_fma_f32 v[130:131], v[130:131], 0.5, v[174:175] op_sel_hi:[1,0,1]
	v_pk_fma_f32 v[128:129], v[128:129], 0.5, v[182:183] op_sel_hi:[1,0,1]
	v_lshl_add_u64 v[174:175], v[164:165], 2, s[38:39]
	ds_bpermute_b32 v246, v238, v128
	ds_bpermute_b32 v247, v238, v129
	ds_bpermute_b32 v248, v238, v130
	ds_bpermute_b32 v249, v238, v131
	v_lshl_add_u64 v[244:245], v[174:175], 0, v[240:241]
	s_waitcnt lgkmcnt(0)
	global_store_dwordx4 v[244:245], v[246:249], off
	v_cvt_pk_bf16_f32 v174, v128, v129
	v_add_f32_e32 v173, v128, v129
	v_lshl_add_u64 v[182:183], v[164:165], 1, s[58:59]
	v_mul_f32_e32 v129, v129, v129
	v_fmac_f32_e32 v129, v128, v128
	v_mul_f32_e32 v128, v130, v130
	v_cvt_pk_bf16_f32 v175, v130, v131
	ds_bpermute_b32 v250, v238, v174
	ds_bpermute_b32 v251, v238, v175
	v_lshl_add_u64 v[244:245], v[182:183], 0, v[242:243]
	s_waitcnt lgkmcnt(0)
	global_store_dwordx2 v[244:245], v[250:251], off
	v_add_f32_e32 v174, v131, v130
	v_fmac_f32_e32 v128, v131, v131
	v_add_f32_e32 v173, v173, v174
	v_add_f32_e32 v174, v129, v128
	v_pk_add_f32 v[128:129], v[188:189], 0 op_sel_hi:[1,0]
	v_pk_add_f32 v[130:131], v[186:187], 0 op_sel_hi:[1,0]
	v_pk_mul_f32 v[128:129], v[128:129], s[12:13] op_sel_hi:[1,0]
	v_pk_mul_f32 v[130:131], v[130:131], s[12:13] op_sel_hi:[1,0]
	v_pk_fma_f32 v[122:123], v[122:123], 0.5, v[128:129] op_sel_hi:[1,0,1]
	v_or_b32_e32 v128, 16, v164
	v_mov_b32_e32 v129, v165
	v_pk_fma_f32 v[120:121], v[120:121], 0.5, v[130:131] op_sel_hi:[1,0,1]
	v_lshl_add_u64 v[130:131], v[128:129], 2, s[38:39]
	v_lshl_add_u64 v[128:129], v[128:129], 1, s[58:59]
	ds_bpermute_b32 v246, v238, v120
	ds_bpermute_b32 v247, v238, v121
	ds_bpermute_b32 v248, v238, v122
	ds_bpermute_b32 v249, v238, v123
	v_lshl_add_u64 v[244:245], v[130:131], 0, v[240:241]
	s_waitcnt lgkmcnt(0)
	global_store_dwordx4 v[244:245], v[246:249], off
	v_cvt_pk_bf16_f32 v130, v120, v121
	v_cvt_pk_bf16_f32 v131, v122, v123
	ds_bpermute_b32 v250, v238, v130
	ds_bpermute_b32 v251, v238, v131
	v_lshl_add_u64 v[244:245], v[128:129], 0, v[242:243]
	s_waitcnt lgkmcnt(0)
	global_store_dwordx2 v[244:245], v[250:251], off
	v_add_f32_e32 v128, v120, v121
	v_mul_f32_e32 v121, v121, v121
	v_add_f32_e32 v129, v123, v122
	v_fmac_f32_e32 v121, v120, v120
	v_mul_f32_e32 v120, v122, v122
	v_add_f32_e32 v173, 0, v173
	v_add_f32_e32 v128, v128, v129
	v_fmac_f32_e32 v120, v123, v123
	v_add_f32_e32 v130, v173, v128
	v_add_f32_e32 v120, v121, v120
	v_pk_add_f32 v[122:123], v[192:193], 0 op_sel_hi:[1,0]
	v_pk_add_f32 v[128:129], v[190:191], 0 op_sel_hi:[1,0]
	v_add_f32_e32 v131, v174, v120
	v_or_b32_e32 v120, 0x80, v164
	v_mov_b32_e32 v121, v165
	v_pk_mul_f32 v[122:123], v[122:123], s[12:13] op_sel_hi:[1,0]
	v_pk_mul_f32 v[128:129], v[128:129], s[12:13] op_sel_hi:[1,0]
	v_pk_fma_f32 v[118:119], v[118:119], 0.5, v[122:123] op_sel_hi:[1,0,1]
	v_pk_fma_f32 v[116:117], v[116:117], 0.5, v[128:129] op_sel_hi:[1,0,1]
	v_lshl_add_u64 v[122:123], v[120:121], 2, s[38:39]
	v_lshl_add_u64 v[120:121], v[120:121], 1, s[58:59]
	ds_bpermute_b32 v246, v238, v116
	ds_bpermute_b32 v247, v238, v117
	ds_bpermute_b32 v248, v238, v118
	ds_bpermute_b32 v249, v238, v119
	v_lshl_add_u64 v[244:245], v[122:123], 0, v[240:241]
	s_waitcnt lgkmcnt(0)
	global_store_dwordx4 v[244:245], v[246:249], off
	v_cvt_pk_bf16_f32 v122, v116, v117
	v_cvt_pk_bf16_f32 v123, v118, v119
	ds_bpermute_b32 v250, v238, v122
	ds_bpermute_b32 v251, v238, v123
	v_lshl_add_u64 v[244:245], v[120:121], 0, v[242:243]
	s_waitcnt lgkmcnt(0)
; __device__ __forceinline__ unsigned cvt_pk_bf16(float lo, float hi) { unsigned r; asm volatile("v_cvt_pk_bf16_f32 %0, %1, %2" : "=v"(r) : "v"(lo), "v"(hi)); return r; }
;     __device__ __forceinline__ void operator()(const f32x4 (&acc)[2][2][4][2], const Unit& u, int wr, int wc, int fr, int fq) const {
;     ...
;                 for (int mm = 0; mm < 2; ++mm) {
;                     const int r = row0 + ai * HALF + (2 * m2 + mm) * 16;
;                     float ps = 0.f, pq = 0.f;
; #pragma unroll
;                     for (int bj = 0; bj < 2; ++bj)
; #pragma unroll
;                         for (int n = 0; n < 2; ++n) {
;                             const f32x4 x = (xv[mm][bj][n] - st[mm][0]) * (gg[bj][n] * st[mm][1]) + bb[bj][n];
;                             const f32x4 o = x * alpha + acc[ai][bj][2 * m2 + mm][n] * scale;
;                             const size_t off = (size_t)r * D + col0 + bj * HALF + n * 16;
;                             *(f32x4*)(Y + off) = o;
;                             if (yb) { u32x2 w; w.x = cvt_pk_bf16(o[0], o[1]); w.y = cvt_pk_bf16(o[2], o[3]); *(u32x2*)(yb + off) = w; }
;                             ps += (o[0] + o[1]) + (o[2] + o[3]); pq += (o[0] * o[0] + o[1] * o[1]) + (o[2] * o[2] + o[3] * o[3]);
;                         }
;                     if (rout) {
;                         ps += __shfl_xor(ps, 16); pq += __shfl_xor(pq, 16); ps += __shfl_xor(ps, 32); pq += __shfl_xor(pq, 32);
;                         if (fq == 0) { atomicAdd(rout + 2 * (size_t)r, ps); atomicAdd(rout + 2 * (size_t)r + 1, pq); }
	global_store_dwordx2 v[244:245], v[250:251], off
	v_add_f32_e32 v120, v116, v117
	v_mul_f32_e32 v117, v117, v117
	v_fmac_f32_e32 v117, v116, v116
	v_mul_f32_e32 v116, v118, v118
	v_fmac_f32_e32 v116, v119, v119
	v_add_f32_e32 v121, v119, v118
	v_add_f32_e32 v116, v117, v116
	v_add_f32_e32 v120, v120, v121
	v_add_f32_e32 v121, v131, v116
	v_pk_add_f32 v[116:117], v[146:147], 0 op_sel_hi:[1,0]
	v_pk_add_f32 v[118:119], v[144:145], 0 op_sel_hi:[1,0]
	v_pk_mul_f32 v[116:117], v[116:117], s[12:13] op_sel_hi:[1,0]
	v_pk_mul_f32 v[118:119], v[118:119], s[12:13] op_sel_hi:[1,0]
	v_or_b32_e32 v164, 0x90, v164
	v_pk_fma_f32 v[114:115], v[114:115], 0.5, v[116:117] op_sel_hi:[1,0,1]
	v_pk_fma_f32 v[112:113], v[112:113], 0.5, v[118:119] op_sel_hi:[1,0,1]
	v_lshl_add_u64 v[116:117], v[164:165], 2, s[38:39]
	ds_bpermute_b32 v246, v238, v112
	ds_bpermute_b32 v247, v238, v113
	ds_bpermute_b32 v248, v238, v114
	ds_bpermute_b32 v249, v238, v115
	v_lshl_add_u64 v[244:245], v[116:117], 0, v[240:241]
	s_waitcnt lgkmcnt(0)
	global_store_dwordx4 v[244:245], v[246:249], off
	v_cvt_pk_bf16_f32 v116, v112, v113
	v_lshl_add_u64 v[118:119], v[164:165], 1, s[58:59]
	v_cvt_pk_bf16_f32 v117, v114, v115
	ds_bpermute_b32 v250, v238, v116
	ds_bpermute_b32 v251, v238, v117
	v_lshl_add_u64 v[244:245], v[118:119], 0, v[242:243]
	s_waitcnt lgkmcnt(0)
	global_store_dwordx2 v[244:245], v[250:251], off
	v_mul_f32_e32 v116, v113, v113
	v_fmac_f32_e32 v116, v112, v112
	v_mul_f32_e32 v117, v114, v114
	v_add_f32_e32 v112, v112, v113
	v_add_f32_e32 v113, v115, v114
	v_and_b32_e32 v114, 64, v172
	v_add_f32_e32 v112, v112, v113
	v_xor_b32_e32 v113, 16, v172
	v_add_u32_e32 v114, 64, v114
	v_cmp_lt_i32_e32 vcc, v113, v114
	v_add_f32_e32 v120, v130, v120
	v_add_f32_e32 v112, v120, v112
	v_cndmask_b32_e32 v113, v172, v113, vcc
	v_lshlrev_b32_e32 v122, 2, v113
	ds_bpermute_b32 v113, v122, v112
	v_fmac_f32_e32 v117, v115, v115
	v_add_f32_e32 v116, v116, v117
	v_add_f32_e32 v116, v121, v116
	v_xor_b32_e32 v115, 32, v172
	s_waitcnt lgkmcnt(0)
	v_add_f32_e32 v112, v112, v113
	ds_bpermute_b32 v113, v122, v116
	v_cmp_lt_i32_e32 vcc, v115, v114
	s_waitcnt lgkmcnt(0)
	v_add_f32_e32 v113, v116, v113
	v_cndmask_b32_e32 v114, v172, v115, vcc
	v_lshlrev_b32_e32 v123, 2, v114
	ds_bpermute_b32 v114, v123, v112
	ds_bpermute_b32 v115, v123, v113
	s_and_saveexec_b64 s[20:21], s[4:5]
	s_cbranch_execz .LBB0_248
	v_lshl_add_u64 v[116:117], v[158:159], 3, s[54:55]
	s_waitcnt lgkmcnt(1)
	v_add_f32_e32 v112, v112, v114
	s_waitcnt lgkmcnt(0)
	v_add_f32_e32 v113, v113, v115
	global_atomic_add_f32 v[116:117], v112, off
	global_atomic_add_f32 v[116:117], v113, off offset:4
.LBB0_248:
	s_or_b64 exec, exec, s[20:21]
	v_lshlrev_b64 v[112:113], 11, v[162:163]
	s_waitcnt lgkmcnt(0)
	v_pk_add_f32 v[114:115], v[142:143], 0 op_sel_hi:[1,0]
	v_pk_add_f32 v[116:117], v[140:141], 0 op_sel_hi:[1,0]
	v_lshl_add_u64 v[112:113], v[112:113], 0, v[156:157]
	v_pk_mul_f32 v[114:115], v[114:115], s[12:13] op_sel_hi:[1,0]
	v_pk_mul_f32 v[116:117], v[116:117], s[12:13] op_sel_hi:[1,0]
	v_pk_fma_f32 v[110:111], v[110:111], 0.5, v[114:115] op_sel_hi:[1,0,1]
	v_pk_fma_f32 v[108:109], v[108:109], 0.5, v[116:117] op_sel_hi:[1,0,1]
	v_lshl_add_u64 v[114:115], v[112:113], 2, s[38:39]
	ds_bpermute_b32 v246, v238, v108
	ds_bpermute_b32 v247, v238, v109
	ds_bpermute_b32 v248, v238, v110
	ds_bpermute_b32 v249, v238, v111
	v_lshl_add_u64 v[244:245], v[114:115], 0, v[240:241]
	s_waitcnt lgkmcnt(0)
	global_store_dwordx4 v[244:245], v[246:249], off
	v_cvt_pk_bf16_f32 v114, v108, v109
	v_lshl_add_u64 v[116:117], v[112:113], 1, s[58:59]
	v_cvt_pk_bf16_f32 v115, v110, v111
	ds_bpermute_b32 v250, v238, v114
	ds_bpermute_b32 v251, v238, v115
	v_lshl_add_u64 v[244:245], v[116:117], 0, v[242:243]
	s_waitcnt lgkmcnt(0)
	global_store_dwordx2 v[244:245], v[250:251], off
	v_add_f32_e32 v114, v108, v109
	v_mul_f32_e32 v109, v109, v109
	v_fmac_f32_e32 v109, v108, v108
	v_mul_f32_e32 v108, v110, v110
	v_add_f32_e32 v115, v111, v110
	v_fmac_f32_e32 v108, v111, v111
	v_add_f32_e32 v114, v114, v115
	v_add_f32_e32 v115, v109, v108
	v_pk_add_f32 v[108:109], v[138:139], 0 op_sel_hi:[1,0]
	v_pk_add_f32 v[110:111], v[136:137], 0 op_sel_hi:[1,0]
	v_pk_mul_f32 v[108:109], v[108:109], s[12:13] op_sel_hi:[1,0]
	v_pk_mul_f32 v[110:111], v[110:111], s[12:13] op_sel_hi:[1,0]
	v_pk_fma_f32 v[106:107], v[106:107], 0.5, v[108:109] op_sel_hi:[1,0,1]
	v_or_b32_e32 v108, 16, v112
	v_mov_b32_e32 v109, v113
	v_pk_fma_f32 v[104:105], v[104:105], 0.5, v[110:111] op_sel_hi:[1,0,1]
	v_lshl_add_u64 v[110:111], v[108:109], 2, s[38:39]
	v_lshl_add_u64 v[108:109], v[108:109], 1, s[58:59]
	ds_bpermute_b32 v246, v238, v104
	ds_bpermute_b32 v247, v238, v105
	ds_bpermute_b32 v248, v238, v106
	ds_bpermute_b32 v249, v238, v107
	v_lshl_add_u64 v[244:245], v[110:111], 0, v[240:241]
	s_waitcnt lgkmcnt(0)
	global_store_dwordx4 v[244:245], v[246:249], off
	v_cvt_pk_bf16_f32 v110, v104, v105
	v_cvt_pk_bf16_f32 v111, v106, v107
	ds_bpermute_b32 v250, v238, v110
	ds_bpermute_b32 v251, v238, v111
	v_lshl_add_u64 v[244:245], v[108:109], 0, v[242:243]
	s_waitcnt lgkmcnt(0)
; __device__ __forceinline__ unsigned cvt_pk_bf16(float lo, float hi) { unsigned r; asm volatile("v_cvt_pk_bf16_f32 %0, %1, %2" : "=v"(r) : "v"(lo), "v"(hi)); return r; }
;     __device__ __forceinline__ void operator()(const f32x4 (&acc)[2][2][4][2], const Unit& u, int wr, int wc, int fr, int fq) const {
;     ...
;                 f32x4 xv[2][2][2]; f32x2 st[2];
; #pragma unroll
;                 for (int mm = 0; mm < 2; ++mm) {
;                     const int r = row0 + ai * HALF + (2 * m2 + mm) * 16;
;                     st[mm] = (f32x2){0.f, 1.f};
;                     if (rin) st[mm] = ln_stats(*(const f32x2*)(rin + 2 * (size_t)r));
; #pragma unroll
;                     for (int bj = 0; bj < 2; ++bj)
; #pragma unroll
;                         for (int n = 0; n < 2; ++n) { const f32x4* rp = (const f32x4*)(res + (size_t)r * D + col0 + bj * HALF + n * 16); xv[mm][bj][n] = stream ? __builtin_nontemporal_load(rp) : *rp; }
;                 }
; #pragma unroll
;                 for (int mm = 0; mm < 2; ++mm) {
;                     const int r = row0 + ai * HALF + (2 * m2 + mm) * 16;
;                     float ps = 0.f, pq = 0.f;
; #pragma unroll
;                     for (int bj = 0; bj < 2; ++bj)
; #pragma unroll
;                         for (int n = 0; n < 2; ++n) {
;                             const f32x4 x = (xv[mm][bj][n] - st[mm][0]) * (gg[bj][n] * st[mm][1]) + bb[bj][n];
;                             const f32x4 o = x * alpha + acc[ai][bj][2 * m2 + mm][n] * scale;
;                             const size_t off = (size_t)r * D + col0 + bj * HALF + n * 16;
;                             *(f32x4*)(Y + off) = o;
;                             if (yb) { u32x2 w; w.x = cvt_pk_bf16(o[0], o[1]); w.y = cvt_pk_bf16(o[2], o[3]); *(u32x2*)(yb + off) = w; }
;                             ps += (o[0] + o[1]) + (o[2] + o[3]); pq += (o[0] * o[0] + o[1] * o[1]) + (o[2] * o[2] + o[3] * o[3]);
;                         }
;                     if (rout) {
;                         ps += __shfl_xor(ps, 16); pq += __shfl_xor(pq, 16); ps += __shfl_xor(ps, 32); pq += __shfl_xor(pq, 32);
;                         if (fq == 0) { atomicAdd(rout + 2 * (size_t)r, ps); atomicAdd(rout + 2 * (size_t)r + 1, pq); }
	global_store_dwordx2 v[244:245], v[250:251], off
	v_add_f32_e32 v108, v104, v105
	v_mul_f32_e32 v105, v105, v105
	v_add_f32_e32 v109, v107, v106
	v_fmac_f32_e32 v105, v104, v104
	v_mul_f32_e32 v104, v106, v106
	v_add_f32_e32 v114, 0, v114
	v_add_f32_e32 v108, v108, v109
	v_fmac_f32_e32 v104, v107, v107
	v_add_f32_e32 v110, v114, v108
	v_add_f32_e32 v104, v105, v104
	v_pk_add_f32 v[106:107], v[134:135], 0 op_sel_hi:[1,0]
	v_pk_add_f32 v[108:109], v[132:133], 0 op_sel_hi:[1,0]
	v_add_f32_e32 v111, v115, v104
	v_or_b32_e32 v104, 0x80, v112
	v_mov_b32_e32 v105, v113
	v_pk_mul_f32 v[106:107], v[106:107], s[12:13] op_sel_hi:[1,0]
	v_pk_mul_f32 v[108:109], v[108:109], s[12:13] op_sel_hi:[1,0]
	v_pk_fma_f32 v[102:103], v[102:103], 0.5, v[106:107] op_sel_hi:[1,0,1]
	v_pk_fma_f32 v[100:101], v[100:101], 0.5, v[108:109] op_sel_hi:[1,0,1]
	v_lshl_add_u64 v[106:107], v[104:105], 2, s[38:39]
	v_lshl_add_u64 v[104:105], v[104:105], 1, s[58:59]
	ds_bpermute_b32 v246, v238, v100
	ds_bpermute_b32 v247, v238, v101
	ds_bpermute_b32 v248, v238, v102
	ds_bpermute_b32 v249, v238, v103
	v_lshl_add_u64 v[244:245], v[106:107], 0, v[240:241]
	s_waitcnt lgkmcnt(0)
	global_store_dwordx4 v[244:245], v[246:249], off
	v_cvt_pk_bf16_f32 v106, v100, v101
	v_cvt_pk_bf16_f32 v107, v102, v103
	ds_bpermute_b32 v250, v238, v106
	ds_bpermute_b32 v251, v238, v107
	v_lshl_add_u64 v[244:245], v[104:105], 0, v[242:243]
	s_waitcnt lgkmcnt(0)
	global_store_dwordx2 v[244:245], v[250:251], off
	v_add_f32_e32 v104, v100, v101
	v_mul_f32_e32 v101, v101, v101
	v_fmac_f32_e32 v101, v100, v100
	v_mul_f32_e32 v100, v102, v102
	v_fmac_f32_e32 v100, v103, v103
	v_add_f32_e32 v105, v103, v102
	v_add_f32_e32 v100, v101, v100
	v_add_f32_e32 v104, v104, v105
	v_add_f32_e32 v107, v111, v100
	v_pk_add_f32 v[100:101], v[126:127], 0 op_sel_hi:[1,0]
	v_pk_add_f32 v[102:103], v[124:125], 0 op_sel_hi:[1,0]
	v_add_f32_e32 v106, v110, v104
	v_pk_mul_f32 v[100:101], v[100:101], s[12:13] op_sel_hi:[1,0]
	v_pk_mul_f32 v[104:105], v[102:103], s[12:13] op_sel_hi:[1,0]
	v_pk_fma_f32 v[102:103], v[98:99], 0.5, v[100:101] op_sel_hi:[1,0,1]
	v_pk_fma_f32 v[100:101], v[96:97], 0.5, v[104:105] op_sel_hi:[1,0,1]
	v_mul_f32_e32 v97, v102, v102
	v_mul_f32_e32 v96, v101, v101
	v_fmac_f32_e32 v96, v100, v100
	v_fmac_f32_e32 v97, v103, v103
	v_add_f32_e32 v96, v96, v97
	v_add_f32_e32 v98, v107, v96
	v_add_f32_e32 v96, v100, v101
	v_add_f32_e32 v97, v103, v102
	v_add_f32_e32 v96, v96, v97
	v_add_f32_e32 v99, v106, v96
	ds_bpermute_b32 v104, v122, v99
	ds_bpermute_b32 v105, v122, v98
	v_or_b32_e32 v112, 0x90, v112
	v_lshl_add_u64 v[96:97], v[112:113], 2, s[38:39]
	ds_bpermute_b32 v246, v238, v100
	ds_bpermute_b32 v247, v238, v101
	ds_bpermute_b32 v248, v238, v102
	ds_bpermute_b32 v249, v238, v103
	v_lshl_add_u64 v[244:245], v[96:97], 0, v[240:241]
	s_waitcnt lgkmcnt(0)
	global_store_dwordx4 v[244:245], v[246:249], off
	s_waitcnt lgkmcnt(1)
	v_add_f32_e32 v96, v99, v104
	s_waitcnt lgkmcnt(0)
	v_add_f32_e32 v97, v98, v105
	ds_bpermute_b32 v98, v123, v96
	ds_bpermute_b32 v99, v123, v97
	v_cvt_pk_bf16_f32 v100, v100, v101
	v_cvt_pk_bf16_f32 v101, v102, v103
	v_lshl_add_u64 v[102:103], v[112:113], 1, s[58:59]
	ds_bpermute_b32 v250, v238, v100
	ds_bpermute_b32 v251, v238, v101
	v_lshl_add_u64 v[244:245], v[102:103], 0, v[242:243]
	s_waitcnt lgkmcnt(0)
	global_store_dwordx2 v[244:245], v[250:251], off
	s_and_saveexec_b64 s[20:21], s[4:5]
	s_cbranch_execz .LBB0_250
	v_lshl_add_u64 v[100:101], v[162:163], 3, s[54:55]
	s_waitcnt lgkmcnt(1)
	v_add_f32_e32 v96, v96, v98
	s_waitcnt lgkmcnt(0)
	v_add_f32_e32 v97, v97, v99
	global_atomic_add_f32 v[100:101], v96, off
	global_atomic_add_f32 v[100:101], v97, off offset:4
.LBB0_250:
	s_or_b64 exec, exec, s[20:21]
	v_or_b32_e32 v118, 32, v158
	v_ashrrev_i32_e32 v119, 31, v118
	v_lshlrev_b64 v[96:97], 13, v[118:119]
	v_lshl_add_u64 v[96:97], v[160:161], 0, v[96:97]
	global_load_dwordx4 v[124:127], v[96:97], off
	global_load_dwordx4 v[128:131], v[96:97], off offset:64
	global_load_dwordx4 v[132:135], v[96:97], off offset:512
	global_load_dwordx4 v[112:115], v[96:97], off offset:576
	v_or_b32_e32 v116, 48, v158
	v_ashrrev_i32_e32 v117, 31, v116
	v_lshlrev_b64 v[96:97], 13, v[116:117]
	v_lshl_add_u64 v[96:97], v[160:161], 0, v[96:97]
	global_load_dwordx4 v[108:111], v[96:97], off
	global_load_dwordx4 v[104:107], v[96:97], off offset:64
	global_load_dwordx4 v[100:103], v[96:97], off offset:512
	s_waitcnt lgkmcnt(0)
	global_load_dwordx4 v[96:99], v[96:97], off offset:576
	v_lshlrev_b64 v[120:121], 11, v[118:119]
	v_lshl_add_u64 v[120:121], v[120:121], 0, v[156:157]
	s_waitcnt vmcnt(7)
	v_pk_add_f32 v[126:127], v[126:127], 0 op_sel_hi:[1,0]
	v_pk_add_f32 v[124:125], v[124:125], 0 op_sel_hi:[1,0]
	v_pk_mul_f32 v[126:127], v[126:127], s[12:13] op_sel_hi:[1,0]
	v_pk_mul_f32 v[124:125], v[124:125], s[12:13] op_sel_hi:[1,0]
	v_pk_fma_f32 v[94:95], v[94:95], 0.5, v[126:127] op_sel_hi:[1,0,1]
	v_pk_fma_f32 v[92:93], v[92:93], 0.5, v[124:125] op_sel_hi:[1,0,1]
	v_lshl_add_u64 v[124:125], v[120:121], 2, s[38:39]
	ds_bpermute_b32 v246, v238, v92
	ds_bpermute_b32 v247, v238, v93
	ds_bpermute_b32 v248, v238, v94
	ds_bpermute_b32 v249, v238, v95
	v_lshl_add_u64 v[244:245], v[124:125], 0, v[240:241]
	s_waitcnt lgkmcnt(0)
	global_store_dwordx4 v[244:245], v[246:249], off
	v_cvt_pk_bf16_f32 v124, v92, v93
	v_lshl_add_u64 v[126:127], v[120:121], 1, s[58:59]
	v_cvt_pk_bf16_f32 v125, v94, v95
	ds_bpermute_b32 v250, v238, v124
	ds_bpermute_b32 v251, v238, v125
	v_lshl_add_u64 v[244:245], v[126:127], 0, v[242:243]
	s_waitcnt lgkmcnt(0)
; __device__ __forceinline__ unsigned cvt_pk_bf16(float lo, float hi) { unsigned r; asm volatile("v_cvt_pk_bf16_f32 %0, %1, %2" : "=v"(r) : "v"(lo), "v"(hi)); return r; }
;     __device__ __forceinline__ void operator()(const f32x4 (&acc)[2][2][4][2], const Unit& u, int wr, int wc, int fr, int fq) const {
;     ...
;                 for (int mm = 0; mm < 2; ++mm) {
;                     const int r = row0 + ai * HALF + (2 * m2 + mm) * 16;
;                     float ps = 0.f, pq = 0.f;
; #pragma unroll
;                     for (int bj = 0; bj < 2; ++bj)
; #pragma unroll
;                         for (int n = 0; n < 2; ++n) {
;                             const f32x4 x = (xv[mm][bj][n] - st[mm][0]) * (gg[bj][n] * st[mm][1]) + bb[bj][n];
;                             const f32x4 o = x * alpha + acc[ai][bj][2 * m2 + mm][n] * scale;
;                             const size_t off = (size_t)r * D + col0 + bj * HALF + n * 16;
;                             *(f32x4*)(Y + off) = o;
;                             if (yb) { u32x2 w; w.x = cvt_pk_bf16(o[0], o[1]); w.y = cvt_pk_bf16(o[2], o[3]); *(u32x2*)(yb + off) = w; }
;                             ps += (o[0] + o[1]) + (o[2] + o[3]); pq += (o[0] * o[0] + o[1] * o[1]) + (o[2] * o[2] + o[3] * o[3]);
;                         }
;                     if (rout) {
;                         ps += __shfl_xor(ps, 16); pq += __shfl_xor(pq, 16); ps += __shfl_xor(ps, 32); pq += __shfl_xor(pq, 32);
;                         if (fq == 0) { atomicAdd(rout + 2 * (size_t)r, ps); atomicAdd(rout + 2 * (size_t)r + 1, pq); }
	global_store_dwordx2 v[244:245], v[250:251], off
	v_add_f32_e32 v124, v92, v93
	v_mul_f32_e32 v93, v93, v93
	v_fmac_f32_e32 v93, v92, v92
	v_mul_f32_e32 v92, v94, v94
	v_add_f32_e32 v125, v95, v94
	v_fmac_f32_e32 v92, v95, v95
	v_add_f32_e32 v124, v124, v125
	v_add_f32_e32 v125, v93, v92
	s_waitcnt vmcnt(8)
	v_pk_add_f32 v[92:93], v[130:131], 0 op_sel_hi:[1,0]
	v_pk_add_f32 v[94:95], v[128:129], 0 op_sel_hi:[1,0]
	v_pk_mul_f32 v[92:93], v[92:93], s[12:13] op_sel_hi:[1,0]
	v_pk_mul_f32 v[94:95], v[94:95], s[12:13] op_sel_hi:[1,0]
	v_pk_fma_f32 v[90:91], v[90:91], 0.5, v[92:93] op_sel_hi:[1,0,1]
	v_or_b32_e32 v92, 16, v120
	v_mov_b32_e32 v93, v121
	v_pk_fma_f32 v[88:89], v[88:89], 0.5, v[94:95] op_sel_hi:[1,0,1]
	v_lshl_add_u64 v[94:95], v[92:93], 2, s[38:39]
	v_lshl_add_u64 v[92:93], v[92:93], 1, s[58:59]
	ds_bpermute_b32 v246, v238, v88
	ds_bpermute_b32 v247, v238, v89
	ds_bpermute_b32 v248, v238, v90
	ds_bpermute_b32 v249, v238, v91
	v_lshl_add_u64 v[244:245], v[94:95], 0, v[240:241]
	s_waitcnt lgkmcnt(0)
	global_store_dwordx4 v[244:245], v[246:249], off
	v_cvt_pk_bf16_f32 v94, v88, v89
	v_cvt_pk_bf16_f32 v95, v90, v91
	ds_bpermute_b32 v250, v238, v94
	ds_bpermute_b32 v251, v238, v95
	v_lshl_add_u64 v[244:245], v[92:93], 0, v[242:243]
	s_waitcnt lgkmcnt(0)
	global_store_dwordx2 v[244:245], v[250:251], off
	v_add_f32_e32 v92, v88, v89
	v_mul_f32_e32 v89, v89, v89
	v_add_f32_e32 v93, v91, v90
	v_fmac_f32_e32 v89, v88, v88
	v_mul_f32_e32 v88, v90, v90
	v_add_f32_e32 v124, 0, v124
	v_add_f32_e32 v92, v92, v93
	v_fmac_f32_e32 v88, v91, v91
	v_add_f32_e32 v94, v124, v92
	v_add_f32_e32 v88, v89, v88
	s_waitcnt vmcnt(9)
	v_pk_add_f32 v[90:91], v[134:135], 0 op_sel_hi:[1,0]
	v_pk_add_f32 v[92:93], v[132:133], 0 op_sel_hi:[1,0]
	v_add_f32_e32 v95, v125, v88
	v_or_b32_e32 v88, 0x80, v120
	v_mov_b32_e32 v89, v121
	v_pk_mul_f32 v[90:91], v[90:91], s[12:13] op_sel_hi:[1,0]
	v_pk_mul_f32 v[92:93], v[92:93], s[12:13] op_sel_hi:[1,0]
	v_pk_fma_f32 v[86:87], v[86:87], 0.5, v[90:91] op_sel_hi:[1,0,1]
	v_pk_fma_f32 v[84:85], v[84:85], 0.5, v[92:93] op_sel_hi:[1,0,1]
	v_lshl_add_u64 v[90:91], v[88:89], 2, s[38:39]
	v_lshl_add_u64 v[88:89], v[88:89], 1, s[58:59]
	ds_bpermute_b32 v246, v238, v84
	ds_bpermute_b32 v247, v238, v85
	ds_bpermute_b32 v248, v238, v86
	ds_bpermute_b32 v249, v238, v87
	v_lshl_add_u64 v[244:245], v[90:91], 0, v[240:241]
	s_waitcnt lgkmcnt(0)
	global_store_dwordx4 v[244:245], v[246:249], off
	v_cvt_pk_bf16_f32 v90, v84, v85
	v_cvt_pk_bf16_f32 v91, v86, v87
	ds_bpermute_b32 v250, v238, v90
	ds_bpermute_b32 v251, v238, v91
	v_lshl_add_u64 v[244:245], v[88:89], 0, v[242:243]
	s_waitcnt lgkmcnt(0)
	global_store_dwordx2 v[244:245], v[250:251], off
	v_add_f32_e32 v88, v84, v85
	v_mul_f32_e32 v85, v85, v85
	v_fmac_f32_e32 v85, v84, v84
	v_mul_f32_e32 v84, v86, v86
	v_fmac_f32_e32 v84, v87, v87
	v_add_f32_e32 v89, v87, v86
	v_add_f32_e32 v84, v85, v84
	v_add_f32_e32 v88, v88, v89
	v_add_f32_e32 v89, v95, v84
	s_waitcnt vmcnt(10)
	v_pk_add_f32 v[84:85], v[114:115], 0 op_sel_hi:[1,0]
	v_pk_add_f32 v[86:87], v[112:113], 0 op_sel_hi:[1,0]
	v_pk_mul_f32 v[84:85], v[84:85], s[12:13] op_sel_hi:[1,0]
	v_pk_mul_f32 v[86:87], v[86:87], s[12:13] op_sel_hi:[1,0]
	v_or_b32_e32 v120, 0x90, v120
	v_pk_fma_f32 v[82:83], v[82:83], 0.5, v[84:85] op_sel_hi:[1,0,1]
	v_pk_fma_f32 v[80:81], v[80:81], 0.5, v[86:87] op_sel_hi:[1,0,1]
	v_lshl_add_u64 v[84:85], v[120:121], 2, s[38:39]
	ds_bpermute_b32 v246, v238, v80
	ds_bpermute_b32 v247, v238, v81
	ds_bpermute_b32 v248, v238, v82
	ds_bpermute_b32 v249, v238, v83
	v_lshl_add_u64 v[244:245], v[84:85], 0, v[240:241]
	s_waitcnt lgkmcnt(0)
	global_store_dwordx4 v[244:245], v[246:249], off
	v_cvt_pk_bf16_f32 v84, v80, v81
	v_lshl_add_u64 v[86:87], v[120:121], 1, s[58:59]
	v_cvt_pk_bf16_f32 v85, v82, v83
	ds_bpermute_b32 v250, v238, v84
	ds_bpermute_b32 v251, v238, v85
	v_lshl_add_u64 v[244:245], v[86:87], 0, v[242:243]
	s_waitcnt lgkmcnt(0)
	global_store_dwordx2 v[244:245], v[250:251], off
	v_mul_f32_e32 v84, v81, v81
	v_fmac_f32_e32 v84, v80, v80
	v_add_f32_e32 v80, v80, v81
	v_add_f32_e32 v81, v83, v82
	v_add_f32_e32 v88, v94, v88
	v_add_f32_e32 v80, v80, v81
	v_add_f32_e32 v80, v88, v80
	ds_bpermute_b32 v81, v122, v80
	v_mul_f32_e32 v85, v82, v82
	v_fmac_f32_e32 v85, v83, v83
	v_add_f32_e32 v84, v84, v85
	v_add_f32_e32 v84, v89, v84
	s_waitcnt lgkmcnt(0)
	v_add_f32_e32 v80, v80, v81
	ds_bpermute_b32 v81, v122, v84
	ds_bpermute_b32 v82, v123, v80
	s_waitcnt lgkmcnt(1)
	v_add_f32_e32 v81, v84, v81
	ds_bpermute_b32 v83, v123, v81
	s_and_saveexec_b64 s[20:21], s[4:5]
	s_cbranch_execz .LBB0_252
	v_lshl_add_u64 v[84:85], v[118:119], 3, s[54:55]
	s_waitcnt lgkmcnt(1)
	v_add_f32_e32 v80, v80, v82
	s_waitcnt lgkmcnt(0)
	v_add_f32_e32 v81, v81, v83
	global_atomic_add_f32 v[84:85], v80, off
	global_atomic_add_f32 v[84:85], v81, off offset:4
; __device__ __forceinline__ unsigned cvt_pk_bf16(float lo, float hi) { unsigned r; asm volatile("v_cvt_pk_bf16_f32 %0, %1, %2" : "=v"(r) : "v"(lo), "v"(hi)); return r; }
;     __device__ __forceinline__ void operator()(const f32x4 (&acc)[2][2][4][2], const Unit& u, int wr, int wc, int fr, int fq) const {
;     ...
;                 for (int mm = 0; mm < 2; ++mm) {
;                     const int r = row0 + ai * HALF + (2 * m2 + mm) * 16;
;                     float ps = 0.f, pq = 0.f;
; #pragma unroll
;                     for (int bj = 0; bj < 2; ++bj)
; #pragma unroll
;                         for (int n = 0; n < 2; ++n) {
;                             const f32x4 x = (xv[mm][bj][n] - st[mm][0]) * (gg[bj][n] * st[mm][1]) + bb[bj][n];
;                             const f32x4 o = x * alpha + acc[ai][bj][2 * m2 + mm][n] * scale;
;                             const size_t off = (size_t)r * D + col0 + bj * HALF + n * 16;
;                             *(f32x4*)(Y + off) = o;
;                             if (yb) { u32x2 w; w.x = cvt_pk_bf16(o[0], o[1]); w.y = cvt_pk_bf16(o[2], o[3]); *(u32x2*)(yb + off) = w; }
;                             ps += (o[0] + o[1]) + (o[2] + o[3]); pq += (o[0] * o[0] + o[1] * o[1]) + (o[2] * o[2] + o[3] * o[3]);
;                         }
;                     if (rout) {
;                         ps += __shfl_xor(ps, 16); pq += __shfl_xor(pq, 16); ps += __shfl_xor(ps, 32); pq += __shfl_xor(pq, 32);
;                         if (fq == 0) { atomicAdd(rout + 2 * (size_t)r, ps); atomicAdd(rout + 2 * (size_t)r + 1, pq); }
.LBB0_252:
	s_or_b64 exec, exec, s[20:21]
	v_lshlrev_b64 v[80:81], 11, v[116:117]
	s_waitcnt vmcnt(11) lgkmcnt(0)
	v_pk_add_f32 v[82:83], v[110:111], 0 op_sel_hi:[1,0]
	v_pk_add_f32 v[84:85], v[108:109], 0 op_sel_hi:[1,0]
	v_lshl_add_u64 v[80:81], v[80:81], 0, v[156:157]
	v_pk_mul_f32 v[82:83], v[82:83], s[12:13] op_sel_hi:[1,0]
	v_pk_mul_f32 v[84:85], v[84:85], s[12:13] op_sel_hi:[1,0]
	v_pk_fma_f32 v[78:79], v[78:79], 0.5, v[82:83] op_sel_hi:[1,0,1]
	v_pk_fma_f32 v[76:77], v[76:77], 0.5, v[84:85] op_sel_hi:[1,0,1]
	v_lshl_add_u64 v[82:83], v[80:81], 2, s[38:39]
	ds_bpermute_b32 v246, v238, v76
	ds_bpermute_b32 v247, v238, v77
	ds_bpermute_b32 v248, v238, v78
	ds_bpermute_b32 v249, v238, v79
	v_lshl_add_u64 v[244:245], v[82:83], 0, v[240:241]
	s_waitcnt lgkmcnt(0)
	global_store_dwordx4 v[244:245], v[246:249], off
	v_cvt_pk_bf16_f32 v82, v76, v77
	v_lshl_add_u64 v[84:85], v[80:81], 1, s[58:59]
	v_cvt_pk_bf16_f32 v83, v78, v79
	ds_bpermute_b32 v250, v238, v82
	ds_bpermute_b32 v251, v238, v83
	v_lshl_add_u64 v[244:245], v[84:85], 0, v[242:243]
	s_waitcnt lgkmcnt(0)
	global_store_dwordx2 v[244:245], v[250:251], off
	v_add_f32_e32 v82, v76, v77
	v_mul_f32_e32 v77, v77, v77
	v_fmac_f32_e32 v77, v76, v76
	v_mul_f32_e32 v76, v78, v78
	v_add_f32_e32 v83, v79, v78
	v_fmac_f32_e32 v76, v79, v79
	v_add_f32_e32 v82, v82, v83
	v_add_f32_e32 v83, v77, v76
	s_waitcnt vmcnt(12)
	v_pk_add_f32 v[76:77], v[106:107], 0 op_sel_hi:[1,0]
	v_pk_add_f32 v[78:79], v[104:105], 0 op_sel_hi:[1,0]
	v_pk_mul_f32 v[76:77], v[76:77], s[12:13] op_sel_hi:[1,0]
	v_pk_mul_f32 v[78:79], v[78:79], s[12:13] op_sel_hi:[1,0]
	v_pk_fma_f32 v[74:75], v[74:75], 0.5, v[76:77] op_sel_hi:[1,0,1]
	v_or_b32_e32 v76, 16, v80
	v_mov_b32_e32 v77, v81
	v_pk_fma_f32 v[72:73], v[72:73], 0.5, v[78:79] op_sel_hi:[1,0,1]
	v_lshl_add_u64 v[78:79], v[76:77], 2, s[38:39]
	v_lshl_add_u64 v[76:77], v[76:77], 1, s[58:59]
	ds_bpermute_b32 v246, v238, v72
	ds_bpermute_b32 v247, v238, v73
	ds_bpermute_b32 v248, v238, v74
	ds_bpermute_b32 v249, v238, v75
	v_lshl_add_u64 v[244:245], v[78:79], 0, v[240:241]
	s_waitcnt lgkmcnt(0)
	global_store_dwordx4 v[244:245], v[246:249], off
	v_cvt_pk_bf16_f32 v78, v72, v73
	v_cvt_pk_bf16_f32 v79, v74, v75
	ds_bpermute_b32 v250, v238, v78
	ds_bpermute_b32 v251, v238, v79
	v_lshl_add_u64 v[244:245], v[76:77], 0, v[242:243]
	s_waitcnt lgkmcnt(0)
	global_store_dwordx2 v[244:245], v[250:251], off
	v_add_f32_e32 v76, v72, v73
	v_mul_f32_e32 v73, v73, v73
	v_add_f32_e32 v77, v75, v74
	v_fmac_f32_e32 v73, v72, v72
	v_mul_f32_e32 v72, v74, v74
	v_add_f32_e32 v82, 0, v82
	v_add_f32_e32 v76, v76, v77
	v_fmac_f32_e32 v72, v75, v75
	v_add_f32_e32 v78, v82, v76
	v_add_f32_e32 v72, v73, v72
	s_waitcnt vmcnt(13)
	v_pk_add_f32 v[74:75], v[102:103], 0 op_sel_hi:[1,0]
	v_pk_add_f32 v[76:77], v[100:101], 0 op_sel_hi:[1,0]
	v_add_f32_e32 v79, v83, v72
	v_or_b32_e32 v72, 0x80, v80
	v_mov_b32_e32 v73, v81
	v_pk_mul_f32 v[74:75], v[74:75], s[12:13] op_sel_hi:[1,0]
	v_pk_mul_f32 v[76:77], v[76:77], s[12:13] op_sel_hi:[1,0]
	v_pk_fma_f32 v[70:71], v[70:71], 0.5, v[74:75] op_sel_hi:[1,0,1]
	v_pk_fma_f32 v[68:69], v[68:69], 0.5, v[76:77] op_sel_hi:[1,0,1]
	v_lshl_add_u64 v[74:75], v[72:73], 2, s[38:39]
	v_lshl_add_u64 v[72:73], v[72:73], 1, s[58:59]
	ds_bpermute_b32 v246, v238, v68
	ds_bpermute_b32 v247, v238, v69
	ds_bpermute_b32 v248, v238, v70
	ds_bpermute_b32 v249, v238, v71
	v_lshl_add_u64 v[244:245], v[74:75], 0, v[240:241]
	s_waitcnt lgkmcnt(0)
	global_store_dwordx4 v[244:245], v[246:249], off
	v_cvt_pk_bf16_f32 v74, v68, v69
	v_cvt_pk_bf16_f32 v75, v70, v71
	ds_bpermute_b32 v250, v238, v74
	ds_bpermute_b32 v251, v238, v75
	v_lshl_add_u64 v[244:245], v[72:73], 0, v[242:243]
	s_waitcnt lgkmcnt(0)
	global_store_dwordx2 v[244:245], v[250:251], off
	v_add_f32_e32 v72, v68, v69
	v_mul_f32_e32 v69, v69, v69
	v_fmac_f32_e32 v69, v68, v68
	v_mul_f32_e32 v68, v70, v70
	v_fmac_f32_e32 v68, v71, v71
	v_add_f32_e32 v73, v71, v70
	v_add_f32_e32 v68, v69, v68
	v_add_f32_e32 v72, v72, v73
	v_add_f32_e32 v75, v79, v68
	s_waitcnt vmcnt(14)
	v_pk_add_f32 v[68:69], v[98:99], 0 op_sel_hi:[1,0]
	v_pk_add_f32 v[70:71], v[96:97], 0 op_sel_hi:[1,0]
	v_add_f32_e32 v74, v78, v72
	v_pk_mul_f32 v[68:69], v[68:69], s[12:13] op_sel_hi:[1,0]
	v_pk_mul_f32 v[72:73], v[70:71], s[12:13] op_sel_hi:[1,0]
	v_pk_fma_f32 v[70:71], v[66:67], 0.5, v[68:69] op_sel_hi:[1,0,1]
	v_pk_fma_f32 v[68:69], v[64:65], 0.5, v[72:73] op_sel_hi:[1,0,1]
	v_mul_f32_e32 v65, v70, v70
	v_mul_f32_e32 v64, v69, v69
	v_fmac_f32_e32 v64, v68, v68
	v_fmac_f32_e32 v65, v71, v71
	v_add_f32_e32 v64, v64, v65
	v_add_f32_e32 v66, v75, v64
	v_add_f32_e32 v64, v68, v69
	v_add_f32_e32 v65, v71, v70
	v_add_f32_e32 v64, v64, v65
	v_add_f32_e32 v67, v74, v64
	ds_bpermute_b32 v72, v122, v67
	ds_bpermute_b32 v73, v122, v66
	v_or_b32_e32 v80, 0x90, v80
	v_lshl_add_u64 v[64:65], v[80:81], 2, s[38:39]
	ds_bpermute_b32 v246, v238, v68
	ds_bpermute_b32 v247, v238, v69
	ds_bpermute_b32 v248, v238, v70
	ds_bpermute_b32 v249, v238, v71
	v_lshl_add_u64 v[244:245], v[64:65], 0, v[240:241]
	s_waitcnt lgkmcnt(0)
	global_store_dwordx4 v[244:245], v[246:249], off
	s_waitcnt lgkmcnt(1)
	v_add_f32_e32 v64, v67, v72
	s_waitcnt lgkmcnt(0)
	v_add_f32_e32 v65, v66, v73
	ds_bpermute_b32 v66, v123, v64
	ds_bpermute_b32 v67, v123, v65
	v_cvt_pk_bf16_f32 v68, v68, v69
	v_cvt_pk_bf16_f32 v69, v70, v71
	v_lshl_add_u64 v[70:71], v[80:81], 1, s[58:59]
	ds_bpermute_b32 v250, v238, v68
	ds_bpermute_b32 v251, v238, v69
	v_lshl_add_u64 v[244:245], v[70:71], 0, v[242:243]
	s_waitcnt lgkmcnt(0)
	global_store_dwordx2 v[244:245], v[250:251], off
	s_and_saveexec_b64 s[20:21], s[4:5]
	s_cbranch_execz .LBB0_254
	v_lshl_add_u64 v[68:69], v[116:117], 3, s[54:55]
	s_waitcnt lgkmcnt(1)
	v_add_f32_e32 v64, v64, v66
	s_waitcnt lgkmcnt(0)
	v_add_f32_e32 v65, v65, v67
	global_atomic_add_f32 v[68:69], v64, off
	global_atomic_add_f32 v[68:69], v65, off offset:4
; __device__ __forceinline__ unsigned cvt_pk_bf16(float lo, float hi) { unsigned r; asm volatile("v_cvt_pk_bf16_f32 %0, %1, %2" : "=v"(r) : "v"(lo), "v"(hi)); return r; }
;     __device__ __forceinline__ void operator()(const f32x4 (&acc)[2][2][4][2], const Unit& u, int wr, int wc, int fr, int fq) const {
;     ...
;                 f32x4 xv[2][2][2]; f32x2 st[2];
; #pragma unroll
;                 for (int mm = 0; mm < 2; ++mm) {
;                     const int r = row0 + ai * HALF + (2 * m2 + mm) * 16;
;                     st[mm] = (f32x2){0.f, 1.f};
;                     if (rin) st[mm] = ln_stats(*(const f32x2*)(rin + 2 * (size_t)r));
; #pragma unroll
;                     for (int bj = 0; bj < 2; ++bj)
; #pragma unroll
;                         for (int n = 0; n < 2; ++n) { const f32x4* rp = (const f32x4*)(res + (size_t)r * D + col0 + bj * HALF + n * 16); xv[mm][bj][n] = stream ? __builtin_nontemporal_load(rp) : *rp; }
;                 }
; #pragma unroll
;                 for (int mm = 0; mm < 2; ++mm) {
;                     const int r = row0 + ai * HALF + (2 * m2 + mm) * 16;
;                     float ps = 0.f, pq = 0.f;
; #pragma unroll
;                     for (int bj = 0; bj < 2; ++bj)
; #pragma unroll
;                         for (int n = 0; n < 2; ++n) {
;                             const f32x4 x = (xv[mm][bj][n] - st[mm][0]) * (gg[bj][n] * st[mm][1]) + bb[bj][n];
;                             const f32x4 o = x * alpha + acc[ai][bj][2 * m2 + mm][n] * scale;
;                             const size_t off = (size_t)r * D + col0 + bj * HALF + n * 16;
;                             *(f32x4*)(Y + off) = o;
;                             if (yb) { u32x2 w; w.x = cvt_pk_bf16(o[0], o[1]); w.y = cvt_pk_bf16(o[2], o[3]); *(u32x2*)(yb + off) = w; }
;                             ps += (o[0] + o[1]) + (o[2] + o[3]); pq += (o[0] * o[0] + o[1] * o[1]) + (o[2] * o[2] + o[3] * o[3]);
;                         }
;                     if (rout) {
;                         ps += __shfl_xor(ps, 16); pq += __shfl_xor(pq, 16); ps += __shfl_xor(ps, 32); pq += __shfl_xor(pq, 32);
;                         if (fq == 0) { atomicAdd(rout + 2 * (size_t)r, ps); atomicAdd(rout + 2 * (size_t)r + 1, pq); }
.LBB0_254:
	s_or_b64 exec, exec, s[20:21]
	v_add_u32_e32 v86, 0x80, v158
	v_ashrrev_i32_e32 v87, 31, v86
	v_lshlrev_b64 v[64:65], 13, v[86:87]
	v_lshl_add_u64 v[64:65], v[160:161], 0, v[64:65]
	global_load_dwordx4 v[90:93], v[64:65], off
	global_load_dwordx4 v[94:97], v[64:65], off offset:64
	global_load_dwordx4 v[98:101], v[64:65], off offset:512
	global_load_dwordx4 v[80:83], v[64:65], off offset:576
	v_add_u32_e32 v84, 0x90, v158
	v_ashrrev_i32_e32 v85, 31, v84
	v_lshlrev_b64 v[64:65], 13, v[84:85]
	v_lshl_add_u64 v[64:65], v[160:161], 0, v[64:65]
	global_load_dwordx4 v[76:79], v[64:65], off
	global_load_dwordx4 v[72:75], v[64:65], off offset:64
	global_load_dwordx4 v[68:71], v[64:65], off offset:512
	s_waitcnt lgkmcnt(0)
	global_load_dwordx4 v[64:67], v[64:65], off offset:576
	v_lshlrev_b64 v[88:89], 11, v[86:87]
	v_lshl_add_u64 v[88:89], v[88:89], 0, v[156:157]
	s_waitcnt vmcnt(7)
	v_pk_add_f32 v[92:93], v[92:93], 0 op_sel_hi:[1,0]
	v_pk_add_f32 v[90:91], v[90:91], 0 op_sel_hi:[1,0]
	v_pk_mul_f32 v[92:93], v[92:93], s[12:13] op_sel_hi:[1,0]
	v_pk_mul_f32 v[90:91], v[90:91], s[12:13] op_sel_hi:[1,0]
	v_pk_fma_f32 v[62:63], v[62:63], 0.5, v[92:93] op_sel_hi:[1,0,1]
	v_pk_fma_f32 v[60:61], v[60:61], 0.5, v[90:91] op_sel_hi:[1,0,1]
	v_lshl_add_u64 v[90:91], v[88:89], 2, s[38:39]
	ds_bpermute_b32 v246, v238, v60
	ds_bpermute_b32 v247, v238, v61
	ds_bpermute_b32 v248, v238, v62
	ds_bpermute_b32 v249, v238, v63
	v_lshl_add_u64 v[244:245], v[90:91], 0, v[240:241]
	s_waitcnt lgkmcnt(0)
	global_store_dwordx4 v[244:245], v[246:249], off
	v_cvt_pk_bf16_f32 v90, v60, v61
	v_lshl_add_u64 v[92:93], v[88:89], 1, s[58:59]
	v_cvt_pk_bf16_f32 v91, v62, v63
	ds_bpermute_b32 v250, v238, v90
	ds_bpermute_b32 v251, v238, v91
	v_lshl_add_u64 v[244:245], v[92:93], 0, v[242:243]
	s_waitcnt lgkmcnt(0)
	global_store_dwordx2 v[244:245], v[250:251], off
	v_add_f32_e32 v90, v60, v61
	v_mul_f32_e32 v61, v61, v61
	v_fmac_f32_e32 v61, v60, v60
	v_mul_f32_e32 v60, v62, v62
	v_add_f32_e32 v91, v63, v62
	v_fmac_f32_e32 v60, v63, v63
	v_add_f32_e32 v90, v90, v91
	v_add_f32_e32 v91, v61, v60
	s_waitcnt vmcnt(8)
	v_pk_add_f32 v[60:61], v[96:97], 0 op_sel_hi:[1,0]
	v_pk_add_f32 v[62:63], v[94:95], 0 op_sel_hi:[1,0]
	v_pk_mul_f32 v[60:61], v[60:61], s[12:13] op_sel_hi:[1,0]
	v_pk_mul_f32 v[62:63], v[62:63], s[12:13] op_sel_hi:[1,0]
	v_pk_fma_f32 v[58:59], v[58:59], 0.5, v[60:61] op_sel_hi:[1,0,1]
	v_or_b32_e32 v60, 16, v88
	v_mov_b32_e32 v61, v89
	v_pk_fma_f32 v[56:57], v[56:57], 0.5, v[62:63] op_sel_hi:[1,0,1]
	v_lshl_add_u64 v[62:63], v[60:61], 2, s[38:39]
	v_lshl_add_u64 v[60:61], v[60:61], 1, s[58:59]
	ds_bpermute_b32 v246, v238, v56
	ds_bpermute_b32 v247, v238, v57
	ds_bpermute_b32 v248, v238, v58
	ds_bpermute_b32 v249, v238, v59
	v_lshl_add_u64 v[244:245], v[62:63], 0, v[240:241]
	s_waitcnt lgkmcnt(0)
	global_store_dwordx4 v[244:245], v[246:249], off
	v_cvt_pk_bf16_f32 v62, v56, v57
	v_cvt_pk_bf16_f32 v63, v58, v59
	ds_bpermute_b32 v250, v238, v62
	ds_bpermute_b32 v251, v238, v63
	v_lshl_add_u64 v[244:245], v[60:61], 0, v[242:243]
	s_waitcnt lgkmcnt(0)
	global_store_dwordx2 v[244:245], v[250:251], off
	v_add_f32_e32 v60, v56, v57
	v_mul_f32_e32 v57, v57, v57
	v_add_f32_e32 v61, v59, v58
	v_fmac_f32_e32 v57, v56, v56
	v_mul_f32_e32 v56, v58, v58
	v_add_f32_e32 v90, 0, v90
	v_add_f32_e32 v60, v60, v61
	v_fmac_f32_e32 v56, v59, v59
	v_add_f32_e32 v62, v90, v60
	v_add_f32_e32 v56, v57, v56
	s_waitcnt vmcnt(9)
	v_pk_add_f32 v[58:59], v[100:101], 0 op_sel_hi:[1,0]
	v_pk_add_f32 v[60:61], v[98:99], 0 op_sel_hi:[1,0]
	v_add_f32_e32 v63, v91, v56
	v_or_b32_e32 v56, 0x80, v88
	v_mov_b32_e32 v57, v89
	v_pk_mul_f32 v[58:59], v[58:59], s[12:13] op_sel_hi:[1,0]
	v_pk_mul_f32 v[60:61], v[60:61], s[12:13] op_sel_hi:[1,0]
	v_pk_fma_f32 v[54:55], v[54:55], 0.5, v[58:59] op_sel_hi:[1,0,1]
	v_pk_fma_f32 v[52:53], v[52:53], 0.5, v[60:61] op_sel_hi:[1,0,1]
	v_lshl_add_u64 v[58:59], v[56:57], 2, s[38:39]
	v_lshl_add_u64 v[56:57], v[56:57], 1, s[58:59]
	ds_bpermute_b32 v246, v238, v52
	ds_bpermute_b32 v247, v238, v53
	ds_bpermute_b32 v248, v238, v54
	ds_bpermute_b32 v249, v238, v55
	v_lshl_add_u64 v[244:245], v[58:59], 0, v[240:241]
	s_waitcnt lgkmcnt(0)
	global_store_dwordx4 v[244:245], v[246:249], off
	v_cvt_pk_bf16_f32 v58, v52, v53
	v_cvt_pk_bf16_f32 v59, v54, v55
	ds_bpermute_b32 v250, v238, v58
	ds_bpermute_b32 v251, v238, v59
	v_lshl_add_u64 v[244:245], v[56:57], 0, v[242:243]
	s_waitcnt lgkmcnt(0)
	global_store_dwordx2 v[244:245], v[250:251], off
	v_add_f32_e32 v56, v52, v53
	v_mul_f32_e32 v53, v53, v53
	v_fmac_f32_e32 v53, v52, v52
	v_mul_f32_e32 v52, v54, v54
	v_fmac_f32_e32 v52, v55, v55
	v_add_f32_e32 v57, v55, v54
	v_add_f32_e32 v52, v53, v52
	v_add_f32_e32 v56, v56, v57
	v_add_f32_e32 v57, v63, v52
	s_waitcnt vmcnt(10)
	v_pk_add_f32 v[52:53], v[82:83], 0 op_sel_hi:[1,0]
	v_pk_add_f32 v[54:55], v[80:81], 0 op_sel_hi:[1,0]
	v_pk_mul_f32 v[52:53], v[52:53], s[12:13] op_sel_hi:[1,0]
	v_pk_mul_f32 v[54:55], v[54:55], s[12:13] op_sel_hi:[1,0]
	v_or_b32_e32 v88, 0x90, v88
	v_pk_fma_f32 v[50:51], v[50:51], 0.5, v[52:53] op_sel_hi:[1,0,1]
	v_pk_fma_f32 v[48:49], v[48:49], 0.5, v[54:55] op_sel_hi:[1,0,1]
	v_lshl_add_u64 v[52:53], v[88:89], 2, s[38:39]
	ds_bpermute_b32 v246, v238, v48
	ds_bpermute_b32 v247, v238, v49
	ds_bpermute_b32 v248, v238, v50
	ds_bpermute_b32 v249, v238, v51
	v_lshl_add_u64 v[244:245], v[52:53], 0, v[240:241]
	s_waitcnt lgkmcnt(0)
	global_store_dwordx4 v[244:245], v[246:249], off
	v_cvt_pk_bf16_f32 v52, v48, v49
	v_lshl_add_u64 v[54:55], v[88:89], 1, s[58:59]
	v_cvt_pk_bf16_f32 v53, v50, v51
	ds_bpermute_b32 v250, v238, v52
	ds_bpermute_b32 v251, v238, v53
	v_lshl_add_u64 v[244:245], v[54:55], 0, v[242:243]
	s_waitcnt lgkmcnt(0)
	global_store_dwordx2 v[244:245], v[250:251], off
	v_mul_f32_e32 v52, v49, v49
	v_fmac_f32_e32 v52, v48, v48
	v_add_f32_e32 v48, v48, v49
	v_add_f32_e32 v49, v51, v50
	v_add_f32_e32 v56, v62, v56
	v_add_f32_e32 v48, v48, v49
	v_add_f32_e32 v48, v56, v48
	ds_bpermute_b32 v49, v122, v48
	v_mul_f32_e32 v53, v50, v50
	v_fmac_f32_e32 v53, v51, v51
	v_add_f32_e32 v52, v52, v53
	v_add_f32_e32 v52, v57, v52
	s_waitcnt lgkmcnt(0)
	v_add_f32_e32 v48, v48, v49
	ds_bpermute_b32 v49, v122, v52
	ds_bpermute_b32 v50, v123, v48
	s_waitcnt lgkmcnt(1)
	v_add_f32_e32 v49, v52, v49
	ds_bpermute_b32 v51, v123, v49
	s_and_saveexec_b64 s[20:21], s[4:5]
	s_cbranch_execz .LBB0_256
	v_lshl_add_u64 v[52:53], v[86:87], 3, s[54:55]
	s_waitcnt lgkmcnt(1)
	v_add_f32_e32 v48, v48, v50
	s_waitcnt lgkmcnt(0)
	v_add_f32_e32 v49, v49, v51
	global_atomic_add_f32 v[52:53], v48, off
	global_atomic_add_f32 v[52:53], v49, off offset:4
; __device__ __forceinline__ unsigned cvt_pk_bf16(float lo, float hi) { unsigned r; asm volatile("v_cvt_pk_bf16_f32 %0, %1, %2" : "=v"(r) : "v"(lo), "v"(hi)); return r; }
;     __device__ __forceinline__ void operator()(const f32x4 (&acc)[2][2][4][2], const Unit& u, int wr, int wc, int fr, int fq) const {
;     ...
;                 for (int mm = 0; mm < 2; ++mm) {
;                     const int r = row0 + ai * HALF + (2 * m2 + mm) * 16;
;                     float ps = 0.f, pq = 0.f;
; #pragma unroll
;                     for (int bj = 0; bj < 2; ++bj)
; #pragma unroll
;                         for (int n = 0; n < 2; ++n) {
;                             const f32x4 x = (xv[mm][bj][n] - st[mm][0]) * (gg[bj][n] * st[mm][1]) + bb[bj][n];
;                             const f32x4 o = x * alpha + acc[ai][bj][2 * m2 + mm][n] * scale;
;                             const size_t off = (size_t)r * D + col0 + bj * HALF + n * 16;
;                             *(f32x4*)(Y + off) = o;
;                             if (yb) { u32x2 w; w.x = cvt_pk_bf16(o[0], o[1]); w.y = cvt_pk_bf16(o[2], o[3]); *(u32x2*)(yb + off) = w; }
;                             ps += (o[0] + o[1]) + (o[2] + o[3]); pq += (o[0] * o[0] + o[1] * o[1]) + (o[2] * o[2] + o[3] * o[3]);
;                         }
;                     if (rout) {
;                         ps += __shfl_xor(ps, 16); pq += __shfl_xor(pq, 16); ps += __shfl_xor(ps, 32); pq += __shfl_xor(pq, 32);
;                         if (fq == 0) { atomicAdd(rout + 2 * (size_t)r, ps); atomicAdd(rout + 2 * (size_t)r + 1, pq); }
.LBB0_256:
	s_or_b64 exec, exec, s[20:21]
	v_lshlrev_b64 v[48:49], 11, v[84:85]
	s_waitcnt vmcnt(11) lgkmcnt(0)
	v_pk_add_f32 v[50:51], v[78:79], 0 op_sel_hi:[1,0]
	v_pk_add_f32 v[52:53], v[76:77], 0 op_sel_hi:[1,0]
	v_lshl_add_u64 v[48:49], v[48:49], 0, v[156:157]
	v_pk_mul_f32 v[50:51], v[50:51], s[12:13] op_sel_hi:[1,0]
	v_pk_mul_f32 v[52:53], v[52:53], s[12:13] op_sel_hi:[1,0]
	v_pk_fma_f32 v[46:47], v[46:47], 0.5, v[50:51] op_sel_hi:[1,0,1]
	v_pk_fma_f32 v[44:45], v[44:45], 0.5, v[52:53] op_sel_hi:[1,0,1]
	v_lshl_add_u64 v[50:51], v[48:49], 2, s[38:39]
	ds_bpermute_b32 v246, v238, v44
	ds_bpermute_b32 v247, v238, v45
	ds_bpermute_b32 v248, v238, v46
	ds_bpermute_b32 v249, v238, v47
	v_lshl_add_u64 v[244:245], v[50:51], 0, v[240:241]
	s_waitcnt lgkmcnt(0)
	global_store_dwordx4 v[244:245], v[246:249], off
	v_cvt_pk_bf16_f32 v50, v44, v45
	v_lshl_add_u64 v[52:53], v[48:49], 1, s[58:59]
	v_cvt_pk_bf16_f32 v51, v46, v47
	ds_bpermute_b32 v250, v238, v50
	ds_bpermute_b32 v251, v238, v51
	v_lshl_add_u64 v[244:245], v[52:53], 0, v[242:243]
	s_waitcnt lgkmcnt(0)
	global_store_dwordx2 v[244:245], v[250:251], off
	v_add_f32_e32 v50, v44, v45
	v_mul_f32_e32 v45, v45, v45
	v_fmac_f32_e32 v45, v44, v44
	v_mul_f32_e32 v44, v46, v46
	v_add_f32_e32 v51, v47, v46
	v_fmac_f32_e32 v44, v47, v47
	v_add_f32_e32 v50, v50, v51
	v_add_f32_e32 v51, v45, v44
	s_waitcnt vmcnt(12)
	v_pk_add_f32 v[44:45], v[74:75], 0 op_sel_hi:[1,0]
	v_pk_add_f32 v[46:47], v[72:73], 0 op_sel_hi:[1,0]
	v_pk_mul_f32 v[44:45], v[44:45], s[12:13] op_sel_hi:[1,0]
	v_pk_mul_f32 v[46:47], v[46:47], s[12:13] op_sel_hi:[1,0]
	v_pk_fma_f32 v[42:43], v[42:43], 0.5, v[44:45] op_sel_hi:[1,0,1]
	v_or_b32_e32 v44, 16, v48
	v_mov_b32_e32 v45, v49
	v_pk_fma_f32 v[40:41], v[40:41], 0.5, v[46:47] op_sel_hi:[1,0,1]
	v_lshl_add_u64 v[46:47], v[44:45], 2, s[38:39]
	v_lshl_add_u64 v[44:45], v[44:45], 1, s[58:59]
	ds_bpermute_b32 v246, v238, v40
	ds_bpermute_b32 v247, v238, v41
	ds_bpermute_b32 v248, v238, v42
	ds_bpermute_b32 v249, v238, v43
	v_lshl_add_u64 v[244:245], v[46:47], 0, v[240:241]
	s_waitcnt lgkmcnt(0)
	global_store_dwordx4 v[244:245], v[246:249], off
	v_cvt_pk_bf16_f32 v46, v40, v41
	v_cvt_pk_bf16_f32 v47, v42, v43
	ds_bpermute_b32 v250, v238, v46
	ds_bpermute_b32 v251, v238, v47
	v_lshl_add_u64 v[244:245], v[44:45], 0, v[242:243]
	s_waitcnt lgkmcnt(0)
	global_store_dwordx2 v[244:245], v[250:251], off
	v_add_f32_e32 v44, v40, v41
	v_mul_f32_e32 v41, v41, v41
	v_add_f32_e32 v45, v43, v42
	v_fmac_f32_e32 v41, v40, v40
	v_mul_f32_e32 v40, v42, v42
	v_add_f32_e32 v50, 0, v50
	v_add_f32_e32 v44, v44, v45
	v_fmac_f32_e32 v40, v43, v43
	v_add_f32_e32 v46, v50, v44
	v_add_f32_e32 v40, v41, v40
	s_waitcnt vmcnt(13)
	v_pk_add_f32 v[42:43], v[70:71], 0 op_sel_hi:[1,0]
	v_pk_add_f32 v[44:45], v[68:69], 0 op_sel_hi:[1,0]
	v_add_f32_e32 v47, v51, v40
	v_or_b32_e32 v40, 0x80, v48
	v_mov_b32_e32 v41, v49
	v_pk_mul_f32 v[42:43], v[42:43], s[12:13] op_sel_hi:[1,0]
	v_pk_mul_f32 v[44:45], v[44:45], s[12:13] op_sel_hi:[1,0]
	v_pk_fma_f32 v[38:39], v[38:39], 0.5, v[42:43] op_sel_hi:[1,0,1]
	v_pk_fma_f32 v[36:37], v[36:37], 0.5, v[44:45] op_sel_hi:[1,0,1]
	v_lshl_add_u64 v[42:43], v[40:41], 2, s[38:39]
	v_lshl_add_u64 v[40:41], v[40:41], 1, s[58:59]
	ds_bpermute_b32 v246, v238, v36
	ds_bpermute_b32 v247, v238, v37
	ds_bpermute_b32 v248, v238, v38
	ds_bpermute_b32 v249, v238, v39
	v_lshl_add_u64 v[244:245], v[42:43], 0, v[240:241]
	s_waitcnt lgkmcnt(0)
	global_store_dwordx4 v[244:245], v[246:249], off
	v_cvt_pk_bf16_f32 v42, v36, v37
	v_cvt_pk_bf16_f32 v43, v38, v39
	ds_bpermute_b32 v250, v238, v42
	ds_bpermute_b32 v251, v238, v43
	v_lshl_add_u64 v[244:245], v[40:41], 0, v[242:243]
	s_waitcnt lgkmcnt(0)
	global_store_dwordx2 v[244:245], v[250:251], off
	v_add_f32_e32 v40, v36, v37
	v_mul_f32_e32 v37, v37, v37
	v_fmac_f32_e32 v37, v36, v36
	v_mul_f32_e32 v36, v38, v38
	v_fmac_f32_e32 v36, v39, v39
	v_add_f32_e32 v41, v39, v38
	v_add_f32_e32 v36, v37, v36
	v_add_f32_e32 v40, v40, v41
	v_add_f32_e32 v43, v47, v36
	s_waitcnt vmcnt(14)
	v_pk_add_f32 v[36:37], v[66:67], 0 op_sel_hi:[1,0]
	v_pk_add_f32 v[38:39], v[64:65], 0 op_sel_hi:[1,0]
	v_add_f32_e32 v42, v46, v40
	v_pk_mul_f32 v[36:37], v[36:37], s[12:13] op_sel_hi:[1,0]
	v_pk_mul_f32 v[40:41], v[38:39], s[12:13] op_sel_hi:[1,0]
	v_pk_fma_f32 v[38:39], v[34:35], 0.5, v[36:37] op_sel_hi:[1,0,1]
	v_pk_fma_f32 v[36:37], v[32:33], 0.5, v[40:41] op_sel_hi:[1,0,1]
	v_mul_f32_e32 v33, v38, v38
	v_mul_f32_e32 v32, v37, v37
	v_fmac_f32_e32 v32, v36, v36
	v_fmac_f32_e32 v33, v39, v39
	v_add_f32_e32 v32, v32, v33
	v_add_f32_e32 v34, v43, v32
	v_add_f32_e32 v32, v36, v37
	v_add_f32_e32 v33, v39, v38
	v_add_f32_e32 v32, v32, v33
	v_add_f32_e32 v35, v42, v32
	ds_bpermute_b32 v40, v122, v35
	ds_bpermute_b32 v41, v122, v34
	v_or_b32_e32 v48, 0x90, v48
	v_lshl_add_u64 v[32:33], v[48:49], 2, s[38:39]
	ds_bpermute_b32 v246, v238, v36
	ds_bpermute_b32 v247, v238, v37
	ds_bpermute_b32 v248, v238, v38
	ds_bpermute_b32 v249, v238, v39
	v_lshl_add_u64 v[244:245], v[32:33], 0, v[240:241]
	s_waitcnt lgkmcnt(0)
	global_store_dwordx4 v[244:245], v[246:249], off
	s_waitcnt lgkmcnt(1)
	v_add_f32_e32 v32, v35, v40
	s_waitcnt lgkmcnt(0)
	v_add_f32_e32 v33, v34, v41
	ds_bpermute_b32 v34, v123, v32
	ds_bpermute_b32 v35, v123, v33
	v_cvt_pk_bf16_f32 v36, v36, v37
	v_cvt_pk_bf16_f32 v37, v38, v39
	v_lshl_add_u64 v[38:39], v[48:49], 1, s[58:59]
	ds_bpermute_b32 v250, v238, v36
	ds_bpermute_b32 v251, v238, v37
	v_lshl_add_u64 v[244:245], v[38:39], 0, v[242:243]
	s_waitcnt lgkmcnt(0)
	global_store_dwordx2 v[244:245], v[250:251], off
	s_and_saveexec_b64 s[20:21], s[4:5]
	s_cbranch_execz .LBB0_258
	v_lshl_add_u64 v[36:37], v[84:85], 3, s[54:55]
	s_waitcnt lgkmcnt(1)
	v_add_f32_e32 v32, v32, v34
	s_waitcnt lgkmcnt(0)
	v_add_f32_e32 v33, v33, v35
	global_atomic_add_f32 v[36:37], v32, off
	global_atomic_add_f32 v[36:37], v33, off offset:4
; __device__ __forceinline__ unsigned cvt_pk_bf16(float lo, float hi) { unsigned r; asm volatile("v_cvt_pk_bf16_f32 %0, %1, %2" : "=v"(r) : "v"(lo), "v"(hi)); return r; }
;     __device__ __forceinline__ void operator()(const f32x4 (&acc)[2][2][4][2], const Unit& u, int wr, int wc, int fr, int fq) const {
;     ...
;                 f32x4 xv[2][2][2]; f32x2 st[2];
; #pragma unroll
;                 for (int mm = 0; mm < 2; ++mm) {
;                     const int r = row0 + ai * HALF + (2 * m2 + mm) * 16;
;                     st[mm] = (f32x2){0.f, 1.f};
;                     if (rin) st[mm] = ln_stats(*(const f32x2*)(rin + 2 * (size_t)r));
; #pragma unroll
;                     for (int bj = 0; bj < 2; ++bj)
; #pragma unroll
;                         for (int n = 0; n < 2; ++n) { const f32x4* rp = (const f32x4*)(res + (size_t)r * D + col0 + bj * HALF + n * 16); xv[mm][bj][n] = stream ? __builtin_nontemporal_load(rp) : *rp; }
;                 }
; #pragma unroll
;                 for (int mm = 0; mm < 2; ++mm) {
;                     const int r = row0 + ai * HALF + (2 * m2 + mm) * 16;
;                     float ps = 0.f, pq = 0.f;
; #pragma unroll
;                     for (int bj = 0; bj < 2; ++bj)
; #pragma unroll
;                         for (int n = 0; n < 2; ++n) {
;                             const f32x4 x = (xv[mm][bj][n] - st[mm][0]) * (gg[bj][n] * st[mm][1]) + bb[bj][n];
;                             const f32x4 o = x * alpha + acc[ai][bj][2 * m2 + mm][n] * scale;
;                             const size_t off = (size_t)r * D + col0 + bj * HALF + n * 16;
;                             *(f32x4*)(Y + off) = o;
;                             if (yb) { u32x2 w; w.x = cvt_pk_bf16(o[0], o[1]); w.y = cvt_pk_bf16(o[2], o[3]); *(u32x2*)(yb + off) = w; }
;                             ps += (o[0] + o[1]) + (o[2] + o[3]); pq += (o[0] * o[0] + o[1] * o[1]) + (o[2] * o[2] + o[3] * o[3]);
;                         }
;                     if (rout) {
;                         ps += __shfl_xor(ps, 16); pq += __shfl_xor(pq, 16); ps += __shfl_xor(ps, 32); pq += __shfl_xor(pq, 32);
;                         if (fq == 0) { atomicAdd(rout + 2 * (size_t)r, ps); atomicAdd(rout + 2 * (size_t)r + 1, pq); }
.LBB0_258:
	s_or_b64 exec, exec, s[20:21]
	v_add_u32_e32 v54, 0xa0, v158
	v_ashrrev_i32_e32 v55, 31, v54
	v_lshlrev_b64 v[32:33], 13, v[54:55]
	v_lshl_add_u64 v[32:33], v[160:161], 0, v[32:33]
	global_load_dwordx4 v[58:61], v[32:33], off
	global_load_dwordx4 v[62:65], v[32:33], off offset:64
	global_load_dwordx4 v[66:69], v[32:33], off offset:512
	global_load_dwordx4 v[48:51], v[32:33], off offset:576
	v_add_u32_e32 v52, 0xb0, v158
	v_ashrrev_i32_e32 v53, 31, v52
	v_lshlrev_b64 v[32:33], 13, v[52:53]
	v_lshl_add_u64 v[32:33], v[160:161], 0, v[32:33]
	global_load_dwordx4 v[44:47], v[32:33], off
	global_load_dwordx4 v[40:43], v[32:33], off offset:64
	global_load_dwordx4 v[36:39], v[32:33], off offset:512
	s_waitcnt lgkmcnt(0)
	global_load_dwordx4 v[32:35], v[32:33], off offset:576
	v_lshlrev_b64 v[56:57], 11, v[54:55]
	v_lshl_add_u64 v[56:57], v[56:57], 0, v[156:157]
	s_waitcnt vmcnt(7)
	v_pk_add_f32 v[60:61], v[60:61], 0 op_sel_hi:[1,0]
	v_pk_add_f32 v[58:59], v[58:59], 0 op_sel_hi:[1,0]
	v_pk_mul_f32 v[60:61], v[60:61], s[12:13] op_sel_hi:[1,0]
	v_pk_mul_f32 v[58:59], v[58:59], s[12:13] op_sel_hi:[1,0]
	v_pk_fma_f32 v[30:31], v[30:31], 0.5, v[60:61] op_sel_hi:[1,0,1]
	v_pk_fma_f32 v[28:29], v[28:29], 0.5, v[58:59] op_sel_hi:[1,0,1]
	v_lshl_add_u64 v[58:59], v[56:57], 2, s[38:39]
	ds_bpermute_b32 v246, v238, v28
	ds_bpermute_b32 v247, v238, v29
	ds_bpermute_b32 v248, v238, v30
	ds_bpermute_b32 v249, v238, v31
	v_lshl_add_u64 v[244:245], v[58:59], 0, v[240:241]
	s_waitcnt lgkmcnt(0)
	global_store_dwordx4 v[244:245], v[246:249], off
	v_cvt_pk_bf16_f32 v58, v28, v29
	v_lshl_add_u64 v[60:61], v[56:57], 1, s[58:59]
	v_cvt_pk_bf16_f32 v59, v30, v31
	ds_bpermute_b32 v250, v238, v58
	ds_bpermute_b32 v251, v238, v59
	v_lshl_add_u64 v[244:245], v[60:61], 0, v[242:243]
	s_waitcnt lgkmcnt(0)
	global_store_dwordx2 v[244:245], v[250:251], off
	v_add_f32_e32 v58, v28, v29
	v_mul_f32_e32 v29, v29, v29
	v_fmac_f32_e32 v29, v28, v28
	v_mul_f32_e32 v28, v30, v30
	v_add_f32_e32 v59, v31, v30
	v_fmac_f32_e32 v28, v31, v31
	v_add_f32_e32 v58, v58, v59
	v_add_f32_e32 v59, v29, v28
	s_waitcnt vmcnt(8)
	v_pk_add_f32 v[28:29], v[64:65], 0 op_sel_hi:[1,0]
	v_pk_add_f32 v[30:31], v[62:63], 0 op_sel_hi:[1,0]
	v_pk_mul_f32 v[28:29], v[28:29], s[12:13] op_sel_hi:[1,0]
	v_pk_mul_f32 v[30:31], v[30:31], s[12:13] op_sel_hi:[1,0]
	v_pk_fma_f32 v[26:27], v[26:27], 0.5, v[28:29] op_sel_hi:[1,0,1]
	v_or_b32_e32 v28, 16, v56
	v_mov_b32_e32 v29, v57
	v_pk_fma_f32 v[24:25], v[24:25], 0.5, v[30:31] op_sel_hi:[1,0,1]
	v_lshl_add_u64 v[30:31], v[28:29], 2, s[38:39]
	v_lshl_add_u64 v[28:29], v[28:29], 1, s[58:59]
	ds_bpermute_b32 v246, v238, v24
	ds_bpermute_b32 v247, v238, v25
	ds_bpermute_b32 v248, v238, v26
	ds_bpermute_b32 v249, v238, v27
	v_lshl_add_u64 v[244:245], v[30:31], 0, v[240:241]
	s_waitcnt lgkmcnt(0)
	global_store_dwordx4 v[244:245], v[246:249], off
	v_cvt_pk_bf16_f32 v30, v24, v25
	v_cvt_pk_bf16_f32 v31, v26, v27
	ds_bpermute_b32 v250, v238, v30
	ds_bpermute_b32 v251, v238, v31
	v_lshl_add_u64 v[244:245], v[28:29], 0, v[242:243]
	s_waitcnt lgkmcnt(0)
	global_store_dwordx2 v[244:245], v[250:251], off
	v_add_f32_e32 v28, v24, v25
	v_mul_f32_e32 v25, v25, v25
	v_add_f32_e32 v29, v27, v26
	v_fmac_f32_e32 v25, v24, v24
	v_mul_f32_e32 v24, v26, v26
	v_add_f32_e32 v58, 0, v58
	v_add_f32_e32 v28, v28, v29
	v_fmac_f32_e32 v24, v27, v27
	v_add_f32_e32 v30, v58, v28
	v_add_f32_e32 v24, v25, v24
	s_waitcnt vmcnt(9)
	v_pk_add_f32 v[26:27], v[68:69], 0 op_sel_hi:[1,0]
	v_pk_add_f32 v[28:29], v[66:67], 0 op_sel_hi:[1,0]
	v_add_f32_e32 v31, v59, v24
	v_or_b32_e32 v24, 0x80, v56
	v_mov_b32_e32 v25, v57
	v_pk_mul_f32 v[26:27], v[26:27], s[12:13] op_sel_hi:[1,0]
	v_pk_mul_f32 v[28:29], v[28:29], s[12:13] op_sel_hi:[1,0]
	v_pk_fma_f32 v[22:23], v[22:23], 0.5, v[26:27] op_sel_hi:[1,0,1]
	v_pk_fma_f32 v[20:21], v[20:21], 0.5, v[28:29] op_sel_hi:[1,0,1]
	v_lshl_add_u64 v[26:27], v[24:25], 2, s[38:39]
	v_lshl_add_u64 v[24:25], v[24:25], 1, s[58:59]
	ds_bpermute_b32 v246, v238, v20
	ds_bpermute_b32 v247, v238, v21
	ds_bpermute_b32 v248, v238, v22
	ds_bpermute_b32 v249, v238, v23
	v_lshl_add_u64 v[244:245], v[26:27], 0, v[240:241]
	s_waitcnt lgkmcnt(0)
	global_store_dwordx4 v[244:245], v[246:249], off
	v_cvt_pk_bf16_f32 v26, v20, v21
	v_cvt_pk_bf16_f32 v27, v22, v23
	ds_bpermute_b32 v250, v238, v26
	ds_bpermute_b32 v251, v238, v27
	v_lshl_add_u64 v[244:245], v[24:25], 0, v[242:243]
	s_waitcnt lgkmcnt(0)
	global_store_dwordx2 v[244:245], v[250:251], off
	v_add_f32_e32 v24, v20, v21
	v_mul_f32_e32 v21, v21, v21
	v_fmac_f32_e32 v21, v20, v20
	v_mul_f32_e32 v20, v22, v22
	v_fmac_f32_e32 v20, v23, v23
	v_add_f32_e32 v25, v23, v22
	v_add_f32_e32 v20, v21, v20
	v_add_f32_e32 v24, v24, v25
	v_add_f32_e32 v25, v31, v20
	s_waitcnt vmcnt(10)
	v_pk_add_f32 v[20:21], v[50:51], 0 op_sel_hi:[1,0]
	v_pk_add_f32 v[22:23], v[48:49], 0 op_sel_hi:[1,0]
	v_pk_mul_f32 v[20:21], v[20:21], s[12:13] op_sel_hi:[1,0]
	v_pk_mul_f32 v[22:23], v[22:23], s[12:13] op_sel_hi:[1,0]
	v_or_b32_e32 v56, 0x90, v56
	v_pk_fma_f32 v[18:19], v[18:19], 0.5, v[20:21] op_sel_hi:[1,0,1]
	v_pk_fma_f32 v[16:17], v[16:17], 0.5, v[22:23] op_sel_hi:[1,0,1]
	v_lshl_add_u64 v[20:21], v[56:57], 2, s[38:39]
	ds_bpermute_b32 v246, v238, v16
	ds_bpermute_b32 v247, v238, v17
	ds_bpermute_b32 v248, v238, v18
	ds_bpermute_b32 v249, v238, v19
	v_lshl_add_u64 v[244:245], v[20:21], 0, v[240:241]
	s_waitcnt lgkmcnt(0)
	global_store_dwordx4 v[244:245], v[246:249], off
	v_cvt_pk_bf16_f32 v20, v16, v17
	v_lshl_add_u64 v[22:23], v[56:57], 1, s[58:59]
	v_cvt_pk_bf16_f32 v21, v18, v19
	ds_bpermute_b32 v250, v238, v20
	ds_bpermute_b32 v251, v238, v21
	v_lshl_add_u64 v[244:245], v[22:23], 0, v[242:243]
	s_waitcnt lgkmcnt(0)
	global_store_dwordx2 v[244:245], v[250:251], off
	v_mul_f32_e32 v20, v17, v17
	v_fmac_f32_e32 v20, v16, v16
	v_add_f32_e32 v16, v16, v17
	v_add_f32_e32 v17, v19, v18
	v_add_f32_e32 v24, v30, v24
	v_add_f32_e32 v16, v16, v17
	v_add_f32_e32 v16, v24, v16
	ds_bpermute_b32 v17, v122, v16
	v_mul_f32_e32 v21, v18, v18
	v_fmac_f32_e32 v21, v19, v19
	v_add_f32_e32 v20, v20, v21
	v_add_f32_e32 v20, v25, v20
	s_waitcnt lgkmcnt(0)
	v_add_f32_e32 v16, v16, v17
	ds_bpermute_b32 v17, v122, v20
	ds_bpermute_b32 v18, v123, v16
	s_waitcnt lgkmcnt(1)
	v_add_f32_e32 v17, v20, v17
	ds_bpermute_b32 v19, v123, v17
	s_and_saveexec_b64 s[20:21], s[4:5]
	s_cbranch_execz .LBB0_260
	v_lshl_add_u64 v[20:21], v[54:55], 3, s[54:55]
	s_waitcnt lgkmcnt(1)
	v_add_f32_e32 v16, v16, v18
	s_waitcnt lgkmcnt(0)
	v_add_f32_e32 v17, v17, v19
	global_atomic_add_f32 v[20:21], v16, off
	global_atomic_add_f32 v[20:21], v17, off offset:4
; __device__ __forceinline__ unsigned cvt_pk_bf16(float lo, float hi) { unsigned r; asm volatile("v_cvt_pk_bf16_f32 %0, %1, %2" : "=v"(r) : "v"(lo), "v"(hi)); return r; }
;     __device__ __forceinline__ void operator()(const f32x4 (&acc)[2][2][4][2], const Unit& u, int wr, int wc, int fr, int fq) const {
;     ...
;                 for (int mm = 0; mm < 2; ++mm) {
;                     const int r = row0 + ai * HALF + (2 * m2 + mm) * 16;
;                     float ps = 0.f, pq = 0.f;
; #pragma unroll
;                     for (int bj = 0; bj < 2; ++bj)
; #pragma unroll
;                         for (int n = 0; n < 2; ++n) {
;                             const f32x4 x = (xv[mm][bj][n] - st[mm][0]) * (gg[bj][n] * st[mm][1]) + bb[bj][n];
;                             const f32x4 o = x * alpha + acc[ai][bj][2 * m2 + mm][n] * scale;
;                             const size_t off = (size_t)r * D + col0 + bj * HALF + n * 16;
;                             *(f32x4*)(Y + off) = o;
;                             if (yb) { u32x2 w; w.x = cvt_pk_bf16(o[0], o[1]); w.y = cvt_pk_bf16(o[2], o[3]); *(u32x2*)(yb + off) = w; }
;                             ps += (o[0] + o[1]) + (o[2] + o[3]); pq += (o[0] * o[0] + o[1] * o[1]) + (o[2] * o[2] + o[3] * o[3]);
;                         }
;                     if (rout) {
;                         ps += __shfl_xor(ps, 16); pq += __shfl_xor(pq, 16); ps += __shfl_xor(ps, 32); pq += __shfl_xor(pq, 32);
;                         if (fq == 0) { atomicAdd(rout + 2 * (size_t)r, ps); atomicAdd(rout + 2 * (size_t)r + 1, pq); }
.LBB0_260:
	s_or_b64 exec, exec, s[20:21]
	v_lshlrev_b64 v[16:17], 11, v[52:53]
	s_waitcnt vmcnt(11) lgkmcnt(0)
	v_pk_add_f32 v[18:19], v[46:47], 0 op_sel_hi:[1,0]
	v_pk_add_f32 v[20:21], v[44:45], 0 op_sel_hi:[1,0]
	v_lshl_add_u64 v[16:17], v[16:17], 0, v[156:157]
	v_pk_mul_f32 v[18:19], v[18:19], s[12:13] op_sel_hi:[1,0]
	v_pk_mul_f32 v[20:21], v[20:21], s[12:13] op_sel_hi:[1,0]
	v_pk_fma_f32 v[14:15], v[14:15], 0.5, v[18:19] op_sel_hi:[1,0,1]
	v_pk_fma_f32 v[12:13], v[12:13], 0.5, v[20:21] op_sel_hi:[1,0,1]
	v_lshl_add_u64 v[18:19], v[16:17], 2, s[38:39]
	ds_bpermute_b32 v246, v238, v12
	ds_bpermute_b32 v247, v238, v13
	ds_bpermute_b32 v248, v238, v14
	ds_bpermute_b32 v249, v238, v15
	v_lshl_add_u64 v[244:245], v[18:19], 0, v[240:241]
	s_waitcnt lgkmcnt(0)
	global_store_dwordx4 v[244:245], v[246:249], off
	v_cvt_pk_bf16_f32 v18, v12, v13
	v_lshl_add_u64 v[20:21], v[16:17], 1, s[58:59]
	v_cvt_pk_bf16_f32 v19, v14, v15
	ds_bpermute_b32 v250, v238, v18
	ds_bpermute_b32 v251, v238, v19
	v_lshl_add_u64 v[244:245], v[20:21], 0, v[242:243]
	s_waitcnt lgkmcnt(0)
	global_store_dwordx2 v[244:245], v[250:251], off
	v_add_f32_e32 v18, v12, v13
	v_mul_f32_e32 v13, v13, v13
	v_fmac_f32_e32 v13, v12, v12
	v_mul_f32_e32 v12, v14, v14
	v_add_f32_e32 v19, v15, v14
	v_fmac_f32_e32 v12, v15, v15
	v_add_f32_e32 v18, v18, v19
	v_add_f32_e32 v19, v13, v12
	s_waitcnt vmcnt(12)
	v_pk_add_f32 v[12:13], v[42:43], 0 op_sel_hi:[1,0]
	v_pk_add_f32 v[14:15], v[40:41], 0 op_sel_hi:[1,0]
	v_pk_mul_f32 v[12:13], v[12:13], s[12:13] op_sel_hi:[1,0]
	v_pk_mul_f32 v[14:15], v[14:15], s[12:13] op_sel_hi:[1,0]
	v_pk_fma_f32 v[10:11], v[10:11], 0.5, v[12:13] op_sel_hi:[1,0,1]
	v_or_b32_e32 v12, 16, v16
	v_mov_b32_e32 v13, v17
	v_pk_fma_f32 v[8:9], v[8:9], 0.5, v[14:15] op_sel_hi:[1,0,1]
	v_lshl_add_u64 v[14:15], v[12:13], 2, s[38:39]
	v_lshl_add_u64 v[12:13], v[12:13], 1, s[58:59]
	ds_bpermute_b32 v246, v238, v8
	ds_bpermute_b32 v247, v238, v9
	ds_bpermute_b32 v248, v238, v10
	ds_bpermute_b32 v249, v238, v11
	v_lshl_add_u64 v[244:245], v[14:15], 0, v[240:241]
	s_waitcnt lgkmcnt(0)
	global_store_dwordx4 v[244:245], v[246:249], off
	v_cvt_pk_bf16_f32 v14, v8, v9
	v_cvt_pk_bf16_f32 v15, v10, v11
	ds_bpermute_b32 v250, v238, v14
	ds_bpermute_b32 v251, v238, v15
	v_lshl_add_u64 v[244:245], v[12:13], 0, v[242:243]
	s_waitcnt lgkmcnt(0)
	global_store_dwordx2 v[244:245], v[250:251], off
	v_add_f32_e32 v12, v8, v9
	v_mul_f32_e32 v9, v9, v9
	v_add_f32_e32 v13, v11, v10
	v_fmac_f32_e32 v9, v8, v8
	v_mul_f32_e32 v8, v10, v10
	v_add_f32_e32 v18, 0, v18
	v_add_f32_e32 v12, v12, v13
	v_fmac_f32_e32 v8, v11, v11
	v_add_f32_e32 v14, v18, v12
	v_add_f32_e32 v8, v9, v8
	s_waitcnt vmcnt(13)
	v_pk_add_f32 v[10:11], v[38:39], 0 op_sel_hi:[1,0]
	v_pk_add_f32 v[12:13], v[36:37], 0 op_sel_hi:[1,0]
	v_add_f32_e32 v15, v19, v8
	v_or_b32_e32 v8, 0x80, v16
	v_mov_b32_e32 v9, v17
	v_pk_mul_f32 v[10:11], v[10:11], s[12:13] op_sel_hi:[1,0]
	v_pk_mul_f32 v[12:13], v[12:13], s[12:13] op_sel_hi:[1,0]
	v_pk_fma_f32 v[6:7], v[6:7], 0.5, v[10:11] op_sel_hi:[1,0,1]
	v_pk_fma_f32 v[4:5], v[4:5], 0.5, v[12:13] op_sel_hi:[1,0,1]
	v_lshl_add_u64 v[10:11], v[8:9], 2, s[38:39]
	v_lshl_add_u64 v[8:9], v[8:9], 1, s[58:59]
	ds_bpermute_b32 v246, v238, v4
	ds_bpermute_b32 v247, v238, v5
	ds_bpermute_b32 v248, v238, v6
	ds_bpermute_b32 v249, v238, v7
	v_lshl_add_u64 v[244:245], v[10:11], 0, v[240:241]
	s_waitcnt lgkmcnt(0)
	global_store_dwordx4 v[244:245], v[246:249], off
	v_cvt_pk_bf16_f32 v10, v4, v5
	v_cvt_pk_bf16_f32 v11, v6, v7
	ds_bpermute_b32 v250, v238, v10
	ds_bpermute_b32 v251, v238, v11
	v_lshl_add_u64 v[244:245], v[8:9], 0, v[242:243]
	s_waitcnt lgkmcnt(0)
	global_store_dwordx2 v[244:245], v[250:251], off
	v_add_f32_e32 v8, v4, v5
	v_mul_f32_e32 v5, v5, v5
	v_fmac_f32_e32 v5, v4, v4
	v_mul_f32_e32 v4, v6, v6
	v_fmac_f32_e32 v4, v7, v7
	v_add_f32_e32 v9, v7, v6
	v_add_f32_e32 v4, v5, v4
	v_add_f32_e32 v8, v8, v9
	v_add_f32_e32 v11, v15, v4
	s_waitcnt vmcnt(14)
	v_pk_add_f32 v[4:5], v[34:35], 0 op_sel_hi:[1,0]
	v_pk_add_f32 v[6:7], v[32:33], 0 op_sel_hi:[1,0]
	v_add_f32_e32 v10, v14, v8
	v_pk_mul_f32 v[4:5], v[4:5], s[12:13] op_sel_hi:[1,0]
	v_pk_mul_f32 v[8:9], v[6:7], s[12:13] op_sel_hi:[1,0]
	v_pk_fma_f32 v[6:7], v[2:3], 0.5, v[4:5] op_sel_hi:[1,0,1]
	v_pk_fma_f32 v[4:5], v[0:1], 0.5, v[8:9] op_sel_hi:[1,0,1]
	v_mul_f32_e32 v1, v6, v6
	v_mul_f32_e32 v0, v5, v5
	v_fmac_f32_e32 v0, v4, v4
	v_fmac_f32_e32 v1, v7, v7
	v_add_f32_e32 v0, v0, v1
	v_add_f32_e32 v2, v11, v0
	v_add_f32_e32 v0, v4, v5
	v_add_f32_e32 v1, v7, v6
	v_add_f32_e32 v0, v0, v1
	v_add_f32_e32 v3, v10, v0
	ds_bpermute_b32 v8, v122, v3
	ds_bpermute_b32 v9, v122, v2
	v_or_b32_e32 v16, 0x90, v16
	v_lshl_add_u64 v[0:1], v[16:17], 2, s[38:39]
	ds_bpermute_b32 v246, v238, v4
	ds_bpermute_b32 v247, v238, v5
	ds_bpermute_b32 v248, v238, v6
	ds_bpermute_b32 v249, v238, v7
	v_lshl_add_u64 v[244:245], v[0:1], 0, v[240:241]
	s_waitcnt lgkmcnt(0)
	global_store_dwordx4 v[244:245], v[246:249], off
	s_waitcnt lgkmcnt(1)
	v_add_f32_e32 v0, v3, v8
	s_waitcnt lgkmcnt(0)
	v_add_f32_e32 v1, v2, v9
	ds_bpermute_b32 v2, v123, v0
	ds_bpermute_b32 v3, v123, v1
	v_cvt_pk_bf16_f32 v4, v4, v5
	v_cvt_pk_bf16_f32 v5, v6, v7
	v_lshl_add_u64 v[6:7], v[16:17], 1, s[58:59]
	ds_bpermute_b32 v250, v238, v4
	ds_bpermute_b32 v251, v238, v5
	v_lshl_add_u64 v[244:245], v[6:7], 0, v[242:243]
	s_waitcnt lgkmcnt(0)
	global_store_dwordx2 v[244:245], v[250:251], off
	s_and_saveexec_b64 s[20:21], s[4:5]
	s_cbranch_execz .LBB0_262
	v_lshl_add_u64 v[4:5], v[52:53], 3, s[54:55]
	s_waitcnt lgkmcnt(1)
	v_add_f32_e32 v0, v0, v2
	s_waitcnt lgkmcnt(0)
	v_add_f32_e32 v1, v1, v3
	global_atomic_add_f32 v[4:5], v0, off
	global_atomic_add_f32 v[4:5], v1, off offset:4

; __device__ __forceinline__ float bflo(unsigned w) { return __uint_as_float(w << 16); }
; __device__ __forceinline__ float bfhi(unsigned w) { return __uint_as_float(w & 0xffff0000u); }
; template <int MODE> ...
;     ...
; #pragma unroll
;             for (int k = 0; k < 3; ++k) {
;                 const int kb = kh * (BW / 2);
;                 const bf16_t* ap = A + (size_t)(rt * 16 + fr) * lda + k * BW + kb + fq * 8;
;                 const bf16_t* bp = Bt + (size_t)k * D * BW + (size_t)(ct * 16 + fr) * ldb + kb + fq * 8;
;                 f32x4 acc = (f32x4){0.f, 0.f, 0.f, 0.f};
; #pragma unroll 8
;                 for (int ks = 0; ks < BW / 64; ++ks) {
;                     const bf16x8 af = *(const bf16x8*)(ap + ks * 32), bfv = *(const bf16x8*)(bp + ks * 32);
;                     acc = __builtin_amdgcn_mfma_f32_16x16x32_bf16(bfv, af, acc, 0, 0, 0);
;                 }
;                 const u32x2 gw = *(const u32x2*)(Zs + (size_t)(rt * 16 + fr) * NZ + 5120 + k * 2048 + ct * 16 + 4 * fq);
;                 tot += acc * (f32x4){bflo(gw.x), bfhi(gw.x), bflo(gw.y), bfhi(gw.y)};
.LBB0_792:
	v_mbcnt_lo_u32_b32 v216, -1, 0
	v_mbcnt_hi_u32_b32 v216, -1, v216
	v_lshrrev_b32_e32 v217, 2, v216
	v_and_b32_e32 v220, 15, v216
	v_sub_u32_e32 v217, v217, v220
	v_mul_i32_i24_e32 v218, 0x1800, v217
	v_and_b32_e32 v221, 3, v216
	v_lshrrev_b32_e32 v223, 4, v216
	v_sub_u32_e32 v221, v221, v223
	v_lshlrev_b32_e32 v221, 4, v221
	v_add_u32_e32 v218, v218, v221
	v_ashrrev_i32_e32 v219, 31, v218
	v_lshl_or_b32 v222, v220, 2, v223
	v_lshlrev_b32_e32 v222, 2, v222
	v_mul_i32_i24_e32 v224, 0x800, v217
	v_add_u32_e32 v224, v224, v221
	v_ashrrev_i32_e32 v225, 31, v224
	s_lshl_b32 s0, s2, 15
	s_and_b32 s0, s0, 0x3e0000
	v_lshl_or_b32 v12, v177, 11, s0
	s_ashr_i32 s0, s2, 3
	v_and_or_b32 v32, s0, -16, v234
	v_mad_i64_i32 v[8:9], s[10:11], v32, s14, 0
	v_mad_i64_i32 v[6:7], s[10:11], v32, s14, v[16:17]
	v_lshl_add_u64 v[6:7], v[6:7], 0, v[218:219]
	v_lshl_add_u64 v[4:5], v[14:15], 0, v[12:13]
	v_lshl_add_u64 v[4:5], v[4:5], 0, v[224:225]
	v_ashrrev_i32_e32 v33, 31, v32
	s_mov_b64 s[10:11], 0
	v_mov_b32_e32 v0, v13
	v_mov_b32_e32 v1, v13
	v_mov_b32_e32 v2, v13
	v_mov_b32_e32 v3, v13
.LBB0_793:
	v_lshl_add_u64 v[66:67], v[4:5], 0, s[10:11]
	v_lshl_add_u64 v[10:11], v[6:7], 0, s[10:11]
	global_load_dwordx4 v[34:37], v[66:67], off offset:-256
	global_load_dwordx4 v[38:41], v[66:67], off offset:-192
	global_load_dwordx4 v[42:45], v[10:11], off offset:-256
	global_load_dwordx4 v[46:49], v[10:11], off offset:-192
	global_load_dwordx4 v[50:53], v[66:67], off offset:-128
	global_load_dwordx4 v[54:57], v[10:11], off offset:-128
	global_load_dwordx4 v[58:61], v[66:67], off offset:-64
	global_load_dwordx4 v[62:65], v[10:11], off offset:-64
	s_add_u32 s10, s10, 0x200
	s_addc_u32 s11, s11, 0
	s_cmpk_eq_i32 s10, 0x400
	s_waitcnt vmcnt(5)
	ds_bpermute_b32 v34, v222, v34
	ds_bpermute_b32 v35, v222, v35
	ds_bpermute_b32 v36, v222, v36
	ds_bpermute_b32 v37, v222, v37
	ds_bpermute_b32 v42, v222, v42
	ds_bpermute_b32 v43, v222, v43
	ds_bpermute_b32 v44, v222, v44
	ds_bpermute_b32 v45, v222, v45
	s_waitcnt lgkmcnt(0)
	v_mfma_f32_16x16x32_bf16 v[0:3], v[34:37], v[42:45], v[0:3]
	global_load_dwordx4 v[34:37], v[66:67], off
	global_load_dwordx4 v[42:45], v[10:11], off
	s_waitcnt vmcnt(6)
	ds_bpermute_b32 v38, v222, v38
	ds_bpermute_b32 v39, v222, v39
	ds_bpermute_b32 v40, v222, v40
	ds_bpermute_b32 v41, v222, v41
	ds_bpermute_b32 v46, v222, v46
	ds_bpermute_b32 v47, v222, v47
	ds_bpermute_b32 v48, v222, v48
	ds_bpermute_b32 v49, v222, v49
	s_waitcnt lgkmcnt(0)
	v_mfma_f32_16x16x32_bf16 v[0:3], v[38:41], v[46:49], v[0:3]
	global_load_dwordx4 v[38:41], v[66:67], off offset:64
	global_load_dwordx4 v[46:49], v[10:11], off offset:64
	s_waitcnt vmcnt(6)
	ds_bpermute_b32 v50, v222, v50
	ds_bpermute_b32 v51, v222, v51
	ds_bpermute_b32 v52, v222, v52
	ds_bpermute_b32 v53, v222, v53
	ds_bpermute_b32 v54, v222, v54
	ds_bpermute_b32 v55, v222, v55
	ds_bpermute_b32 v56, v222, v56
	ds_bpermute_b32 v57, v222, v57
	s_waitcnt lgkmcnt(0)
	v_mfma_f32_16x16x32_bf16 v[0:3], v[50:53], v[54:57], v[0:3]
	global_load_dwordx4 v[50:53], v[66:67], off offset:128
	global_load_dwordx4 v[54:57], v[10:11], off offset:128
	s_waitcnt vmcnt(6)
	ds_bpermute_b32 v58, v222, v58
	ds_bpermute_b32 v59, v222, v59
	ds_bpermute_b32 v60, v222, v60
	ds_bpermute_b32 v61, v222, v61
	ds_bpermute_b32 v62, v222, v62
	ds_bpermute_b32 v63, v222, v63
	ds_bpermute_b32 v64, v222, v64
	ds_bpermute_b32 v65, v222, v65
	s_waitcnt lgkmcnt(0)
	v_mfma_f32_16x16x32_bf16 v[0:3], v[58:61], v[62:65], v[0:3]
	s_waitcnt vmcnt(4)
	ds_bpermute_b32 v34, v222, v34
	ds_bpermute_b32 v35, v222, v35
	ds_bpermute_b32 v36, v222, v36
	ds_bpermute_b32 v37, v222, v37
	ds_bpermute_b32 v42, v222, v42
	ds_bpermute_b32 v43, v222, v43
	ds_bpermute_b32 v44, v222, v44
	ds_bpermute_b32 v45, v222, v45
	s_waitcnt lgkmcnt(0)
	v_mfma_f32_16x16x32_bf16 v[0:3], v[34:37], v[42:45], v[0:3]
	global_load_dwordx4 v[34:37], v[66:67], off offset:192
	s_waitcnt vmcnt(3)
	ds_bpermute_b32 v38, v222, v38
	ds_bpermute_b32 v39, v222, v39
	ds_bpermute_b32 v40, v222, v40
	ds_bpermute_b32 v41, v222, v41
	ds_bpermute_b32 v46, v222, v46
	ds_bpermute_b32 v47, v222, v47
	ds_bpermute_b32 v48, v222, v48
	ds_bpermute_b32 v49, v222, v49
	s_waitcnt lgkmcnt(0)
	v_mfma_f32_16x16x32_bf16 v[0:3], v[38:41], v[46:49], v[0:3]
	global_load_dwordx4 v[38:41], v[10:11], off offset:192
	s_waitcnt vmcnt(2)
	ds_bpermute_b32 v50, v222, v50
	ds_bpermute_b32 v51, v222, v51
	ds_bpermute_b32 v52, v222, v52
	ds_bpermute_b32 v53, v222, v53
	ds_bpermute_b32 v54, v222, v54
	ds_bpermute_b32 v55, v222, v55
	ds_bpermute_b32 v56, v222, v56
	ds_bpermute_b32 v57, v222, v57
	s_waitcnt lgkmcnt(0)
	v_mfma_f32_16x16x32_bf16 v[0:3], v[50:53], v[54:57], v[0:3]
	s_waitcnt vmcnt(0)
	ds_bpermute_b32 v34, v222, v34
	ds_bpermute_b32 v35, v222, v35
	ds_bpermute_b32 v36, v222, v36
	ds_bpermute_b32 v37, v222, v37
	ds_bpermute_b32 v38, v222, v38
	ds_bpermute_b32 v39, v222, v39
	ds_bpermute_b32 v40, v222, v40
	ds_bpermute_b32 v41, v222, v41
	s_waitcnt lgkmcnt(0)
	v_mfma_f32_16x16x32_bf16 v[0:3], v[34:37], v[38:41], v[0:3]
	s_cbranch_scc0 .LBB0_793
	s_and_b32 s0, s2, 0x7c
	s_or_b32 s17, s0, s56
	v_mad_i64_i32 v[4:5], s[10:11], v32, s15, v[26:27]
	s_lshl_b32 s0, s17, 5
	v_lshl_add_u64 v[4:5], v[4:5], 0, s[0:1]
	v_lshl_add_u64 v[4:5], v[4:5], 0, v[30:31]
	v_add_co_u32_e32 v6, vcc, 0x19da2000, v4
	v_lshl_add_u64 v[36:37], v[4:5], 0, s[8:9]
	s_nop 0
	v_addc_co_u32_e32 v7, vcc, 0, v5, vcc
	global_load_dwordx2 v[34:35], v[6:7], off offset:2048
	v_mov_b32_e32 v4, 0
	v_lshl_add_u64 v[10:11], v[20:21], 0, v[12:13]
	v_lshl_add_u64 v[10:11], v[10:11], 0, v[224:225]
	s_lshl_b32 s0, s17, 4
	v_lshl_add_u64 v[38:39], v[18:19], 0, v[8:9]
	v_lshl_add_u64 v[38:39], v[38:39], 0, v[218:219]
	s_mov_b64 s[10:11], 0
	v_mov_b32_e32 v5, v4
	v_mov_b32_e32 v6, v4
	v_mov_b32_e32 v7, v4
; template <int MODE> ...
;     ...
;             for (int k = 0; k < 3; ++k) {
;                 const int kb = kh * (BW / 2);
;                 const bf16_t* ap = A + (size_t)(rt * 16 + fr) * lda + k * BW + kb + fq * 8;
;                 const bf16_t* bp = Bt + (size_t)k * D * BW + (size_t)(ct * 16 + fr) * ldb + kb + fq * 8;
;                 f32x4 acc = (f32x4){0.f, 0.f, 0.f, 0.f};
; #pragma unroll 8
;                 for (int ks = 0; ks < BW / 64; ++ks) {
;                     const bf16x8 af = *(const bf16x8*)(ap + ks * 32), bfv = *(const bf16x8*)(bp + ks * 32);
;                     acc = __builtin_amdgcn_mfma_f32_16x16x32_bf16(bfv, af, acc, 0, 0, 0);
;                 }
.LBB0_795:
	v_lshl_add_u64 v[74:75], v[10:11], 0, s[10:11]
	v_lshl_add_u64 v[72:73], v[38:39], 0, s[10:11]
	global_load_dwordx4 v[40:43], v[74:75], off offset:-256
	global_load_dwordx4 v[44:47], v[74:75], off offset:-192
	global_load_dwordx4 v[48:51], v[72:73], off offset:-256
	global_load_dwordx4 v[52:55], v[72:73], off offset:-192
	global_load_dwordx4 v[56:59], v[74:75], off offset:-128
	global_load_dwordx4 v[60:63], v[72:73], off offset:-128
	global_load_dwordx4 v[64:67], v[74:75], off offset:-64
	global_load_dwordx4 v[68:71], v[72:73], off offset:-64
	s_add_u32 s10, s10, 0x200
	s_addc_u32 s11, s11, 0
	s_cmpk_lg_i32 s10, 0x400
	s_waitcnt vmcnt(5)
	ds_bpermute_b32 v40, v222, v40
	ds_bpermute_b32 v41, v222, v41
	ds_bpermute_b32 v42, v222, v42
	ds_bpermute_b32 v43, v222, v43
	ds_bpermute_b32 v48, v222, v48
	ds_bpermute_b32 v49, v222, v49
	ds_bpermute_b32 v50, v222, v50
	ds_bpermute_b32 v51, v222, v51
	s_waitcnt lgkmcnt(0)
	v_mfma_f32_16x16x32_bf16 v[4:7], v[40:43], v[48:51], v[4:7]
	global_load_dwordx4 v[40:43], v[74:75], off
	global_load_dwordx4 v[48:51], v[72:73], off
	s_waitcnt vmcnt(6)
	ds_bpermute_b32 v44, v222, v44
	ds_bpermute_b32 v45, v222, v45
	ds_bpermute_b32 v46, v222, v46
	ds_bpermute_b32 v47, v222, v47
	ds_bpermute_b32 v52, v222, v52
	ds_bpermute_b32 v53, v222, v53
	ds_bpermute_b32 v54, v222, v54
	ds_bpermute_b32 v55, v222, v55
	s_waitcnt lgkmcnt(0)
	v_mfma_f32_16x16x32_bf16 v[4:7], v[44:47], v[52:55], v[4:7]
	global_load_dwordx4 v[44:47], v[74:75], off offset:64
	global_load_dwordx4 v[52:55], v[72:73], off offset:64
	s_waitcnt vmcnt(6)
	ds_bpermute_b32 v56, v222, v56
	ds_bpermute_b32 v57, v222, v57
	ds_bpermute_b32 v58, v222, v58
	ds_bpermute_b32 v59, v222, v59
	ds_bpermute_b32 v60, v222, v60
	ds_bpermute_b32 v61, v222, v61
	ds_bpermute_b32 v62, v222, v62
	ds_bpermute_b32 v63, v222, v63
	s_waitcnt lgkmcnt(0)
	v_mfma_f32_16x16x32_bf16 v[4:7], v[56:59], v[60:63], v[4:7]
	global_load_dwordx4 v[56:59], v[74:75], off offset:128
	global_load_dwordx4 v[60:63], v[72:73], off offset:128
	s_waitcnt vmcnt(6)
	ds_bpermute_b32 v64, v222, v64
	ds_bpermute_b32 v65, v222, v65
	ds_bpermute_b32 v66, v222, v66
	ds_bpermute_b32 v67, v222, v67
	ds_bpermute_b32 v68, v222, v68
	ds_bpermute_b32 v69, v222, v69
	ds_bpermute_b32 v70, v222, v70
	ds_bpermute_b32 v71, v222, v71
	s_waitcnt lgkmcnt(0)
	v_mfma_f32_16x16x32_bf16 v[4:7], v[64:67], v[68:71], v[4:7]
	s_waitcnt vmcnt(4)
	ds_bpermute_b32 v40, v222, v40
	ds_bpermute_b32 v41, v222, v41
	ds_bpermute_b32 v42, v222, v42
	ds_bpermute_b32 v43, v222, v43
	ds_bpermute_b32 v48, v222, v48
	ds_bpermute_b32 v49, v222, v49
	ds_bpermute_b32 v50, v222, v50
	ds_bpermute_b32 v51, v222, v51
	s_waitcnt lgkmcnt(0)
	v_mfma_f32_16x16x32_bf16 v[4:7], v[40:43], v[48:51], v[4:7]
	global_load_dwordx4 v[40:43], v[74:75], off offset:192
	s_waitcnt vmcnt(3)
	ds_bpermute_b32 v44, v222, v44
	ds_bpermute_b32 v45, v222, v45
	ds_bpermute_b32 v46, v222, v46
	ds_bpermute_b32 v47, v222, v47
	ds_bpermute_b32 v52, v222, v52
	ds_bpermute_b32 v53, v222, v53
	ds_bpermute_b32 v54, v222, v54
	ds_bpermute_b32 v55, v222, v55
	s_waitcnt lgkmcnt(0)
	v_mfma_f32_16x16x32_bf16 v[4:7], v[44:47], v[52:55], v[4:7]
	global_load_dwordx4 v[44:47], v[72:73], off offset:192
	s_waitcnt vmcnt(2)
	ds_bpermute_b32 v56, v222, v56
	ds_bpermute_b32 v57, v222, v57
	ds_bpermute_b32 v58, v222, v58
	ds_bpermute_b32 v59, v222, v59
	ds_bpermute_b32 v60, v222, v60
	ds_bpermute_b32 v61, v222, v61
	ds_bpermute_b32 v62, v222, v62
	ds_bpermute_b32 v63, v222, v63
	s_waitcnt lgkmcnt(0)
	v_mfma_f32_16x16x32_bf16 v[4:7], v[56:59], v[60:63], v[4:7]
	s_waitcnt vmcnt(0)
	ds_bpermute_b32 v40, v222, v40
	ds_bpermute_b32 v41, v222, v41
	ds_bpermute_b32 v42, v222, v42
	ds_bpermute_b32 v43, v222, v43
	ds_bpermute_b32 v44, v222, v44
	ds_bpermute_b32 v45, v222, v45
	ds_bpermute_b32 v46, v222, v46
	ds_bpermute_b32 v47, v222, v47
	s_waitcnt lgkmcnt(0)
	v_mfma_f32_16x16x32_bf16 v[4:7], v[40:43], v[44:47], v[4:7]
	s_cbranch_scc1 .LBB0_795
	v_add_co_u32_e32 v10, vcc, 0x1000, v36
	v_lshl_add_u64 v[42:43], v[22:23], 0, v[8:9]
	v_lshl_add_u64 v[42:43], v[42:43], 0, v[218:219]
	s_nop 0
	v_addc_co_u32_e32 v11, vcc, 0, v37, vcc
	global_load_dwordx2 v[38:39], v[10:11], off
	v_mov_b32_e32 v8, 0
	v_lshl_add_u64 v[40:41], v[24:25], 0, v[12:13]
	v_lshl_add_u64 v[40:41], v[40:41], 0, v[224:225]
	s_mov_b64 s[10:11], 0
	v_mov_b32_e32 v9, v8
	v_mov_b32_e32 v10, v8
	v_mov_b32_e32 v11, v8
; __device__ __forceinline__ float bflo(unsigned w) { return __uint_as_float(w << 16); }
; __device__ __forceinline__ float bfhi(unsigned w) { return __uint_as_float(w & 0xffff0000u); }
; template <int MODE> ...
;     ...
;             for (int k = 0; k < 3; ++k) {
;                 const int kb = kh * (BW / 2);
;                 const bf16_t* ap = A + (size_t)(rt * 16 + fr) * lda + k * BW + kb + fq * 8;
;                 const bf16_t* bp = Bt + (size_t)k * D * BW + (size_t)(ct * 16 + fr) * ldb + kb + fq * 8;
;                 f32x4 acc = (f32x4){0.f, 0.f, 0.f, 0.f};
; #pragma unroll 8
;                 for (int ks = 0; ks < BW / 64; ++ks) {
;                     const bf16x8 af = *(const bf16x8*)(ap + ks * 32), bfv = *(const bf16x8*)(bp + ks * 32);
;                     acc = __builtin_amdgcn_mfma_f32_16x16x32_bf16(bfv, af, acc, 0, 0, 0);
;                 }
;                 const u32x2 gw = *(const u32x2*)(Zs + (size_t)(rt * 16 + fr) * NZ + 5120 + k * 2048 + ct * 16 + 4 * fq);
;                 tot += acc * (f32x4){bflo(gw.x), bfhi(gw.x), bflo(gw.y), bfhi(gw.y)};
;             }
;         }
;         if (kh == 1) red[tw * 64 + lane] = tot;
.LBB0_797:
	v_lshl_add_u64 v[78:79], v[40:41], 0, s[10:11]
	v_lshl_add_u64 v[76:77], v[42:43], 0, s[10:11]
	global_load_dwordx4 v[44:47], v[78:79], off offset:-256
	global_load_dwordx4 v[48:51], v[78:79], off offset:-192
	global_load_dwordx4 v[52:55], v[76:77], off offset:-256
	global_load_dwordx4 v[56:59], v[76:77], off offset:-192
	global_load_dwordx4 v[60:63], v[78:79], off offset:-128
	global_load_dwordx4 v[64:67], v[76:77], off offset:-128
	global_load_dwordx4 v[68:71], v[78:79], off offset:-64
	global_load_dwordx4 v[72:75], v[76:77], off offset:-64
	s_add_u32 s10, s10, 0x200
	s_addc_u32 s11, s11, 0
	s_cmpk_lg_i32 s10, 0x400
	s_waitcnt vmcnt(5)
	ds_bpermute_b32 v44, v222, v44
	ds_bpermute_b32 v45, v222, v45
	ds_bpermute_b32 v46, v222, v46
	ds_bpermute_b32 v47, v222, v47
	ds_bpermute_b32 v52, v222, v52
	ds_bpermute_b32 v53, v222, v53
	ds_bpermute_b32 v54, v222, v54
	ds_bpermute_b32 v55, v222, v55
	s_waitcnt lgkmcnt(0)
	v_mfma_f32_16x16x32_bf16 v[8:11], v[44:47], v[52:55], v[8:11]
	global_load_dwordx4 v[44:47], v[78:79], off
	global_load_dwordx4 v[52:55], v[76:77], off
	s_waitcnt vmcnt(6)
	ds_bpermute_b32 v48, v222, v48
	ds_bpermute_b32 v49, v222, v49
	ds_bpermute_b32 v50, v222, v50
	ds_bpermute_b32 v51, v222, v51
	ds_bpermute_b32 v56, v222, v56
	ds_bpermute_b32 v57, v222, v57
	ds_bpermute_b32 v58, v222, v58
	ds_bpermute_b32 v59, v222, v59
	s_waitcnt lgkmcnt(0)
	v_mfma_f32_16x16x32_bf16 v[8:11], v[48:51], v[56:59], v[8:11]
	global_load_dwordx4 v[48:51], v[78:79], off offset:64
	global_load_dwordx4 v[56:59], v[76:77], off offset:64
	s_waitcnt vmcnt(6)
	ds_bpermute_b32 v60, v222, v60
	ds_bpermute_b32 v61, v222, v61
	ds_bpermute_b32 v62, v222, v62
	ds_bpermute_b32 v63, v222, v63
	ds_bpermute_b32 v64, v222, v64
	ds_bpermute_b32 v65, v222, v65
	ds_bpermute_b32 v66, v222, v66
	ds_bpermute_b32 v67, v222, v67
	s_waitcnt lgkmcnt(0)
	v_mfma_f32_16x16x32_bf16 v[8:11], v[60:63], v[64:67], v[8:11]
	global_load_dwordx4 v[60:63], v[78:79], off offset:128
	global_load_dwordx4 v[64:67], v[76:77], off offset:128
	s_waitcnt vmcnt(6)
	ds_bpermute_b32 v68, v222, v68
	ds_bpermute_b32 v69, v222, v69
	ds_bpermute_b32 v70, v222, v70
	ds_bpermute_b32 v71, v222, v71
	ds_bpermute_b32 v72, v222, v72
	ds_bpermute_b32 v73, v222, v73
	ds_bpermute_b32 v74, v222, v74
	ds_bpermute_b32 v75, v222, v75
	s_waitcnt lgkmcnt(0)
	v_mfma_f32_16x16x32_bf16 v[8:11], v[68:71], v[72:75], v[8:11]
	s_waitcnt vmcnt(4)
	ds_bpermute_b32 v44, v222, v44
	ds_bpermute_b32 v45, v222, v45
	ds_bpermute_b32 v46, v222, v46
	ds_bpermute_b32 v47, v222, v47
	ds_bpermute_b32 v52, v222, v52
	ds_bpermute_b32 v53, v222, v53
	ds_bpermute_b32 v54, v222, v54
	ds_bpermute_b32 v55, v222, v55
	s_waitcnt lgkmcnt(0)
	v_mfma_f32_16x16x32_bf16 v[8:11], v[44:47], v[52:55], v[8:11]
	global_load_dwordx4 v[44:47], v[78:79], off offset:192
	s_waitcnt vmcnt(3)
	ds_bpermute_b32 v48, v222, v48
	ds_bpermute_b32 v49, v222, v49
	ds_bpermute_b32 v50, v222, v50
	ds_bpermute_b32 v51, v222, v51
	ds_bpermute_b32 v56, v222, v56
	ds_bpermute_b32 v57, v222, v57
	ds_bpermute_b32 v58, v222, v58
	ds_bpermute_b32 v59, v222, v59
	s_waitcnt lgkmcnt(0)
	v_mfma_f32_16x16x32_bf16 v[8:11], v[48:51], v[56:59], v[8:11]
	global_load_dwordx4 v[48:51], v[76:77], off offset:192
	s_waitcnt vmcnt(2)
	ds_bpermute_b32 v60, v222, v60
	ds_bpermute_b32 v61, v222, v61
	ds_bpermute_b32 v62, v222, v62
	ds_bpermute_b32 v63, v222, v63
	ds_bpermute_b32 v64, v222, v64
	ds_bpermute_b32 v65, v222, v65
	ds_bpermute_b32 v66, v222, v66
	ds_bpermute_b32 v67, v222, v67
	s_waitcnt lgkmcnt(0)
	v_mfma_f32_16x16x32_bf16 v[8:11], v[60:63], v[64:67], v[8:11]
	s_waitcnt vmcnt(0)
	ds_bpermute_b32 v44, v222, v44
	ds_bpermute_b32 v45, v222, v45
	ds_bpermute_b32 v46, v222, v46
	ds_bpermute_b32 v47, v222, v47
	ds_bpermute_b32 v48, v222, v48
	ds_bpermute_b32 v49, v222, v49
	ds_bpermute_b32 v50, v222, v50
	ds_bpermute_b32 v51, v222, v51
	s_waitcnt lgkmcnt(0)
	v_mfma_f32_16x16x32_bf16 v[8:11], v[44:47], v[48:51], v[8:11]
	s_cbranch_scc1 .LBB0_797
	v_add_co_u32_e32 v36, vcc, s16, v36
	v_lshlrev_b32_e32 v40, 16, v34
	s_nop 0
	v_addc_co_u32_e32 v37, vcc, 0, v37, vcc
	global_load_dwordx2 v[36:37], v[36:37], off
	v_and_b32_e32 v41, 0xffff0000, v34
	v_lshlrev_b32_e32 v34, 16, v35
	v_and_b32_e32 v35, 0xffff0000, v35
	v_lshlrev_b32_e32 v42, 16, v38
	v_and_b32_e32 v43, 0xffff0000, v38
	v_lshlrev_b32_e32 v38, 16, v39
	v_and_b32_e32 v39, 0xffff0000, v39
	v_pk_fma_f32 v[2:3], v[2:3], v[34:35], 0 op_sel_hi:[1,1,0]
	v_pk_fma_f32 v[0:1], v[0:1], v[40:41], 0 op_sel_hi:[1,1,0]
	v_pk_fma_f32 v[2:3], v[6:7], v[38:39], v[2:3]
	v_pk_fma_f32 v[0:1], v[4:5], v[42:43], v[0:1]
	s_and_b64 vcc, exec, s[4:5]
	s_waitcnt vmcnt(0)
	v_lshlrev_b32_e32 v4, 16, v36
	v_and_b32_e32 v5, 0xffff0000, v36
	v_lshlrev_b32_e32 v6, 16, v37
	v_and_b32_e32 v7, 0xffff0000, v37
	v_pk_fma_f32 v[2:3], v[10:11], v[6:7], v[2:3]
	v_pk_fma_f32 v[0:1], v[8:9], v[4:5], v[0:1]
	s_cbranch_vccz .LBB0_800
	v_add_u32_e32 v4, s3, v235
	ds_write_b128 v4, v[0:3]

; __device__ __forceinline__ f32x2 ln_stats(f32x2 sm) { const float mu = sm[0] * (1.f / D); const float var = fmaxf(sm[1] * (1.f / D) - mu * mu, 0.f); return (f32x2){mu, 1.0f / sqrtf(var + LN_EPS)}; }
;     __device__ __forceinline__ void operator()(const f32x4 (&acc)[2][2][4][2], const Unit& u, int wr, int wc, int fr, int fq) const {
;     ...
;                 f32x4 xv[2][2][2]; f32x2 st[2];
; #pragma unroll
;                 for (int mm = 0; mm < 2; ++mm) {
;                     const int r = row0 + ai * HALF + (2 * m2 + mm) * 16;
;                     st[mm] = (f32x2){0.f, 1.f};
;                     if (rin) st[mm] = ln_stats(*(const f32x2*)(rin + 2 * (size_t)r));
; #pragma unroll
;                     for (int bj = 0; bj < 2; ++bj)
; #pragma unroll
;                         for (int n = 0; n < 2; ++n) { const f32x4* rp = (const f32x4*)(res + (size_t)r * D + col0 + bj * HALF + n * 16); xv[mm][bj][n] = stream ? __builtin_nontemporal_load(rp) : *rp; }
;                 }
; #pragma unroll
;                 for (int mm = 0; mm < 2; ++mm) {
;                     const int r = row0 + ai * HALF + (2 * m2 + mm) * 16;
;                     float ps = 0.f, pq = 0.f;
; #pragma unroll
;                     for (int bj = 0; bj < 2; ++bj)
; #pragma unroll
;                         for (int n = 0; n < 2; ++n) {
;                             const f32x4 x = (xv[mm][bj][n] - st[mm][0]) * (gg[bj][n] * st[mm][1]) + bb[bj][n];
;                             const f32x4 o = x * alpha + acc[ai][bj][2 * m2 + mm][n] * scale;
;                             const size_t off = (size_t)r * D + col0 + bj * HALF + n * 16;
;                             *(f32x4*)(Y + off) = o;
.LBB0_1123:
	v_mbcnt_lo_u32_b32 v246, -1, 0
	v_mbcnt_hi_u32_b32 v246, -1, v246
	v_lshrrev_b32_e32 v247, 2, v246
	v_and_b32_e32 v248, 3, v246
	v_lshl_add_u32 v238, v248, 4, v247
	v_lshlrev_b32_e32 v238, 2, v238
	v_and_b32_e32 v249, 15, v246
	v_sub_u32_e32 v247, v247, v249
	v_lshrrev_b32_e32 v249, 4, v246
	v_sub_u32_e32 v248, v248, v249
	v_mul_i32_i24_e32 v240, 0x2000, v247
	v_lshl_add_u32 v240, v248, 4, v240
	v_ashrrev_i32_e32 v241, 31, v240
	v_mul_i32_i24_e32 v242, 0x1000, v247
	v_lshl_add_u32 v242, v248, 3, v242
	v_ashrrev_i32_e32 v243, 31, v242
	v_lshl_or_b32 v96, s48, 8, v177
	v_lshl_add_u32 v172, s47, 8, v174
	v_ashrrev_i32_e32 v97, 31, v96
	v_ashrrev_i32_e32 v173, 31, v172
	v_lshlrev_b64 v[168:169], 2, v[96:97]
	v_lshl_add_u64 v[96:97], v[172:173], 3, s[8:9]
	global_load_dwordx2 v[216:217], v[96:97], off
	v_or_b32_e32 v98, 16, v172
	v_ashrrev_i32_e32 v99, 31, v98
	v_lshl_add_u64 v[170:171], s[38:39], 0, v[168:169]
	v_lshlrev_b64 v[96:97], 13, v[172:173]
	v_lshl_add_u64 v[100:101], v[98:99], 3, s[8:9]
	v_lshl_add_u64 v[196:197], v[170:171], 0, v[96:97]
	global_load_dwordx2 v[218:219], v[100:101], off
	global_load_dwordx4 v[184:187], v[196:197], off
	global_load_dwordx4 v[188:191], v[196:197], off offset:64
	global_load_dwordx4 v[192:195], v[196:197], off offset:576
	v_readlane_b32 s48, v254, 27
	v_readlane_b32 s50, v254, 29
	v_readlane_b32 s51, v254, 30
	v_readlane_b32 s58, v254, 37
	v_readlane_b32 s59, v254, 38
	v_readlane_b32 s52, v254, 31
	v_readlane_b32 s53, v254, 32
	v_readlane_b32 s60, v254, 39
	v_readlane_b32 s61, v254, 40
	s_mov_b64 s[50:51], s[58:59]
	s_mov_b64 s[52:53], s[60:61]
	v_lshl_add_u64 v[100:101], s[50:51], 0, v[168:169]
	v_lshl_add_u64 v[198:199], s[52:53], 0, v[168:169]
	v_lshlrev_b64 v[220:221], 13, v[98:99]
	v_lshl_add_u64 v[200:201], s[38:39], 0, v[96:97]
	global_load_dwordx4 v[124:127], v[100:101], off
	global_load_dwordx4 v[116:119], v[100:101], off offset:64
	global_load_dwordx4 v[120:123], v[198:199], off
	global_load_dwordx4 v[112:115], v[198:199], off offset:64
	global_load_dwordx4 v[108:111], v[100:101], off offset:512
	s_nop 0
	global_load_dwordx4 v[100:103], v[100:101], off offset:576
	s_nop 0
	global_load_dwordx4 v[104:107], v[198:199], off offset:512
	global_load_dwordx4 v[96:99], v[198:199], off offset:576
	v_lshl_add_u64 v[212:213], v[170:171], 0, v[220:221]
	v_lshl_add_u64 v[222:223], v[200:201], 0, v[168:169]
	global_load_dwordx4 v[196:199], v[196:197], off offset:512
	s_nop 0
	global_load_dwordx4 v[200:203], v[212:213], off
	global_load_dwordx4 v[204:207], v[212:213], off offset:64
	global_load_dwordx4 v[208:211], v[212:213], off offset:512
	s_nop 0
	global_load_dwordx4 v[212:215], v[212:213], off offset:576
	v_readlane_b32 s49, v254, 28
	v_readlane_b32 s54, v254, 33
	v_readlane_b32 s55, v254, 34
	v_readlane_b32 s56, v254, 35
	v_readlane_b32 s57, v254, 36
	v_readlane_b32 s62, v254, 41
	v_readlane_b32 s63, v254, 42
	s_waitcnt vmcnt(0)
	v_pk_mul_f32 v[216:217], v[216:217], s[14:15] op_sel_hi:[1,0]
	s_nop 0
	v_fma_f32 v173, -v216, v216, v217
	v_max_f32_e32 v173, 0, v173
	v_add_f32_e32 v173, 0x3727c5ac, v173
	v_pk_mul_f32 v[218:219], v[218:219], s[14:15] op_sel_hi:[1,0]
	v_mul_f32_e32 v217, 0x4f800000, v173
	v_fma_f32 v183, -v218, v218, v219
	v_cmp_gt_f32_e32 vcc, s44, v173
	v_max_f32_e32 v183, 0, v183
	v_add_f32_e32 v183, 0x3727c5ac, v183
	v_cndmask_b32_e32 v173, v173, v217, vcc
	v_sqrt_f32_e32 v217, v173
	v_mul_f32_e32 v219, 0x4f800000, v183
	v_cmp_gt_f32_e64 s[0:1], s44, v183
	v_sub_f32_e32 v185, v185, v216
	v_add_u32_e32 v224, -1, v217
	v_cndmask_b32_e64 v183, v183, v219, s[0:1]
	v_sqrt_f32_e32 v219, v183
	v_add_u32_e32 v225, 1, v217
	v_fma_f32 v226, -v224, v217, v173
	v_fma_f32 v227, -v225, v217, v173
	v_cmp_ge_f32_e64 s[4:5], 0, v226
	v_add_u32_e32 v226, 1, v219
	v_sub_f32_e32 v184, v184, v216
	v_cndmask_b32_e64 v217, v217, v224, s[4:5]
	v_add_u32_e32 v224, -1, v219
	v_cmp_lt_f32_e64 s[4:5], 0, v227
	v_fma_f32 v227, -v226, v219, v183
	v_sub_f32_e32 v187, v187, v216
	v_cndmask_b32_e64 v217, v217, v225, s[4:5]
	v_fma_f32 v225, -v224, v219, v183
	v_mul_f32_e32 v228, 0x37800000, v217
	v_cmp_ge_f32_e64 s[4:5], 0, v225
	v_cndmask_b32_e32 v217, v217, v228, vcc
	v_cmp_lt_f32_e32 vcc, 0, v227
	v_cndmask_b32_e64 v219, v219, v224, s[4:5]
	v_sub_f32_e32 v186, v186, v216
	v_cndmask_b32_e32 v219, v219, v226, vcc
	v_cmp_class_f32_e32 vcc, v173, v182
	v_sub_f32_e32 v189, v189, v216
	v_sub_f32_e32 v188, v188, v216
	v_cndmask_b32_e32 v173, v217, v173, vcc
	v_mul_f32_e32 v217, 0x37800000, v219
	v_div_scale_f32 v224, s[4:5], v173, v173, 1.0
	v_cndmask_b32_e64 v217, v219, v217, s[0:1]
	v_cmp_class_f32_e64 s[0:1], v183, v182
	v_rcp_f32_e32 v219, v224
	v_div_scale_f32 v225, vcc, 1.0, v173, 1.0
	v_cndmask_b32_e64 v183, v217, v183, s[0:1]
	v_div_scale_f32 v217, s[0:1], v183, v183, 1.0
	v_rcp_f32_e32 v227, v217
	v_fma_f32 v228, -v224, v219, 1.0
	v_fmac_f32_e32 v219, v228, v219
	v_mul_f32_e32 v228, v225, v219
	v_fma_f32 v229, -v217, v227, 1.0
	v_div_scale_f32 v226, s[0:1], 1.0, v183, 1.0
	v_fma_f32 v230, -v224, v228, v225
	v_fmac_f32_e32 v227, v229, v227
	v_fmac_f32_e32 v228, v230, v219
	v_mul_f32_e32 v229, v226, v227
	v_fma_f32 v224, -v224, v228, v225
	v_fma_f32 v225, -v217, v229, v226
	v_div_fmas_f32 v219, v224, v219, v228
	v_fmac_f32_e32 v229, v225, v227
	v_div_fixup_f32 v224, v219, v173, 1.0
	v_fma_f32 v173, -v217, v229, v226
	s_mov_b64 vcc, s[0:1]
	v_div_fmas_f32 v173, v173, v227, v229
	v_pk_mul_f32 v[226:227], v[124:125], v[224:225] op_sel_hi:[1,0]
	v_pk_mul_f32 v[228:229], v[126:127], v[224:225] op_sel_hi:[1,0]
	v_pk_fma_f32 v[184:185], v[184:185], v[226:227], v[120:121]
	v_pk_fma_f32 v[186:187], v[186:187], v[228:229], v[122:123]
	v_pk_mul_f32 v[184:185], v[184:185], s[16:17] op_sel_hi:[1,0]
	v_pk_mul_f32 v[186:187], v[186:187], s[16:17] op_sel_hi:[1,0]
	v_pk_fma_f32 v[156:157], v[156:157], 0.5, v[184:185] op_sel_hi:[1,0,1]
	v_pk_fma_f32 v[158:159], v[158:159], 0.5, v[186:187] op_sel_hi:[1,0,1]
	ds_bpermute_b32 v246, v238, v156
	ds_bpermute_b32 v247, v238, v157
	ds_bpermute_b32 v248, v238, v158
	ds_bpermute_b32 v249, v238, v159
	v_lshl_add_u64 v[244:245], v[222:223], 0, v[240:241]
	s_waitcnt lgkmcnt(0)
;     __device__ __forceinline__ void operator()(const f32x4 (&acc)[2][2][4][2], const Unit& u, int wr, int wc, int fr, int fq) const {
;     ...
;                 for (int mm = 0; mm < 2; ++mm) {
;                     const int r = row0 + ai * HALF + (2 * m2 + mm) * 16;
;                     float ps = 0.f, pq = 0.f;
; #pragma unroll
;                     for (int bj = 0; bj < 2; ++bj)
; #pragma unroll
;                         for (int n = 0; n < 2; ++n) {
;                             const f32x4 x = (xv[mm][bj][n] - st[mm][0]) * (gg[bj][n] * st[mm][1]) + bb[bj][n];
;                             const f32x4 o = x * alpha + acc[ai][bj][2 * m2 + mm][n] * scale;
;                             const size_t off = (size_t)r * D + col0 + bj * HALF + n * 16;
;                             *(f32x4*)(Y + off) = o;
	global_store_dwordx4 v[244:245], v[246:249], off
	v_pk_mul_f32 v[184:185], v[118:119], v[224:225] op_sel_hi:[1,0]
	v_div_fixup_f32 v230, v173, v183, 1.0
	v_sub_f32_e32 v157, v191, v216
	v_sub_f32_e32 v156, v190, v216
	v_pk_mul_f32 v[158:159], v[116:117], v[224:225] op_sel_hi:[1,0]
	v_pk_fma_f32 v[156:157], v[156:157], v[184:185], v[114:115]
	v_pk_fma_f32 v[158:159], v[188:189], v[158:159], v[112:113]
	v_pk_mul_f32 v[156:157], v[156:157], s[16:17] op_sel_hi:[1,0]
	v_pk_mul_f32 v[158:159], v[158:159], s[16:17] op_sel_hi:[1,0]
	v_pk_fma_f32 v[154:155], v[154:155], 0.5, v[156:157] op_sel_hi:[1,0,1]
	v_pk_fma_f32 v[152:153], v[152:153], 0.5, v[158:159] op_sel_hi:[1,0,1]
	ds_bpermute_b32 v250, v238, v152
	ds_bpermute_b32 v251, v238, v153
	ds_bpermute_b32 v252, v238, v154
	ds_bpermute_b32 v253, v238, v155
	v_lshl_add_u64 v[244:245], v[222:223], 0, v[240:241]
	s_waitcnt lgkmcnt(0)
	global_store_dwordx4 v[244:245], v[250:253], off offset:64
	v_pk_mul_f32 v[156:157], v[108:109], v[224:225] op_sel_hi:[1,0]
	v_pk_mul_f32 v[158:159], v[110:111], v[224:225] op_sel_hi:[1,0]
	v_sub_f32_e32 v153, v197, v216
	v_sub_f32_e32 v152, v196, v216
	v_sub_f32_e32 v155, v199, v216
	v_sub_f32_e32 v154, v198, v216
	v_pk_fma_f32 v[154:155], v[154:155], v[158:159], v[106:107]
	v_pk_fma_f32 v[152:153], v[152:153], v[156:157], v[104:105]
	v_pk_mul_f32 v[154:155], v[154:155], s[16:17] op_sel_hi:[1,0]
	v_pk_mul_f32 v[152:153], v[152:153], s[16:17] op_sel_hi:[1,0]
	v_pk_fma_f32 v[150:151], v[150:151], 0.5, v[154:155] op_sel_hi:[1,0,1]
	v_pk_fma_f32 v[148:149], v[148:149], 0.5, v[152:153] op_sel_hi:[1,0,1]
	ds_bpermute_b32 v246, v238, v148
	ds_bpermute_b32 v247, v238, v149
	ds_bpermute_b32 v248, v238, v150
	ds_bpermute_b32 v249, v238, v151
	v_lshl_add_u64 v[244:245], v[222:223], 0, v[240:241]
	s_waitcnt lgkmcnt(0)
	global_store_dwordx4 v[244:245], v[246:249], off offset:512
	v_pk_mul_f32 v[152:153], v[100:101], v[224:225] op_sel_hi:[1,0]
	v_pk_mul_f32 v[154:155], v[102:103], v[224:225] op_sel_hi:[1,0]
	v_sub_f32_e32 v149, v193, v216
	v_sub_f32_e32 v148, v192, v216
	v_sub_f32_e32 v151, v195, v216
	v_sub_f32_e32 v150, v194, v216
	v_pk_fma_f32 v[150:151], v[150:151], v[154:155], v[98:99]
	v_pk_fma_f32 v[148:149], v[148:149], v[152:153], v[96:97]
	v_pk_mul_f32 v[150:151], v[150:151], s[16:17] op_sel_hi:[1,0]
	v_pk_mul_f32 v[148:149], v[148:149], s[16:17] op_sel_hi:[1,0]
	v_pk_fma_f32 v[142:143], v[142:143], 0.5, v[150:151] op_sel_hi:[1,0,1]
	v_pk_fma_f32 v[140:141], v[140:141], 0.5, v[148:149] op_sel_hi:[1,0,1]
	ds_bpermute_b32 v250, v238, v140
	ds_bpermute_b32 v251, v238, v141
	ds_bpermute_b32 v252, v238, v142
	ds_bpermute_b32 v253, v238, v143
	v_lshl_add_u64 v[244:245], v[222:223], 0, v[240:241]
	s_waitcnt lgkmcnt(0)
	global_store_dwordx4 v[244:245], v[250:253], off offset:576
	v_pk_mul_f32 v[148:149], v[124:125], v[230:231] op_sel_hi:[1,0]
	v_pk_mul_f32 v[150:151], v[126:127], v[230:231] op_sel_hi:[1,0]
	v_sub_f32_e32 v141, v201, v218
	v_sub_f32_e32 v140, v200, v218
	v_sub_f32_e32 v143, v203, v218
	v_sub_f32_e32 v142, v202, v218
	v_pk_fma_f32 v[140:141], v[140:141], v[148:149], v[120:121]
	v_pk_fma_f32 v[142:143], v[142:143], v[150:151], v[122:123]
	v_pk_mul_f32 v[140:141], v[140:141], s[16:17] op_sel_hi:[1,0]
	v_pk_mul_f32 v[142:143], v[142:143], s[16:17] op_sel_hi:[1,0]
	v_pk_fma_f32 v[140:141], v[144:145], 0.5, v[140:141] op_sel_hi:[1,0,1]
	v_lshl_add_u64 v[144:145], s[38:39], 0, v[220:221]
	v_pk_fma_f32 v[142:143], v[146:147], 0.5, v[142:143] op_sel_hi:[1,0,1]
	v_lshl_add_u64 v[144:145], v[144:145], 0, v[168:169]
	ds_bpermute_b32 v246, v238, v140
	ds_bpermute_b32 v247, v238, v141
	ds_bpermute_b32 v248, v238, v142
	ds_bpermute_b32 v249, v238, v143
	v_lshl_add_u64 v[244:245], v[144:145], 0, v[240:241]
	s_waitcnt lgkmcnt(0)
	global_store_dwordx4 v[244:245], v[246:249], off
	v_pk_mul_f32 v[146:147], v[116:117], v[230:231] op_sel_hi:[1,0]
	v_pk_mul_f32 v[148:149], v[118:119], v[230:231] op_sel_hi:[1,0]
	v_sub_f32_e32 v141, v205, v218
	v_sub_f32_e32 v140, v204, v218
	v_sub_f32_e32 v143, v207, v218
	v_sub_f32_e32 v142, v206, v218
	v_pk_fma_f32 v[142:143], v[142:143], v[148:149], v[114:115]
	v_pk_fma_f32 v[140:141], v[140:141], v[146:147], v[112:113]
	v_pk_mul_f32 v[142:143], v[142:143], s[16:17] op_sel_hi:[1,0]
	v_pk_mul_f32 v[140:141], v[140:141], s[16:17] op_sel_hi:[1,0]
	v_pk_fma_f32 v[138:139], v[138:139], 0.5, v[142:143] op_sel_hi:[1,0,1]
	v_pk_fma_f32 v[136:137], v[136:137], 0.5, v[140:141] op_sel_hi:[1,0,1]
	ds_bpermute_b32 v250, v238, v136
	ds_bpermute_b32 v251, v238, v137
	ds_bpermute_b32 v252, v238, v138
	ds_bpermute_b32 v253, v238, v139
	v_lshl_add_u64 v[244:245], v[144:145], 0, v[240:241]
	s_waitcnt lgkmcnt(0)
	global_store_dwordx4 v[244:245], v[250:253], off offset:64
	v_pk_mul_f32 v[140:141], v[108:109], v[230:231] op_sel_hi:[1,0]
	v_pk_mul_f32 v[142:143], v[110:111], v[230:231] op_sel_hi:[1,0]
	v_sub_f32_e32 v137, v209, v218
	v_sub_f32_e32 v136, v208, v218
	v_sub_f32_e32 v139, v211, v218
	v_sub_f32_e32 v138, v210, v218
	v_pk_fma_f32 v[138:139], v[138:139], v[142:143], v[106:107]
	v_pk_fma_f32 v[136:137], v[136:137], v[140:141], v[104:105]
	v_pk_mul_f32 v[138:139], v[138:139], s[16:17] op_sel_hi:[1,0]
	v_pk_mul_f32 v[136:137], v[136:137], s[16:17] op_sel_hi:[1,0]
	v_pk_fma_f32 v[134:135], v[134:135], 0.5, v[138:139] op_sel_hi:[1,0,1]
	v_pk_fma_f32 v[132:133], v[132:133], 0.5, v[136:137] op_sel_hi:[1,0,1]
	ds_bpermute_b32 v246, v238, v132
	ds_bpermute_b32 v247, v238, v133
	ds_bpermute_b32 v248, v238, v134
	ds_bpermute_b32 v249, v238, v135
	v_lshl_add_u64 v[244:245], v[144:145], 0, v[240:241]
	s_waitcnt lgkmcnt(0)
; __device__ __forceinline__ f32x2 ln_stats(f32x2 sm) { const float mu = sm[0] * (1.f / D); const float var = fmaxf(sm[1] * (1.f / D) - mu * mu, 0.f); return (f32x2){mu, 1.0f / sqrtf(var + LN_EPS)}; }
;     __device__ __forceinline__ void operator()(const f32x4 (&acc)[2][2][4][2], const Unit& u, int wr, int wc, int fr, int fq) const {
;     ...
;                 f32x4 xv[2][2][2]; f32x2 st[2];
; #pragma unroll
;                 for (int mm = 0; mm < 2; ++mm) {
;                     const int r = row0 + ai * HALF + (2 * m2 + mm) * 16;
;                     st[mm] = (f32x2){0.f, 1.f};
;                     if (rin) st[mm] = ln_stats(*(const f32x2*)(rin + 2 * (size_t)r));
; #pragma unroll
;                     for (int bj = 0; bj < 2; ++bj)
; #pragma unroll
;                         for (int n = 0; n < 2; ++n) { const f32x4* rp = (const f32x4*)(res + (size_t)r * D + col0 + bj * HALF + n * 16); xv[mm][bj][n] = stream ? __builtin_nontemporal_load(rp) : *rp; }
;                 }
; #pragma unroll
;                 for (int mm = 0; mm < 2; ++mm) {
;                     const int r = row0 + ai * HALF + (2 * m2 + mm) * 16;
;                     float ps = 0.f, pq = 0.f;
; #pragma unroll
;                     for (int bj = 0; bj < 2; ++bj)
; #pragma unroll
;                         for (int n = 0; n < 2; ++n) {
;                             const f32x4 x = (xv[mm][bj][n] - st[mm][0]) * (gg[bj][n] * st[mm][1]) + bb[bj][n];
;                             const f32x4 o = x * alpha + acc[ai][bj][2 * m2 + mm][n] * scale;
;                             const size_t off = (size_t)r * D + col0 + bj * HALF + n * 16;
;                             *(f32x4*)(Y + off) = o;
	global_store_dwordx4 v[244:245], v[246:249], off offset:512
	v_pk_mul_f32 v[136:137], v[100:101], v[230:231] op_sel_hi:[1,0]
	v_pk_mul_f32 v[138:139], v[102:103], v[230:231] op_sel_hi:[1,0]
	v_sub_f32_e32 v133, v213, v218
	v_sub_f32_e32 v132, v212, v218
	v_sub_f32_e32 v135, v215, v218
	v_sub_f32_e32 v134, v214, v218
	v_pk_fma_f32 v[134:135], v[134:135], v[138:139], v[98:99]
	v_pk_fma_f32 v[132:133], v[132:133], v[136:137], v[96:97]
	v_pk_mul_f32 v[134:135], v[134:135], s[16:17] op_sel_hi:[1,0]
	v_pk_mul_f32 v[132:133], v[132:133], s[16:17] op_sel_hi:[1,0]
	v_pk_fma_f32 v[130:131], v[130:131], 0.5, v[134:135] op_sel_hi:[1,0,1]
	v_pk_fma_f32 v[128:129], v[128:129], 0.5, v[132:133] op_sel_hi:[1,0,1]
	ds_bpermute_b32 v250, v238, v128
	ds_bpermute_b32 v251, v238, v129
	ds_bpermute_b32 v252, v238, v130
	ds_bpermute_b32 v253, v238, v131
	v_lshl_add_u64 v[244:245], v[144:145], 0, v[240:241]
	s_waitcnt lgkmcnt(0)
	global_store_dwordx4 v[244:245], v[250:253], off offset:576
	v_or_b32_e32 v144, 48, v172
	v_ashrrev_i32_e32 v145, 31, v144
	v_or_b32_e32 v128, 32, v172
	v_ashrrev_i32_e32 v129, 31, v128
	v_lshl_add_u64 v[130:131], v[128:129], 3, s[8:9]
	global_load_dwordx2 v[132:133], v[130:131], off
	v_lshl_add_u64 v[130:131], v[144:145], 3, s[8:9]
	global_load_dwordx2 v[146:147], v[130:131], off
	v_lshlrev_b64 v[184:185], 13, v[128:129]
	v_lshl_add_u64 v[140:141], v[170:171], 0, v[184:185]
	v_lshlrev_b64 v[190:191], 13, v[144:145]
	v_lshl_add_u64 v[156:157], v[170:171], 0, v[190:191]
	s_waitcnt vmcnt(1)
	v_pk_mul_f32 v[186:187], v[132:133], s[14:15] op_sel_hi:[1,0]
	s_nop 0
	v_fma_f32 v132, -v186, v186, v187
	v_max_f32_e32 v132, 0, v132
	v_add_f32_e32 v132, 0x3727c5ac, v132
	v_mul_f32_e32 v133, 0x4f800000, v132
	v_cmp_gt_f32_e32 vcc, s44, v132
	s_nop 1
	v_cndmask_b32_e32 v136, v132, v133, vcc
	v_sqrt_f32_e32 v137, v136
	s_nop 0
	v_add_u32_e32 v132, -1, v137
	v_fma_f32 v133, -v132, v137, v136
	v_cmp_ge_f32_e64 s[0:1], 0, v133
	v_add_u32_e32 v139, 1, v137
	s_nop 0
	v_cndmask_b32_e64 v138, v137, v132, s[0:1]
	v_fma_f32 v137, -v139, v137, v136
	v_cmp_lt_f32_e64 s[0:1], 0, v137
	global_load_dwordx4 v[132:135], v[140:141], off offset:64
	s_waitcnt vmcnt(1)
	v_pk_mul_f32 v[188:189], v[146:147], s[14:15] op_sel_hi:[1,0]
	v_cndmask_b32_e64 v137, v138, v139, s[0:1]
	v_mul_f32_e32 v138, 0x37800000, v137
	v_cndmask_b32_e32 v137, v137, v138, vcc
	v_cmp_class_f32_e32 vcc, v136, v182
	v_fma_f32 v146, -v188, v188, v189
	v_max_f32_e32 v146, 0, v146
	v_cndmask_b32_e32 v148, v137, v136, vcc
	v_div_scale_f32 v149, s[0:1], v148, v148, 1.0
	v_rcp_f32_e32 v150, v149
	global_load_dwordx4 v[128:131], v[140:141], off
	v_add_f32_e32 v146, 0x3727c5ac, v146
	v_mul_f32_e32 v147, 0x4f800000, v146
	v_cmp_gt_f32_e64 s[0:1], s44, v146
	v_fma_f32 v151, -v149, v150, 1.0
	v_fmac_f32_e32 v150, v151, v150
	v_cndmask_b32_e64 v153, v146, v147, s[0:1]
	v_sqrt_f32_e32 v146, v153
	v_div_scale_f32 v151, vcc, 1.0, v148, 1.0
	v_mul_f32_e32 v152, v151, v150
	v_fma_f32 v147, -v149, v152, v151
	v_fmac_f32_e32 v152, v147, v150
	v_add_u32_e32 v147, -1, v146
	v_fma_f32 v149, -v149, v152, v151
	v_fma_f32 v151, -v147, v146, v153
	v_add_u32_e32 v154, 1, v146
	global_load_dwordx4 v[136:139], v[140:141], off offset:576
	s_nop 0
	global_load_dwordx4 v[140:143], v[140:141], off offset:512
	v_cmp_ge_f32_e64 s[4:5], 0, v151
	v_fma_f32 v155, -v154, v146, v153
	v_div_fmas_f32 v149, v149, v150, v152
	v_cndmask_b32_e64 v151, v146, v147, s[4:5]
	v_cmp_lt_f32_e64 s[4:5], 0, v155
	global_load_dwordx4 v[144:147], v[156:157], off
	v_div_fixup_f32 v192, v149, v148, 1.0
	v_cndmask_b32_e64 v151, v151, v154, s[4:5]
	v_mul_f32_e32 v154, 0x37800000, v151
	v_cndmask_b32_e64 v151, v151, v154, s[0:1]
	v_cmp_class_f32_e64 s[0:1], v153, v182
	v_pk_mul_f32 v[196:197], v[124:125], v[192:193] op_sel_hi:[1,0]
	v_pk_mul_f32 v[198:199], v[126:127], v[192:193] op_sel_hi:[1,0]
	v_cndmask_b32_e64 v153, v151, v153, s[0:1]
	v_div_scale_f32 v154, s[0:1], v153, v153, 1.0
	v_rcp_f32_e32 v155, v154
	v_div_scale_f32 v152, vcc, 1.0, v153, 1.0
	v_fma_f32 v148, -v154, v155, 1.0
	v_fmac_f32_e32 v155, v148, v155
	global_load_dwordx4 v[148:151], v[156:157], off offset:64
	v_mul_f32_e32 v158, v152, v155
	v_fma_f32 v159, -v154, v158, v152
	v_fmac_f32_e32 v158, v159, v155
	v_fma_f32 v152, -v154, v158, v152
	v_div_fmas_f32 v152, v152, v155, v158
	v_div_fixup_f32 v194, v152, v153, 1.0
	global_load_dwordx4 v[152:155], v[156:157], off offset:512
	s_nop 0
	global_load_dwordx4 v[156:159], v[156:157], off offset:576
	s_waitcnt vmcnt(6)
	v_sub_f32_e32 v129, v129, v186
	v_sub_f32_e32 v128, v128, v186
	v_sub_f32_e32 v131, v131, v186
	v_sub_f32_e32 v130, v130, v186
	v_pk_fma_f32 v[128:129], v[128:129], v[196:197], v[120:121]
	v_pk_fma_f32 v[130:131], v[130:131], v[198:199], v[122:123]
	v_pk_mul_f32 v[128:129], v[128:129], s[16:17] op_sel_hi:[1,0]
	v_pk_mul_f32 v[130:131], v[130:131], s[16:17] op_sel_hi:[1,0]
	v_pk_fma_f32 v[92:93], v[92:93], 0.5, v[128:129] op_sel_hi:[1,0,1]
	v_lshl_add_u64 v[128:129], s[38:39], 0, v[184:185]
	v_pk_fma_f32 v[94:95], v[94:95], 0.5, v[130:131] op_sel_hi:[1,0,1]
	v_lshl_add_u64 v[128:129], v[128:129], 0, v[168:169]
	ds_bpermute_b32 v246, v238, v92
	ds_bpermute_b32 v247, v238, v93
	ds_bpermute_b32 v248, v238, v94
	ds_bpermute_b32 v249, v238, v95
	v_lshl_add_u64 v[244:245], v[128:129], 0, v[240:241]
	s_waitcnt lgkmcnt(0)
; __device__ __forceinline__ unsigned cvt_pk_bf16(float lo, float hi) { unsigned r; asm volatile("v_cvt_pk_bf16_f32 %0, %1, %2" : "=v"(r) : "v"(lo), "v"(hi)); return r; }
; __device__ __forceinline__ f32x2 ln_stats(f32x2 sm) { const float mu = sm[0] * (1.f / D); const float var = fmaxf(sm[1] * (1.f / D) - mu * mu, 0.f); return (f32x2){mu, 1.0f / sqrtf(var + LN_EPS)}; }
;     __device__ __forceinline__ void operator()(const f32x4 (&acc)[2][2][4][2], const Unit& u, int wr, int wc, int fr, int fq) const {
;     ...
;                 f32x4 xv[2][2][2]; f32x2 st[2];
; #pragma unroll
;                 for (int mm = 0; mm < 2; ++mm) {
;                     const int r = row0 + ai * HALF + (2 * m2 + mm) * 16;
;                     st[mm] = (f32x2){0.f, 1.f};
;                     if (rin) st[mm] = ln_stats(*(const f32x2*)(rin + 2 * (size_t)r));
; #pragma unroll
;                     for (int bj = 0; bj < 2; ++bj)
; #pragma unroll
;                         for (int n = 0; n < 2; ++n) { const f32x4* rp = (const f32x4*)(res + (size_t)r * D + col0 + bj * HALF + n * 16); xv[mm][bj][n] = stream ? __builtin_nontemporal_load(rp) : *rp; }
;                 }
; #pragma unroll
;                 for (int mm = 0; mm < 2; ++mm) {
;                     const int r = row0 + ai * HALF + (2 * m2 + mm) * 16;
;                     float ps = 0.f, pq = 0.f;
; #pragma unroll
;                     for (int bj = 0; bj < 2; ++bj)
; #pragma unroll
;                         for (int n = 0; n < 2; ++n) {
;                             const f32x4 x = (xv[mm][bj][n] - st[mm][0]) * (gg[bj][n] * st[mm][1]) + bb[bj][n];
;                             const f32x4 o = x * alpha + acc[ai][bj][2 * m2 + mm][n] * scale;
;                             const size_t off = (size_t)r * D + col0 + bj * HALF + n * 16;
;                             *(f32x4*)(Y + off) = o;
;                             if (yb) { u32x2 w; w.x = cvt_pk_bf16(o[0], o[1]); w.y = cvt_pk_bf16(o[2], o[3]); *(u32x2*)(yb + off) = w; }
;                             ps += (o[0] + o[1]) + (o[2] + o[3]); pq += (o[0] * o[0] + o[1] * o[1]) + (o[2] * o[2] + o[3] * o[3]);
;                         }
	global_store_dwordx4 v[244:245], v[246:249], off
	v_pk_mul_f32 v[130:131], v[116:117], v[192:193] op_sel_hi:[1,0]
	s_nop 0
	v_sub_f32_e32 v93, v133, v186
	v_sub_f32_e32 v92, v132, v186
	v_sub_f32_e32 v95, v135, v186
	v_sub_f32_e32 v94, v134, v186
	v_pk_mul_f32 v[132:133], v[118:119], v[192:193] op_sel_hi:[1,0]
	v_pk_fma_f32 v[92:93], v[92:93], v[130:131], v[112:113]
	v_pk_fma_f32 v[94:95], v[94:95], v[132:133], v[114:115]
	v_pk_mul_f32 v[92:93], v[92:93], s[16:17] op_sel_hi:[1,0]
	v_pk_mul_f32 v[94:95], v[94:95], s[16:17] op_sel_hi:[1,0]
	v_pk_fma_f32 v[88:89], v[88:89], 0.5, v[92:93] op_sel_hi:[1,0,1]
	v_pk_fma_f32 v[90:91], v[90:91], 0.5, v[94:95] op_sel_hi:[1,0,1]
	ds_bpermute_b32 v250, v238, v88
	ds_bpermute_b32 v251, v238, v89
	ds_bpermute_b32 v252, v238, v90
	ds_bpermute_b32 v253, v238, v91
	v_lshl_add_u64 v[244:245], v[128:129], 0, v[240:241]
	s_waitcnt lgkmcnt(0)
	global_store_dwordx4 v[244:245], v[250:253], off offset:64
	v_pk_mul_f32 v[92:93], v[108:109], v[192:193] op_sel_hi:[1,0]
	v_pk_mul_f32 v[94:95], v[110:111], v[192:193] op_sel_hi:[1,0]
	s_waitcnt vmcnt(6)
	v_sub_f32_e32 v89, v141, v186
	v_sub_f32_e32 v88, v140, v186
	v_sub_f32_e32 v91, v143, v186
	v_sub_f32_e32 v90, v142, v186
	v_pk_fma_f32 v[90:91], v[90:91], v[94:95], v[106:107]
	v_pk_fma_f32 v[88:89], v[88:89], v[92:93], v[104:105]
	v_pk_mul_f32 v[90:91], v[90:91], s[16:17] op_sel_hi:[1,0]
	v_pk_mul_f32 v[88:89], v[88:89], s[16:17] op_sel_hi:[1,0]
	v_pk_fma_f32 v[86:87], v[86:87], 0.5, v[90:91] op_sel_hi:[1,0,1]
	v_pk_fma_f32 v[84:85], v[84:85], 0.5, v[88:89] op_sel_hi:[1,0,1]
	ds_bpermute_b32 v246, v238, v84
	ds_bpermute_b32 v247, v238, v85
	ds_bpermute_b32 v248, v238, v86
	ds_bpermute_b32 v249, v238, v87
	v_lshl_add_u64 v[244:245], v[128:129], 0, v[240:241]
	s_waitcnt lgkmcnt(0)
	global_store_dwordx4 v[244:245], v[246:249], off offset:512
	v_pk_mul_f32 v[88:89], v[100:101], v[192:193] op_sel_hi:[1,0]
	v_pk_mul_f32 v[90:91], v[102:103], v[192:193] op_sel_hi:[1,0]
	v_sub_f32_e32 v85, v137, v186
	v_sub_f32_e32 v84, v136, v186
	v_sub_f32_e32 v87, v139, v186
	v_sub_f32_e32 v86, v138, v186
	v_pk_fma_f32 v[86:87], v[86:87], v[90:91], v[98:99]
	v_pk_fma_f32 v[84:85], v[84:85], v[88:89], v[96:97]
	v_pk_mul_f32 v[86:87], v[86:87], s[16:17] op_sel_hi:[1,0]
	v_pk_mul_f32 v[84:85], v[84:85], s[16:17] op_sel_hi:[1,0]
	v_pk_fma_f32 v[78:79], v[78:79], 0.5, v[86:87] op_sel_hi:[1,0,1]
	v_pk_fma_f32 v[76:77], v[76:77], 0.5, v[84:85] op_sel_hi:[1,0,1]
	ds_bpermute_b32 v250, v238, v76
	ds_bpermute_b32 v251, v238, v77
	ds_bpermute_b32 v252, v238, v78
	ds_bpermute_b32 v253, v238, v79
	v_lshl_add_u64 v[244:245], v[128:129], 0, v[240:241]
	s_waitcnt lgkmcnt(0)
	global_store_dwordx4 v[244:245], v[250:253], off offset:576
	v_pk_mul_f32 v[84:85], v[124:125], v[194:195] op_sel_hi:[1,0]
	v_pk_mul_f32 v[86:87], v[126:127], v[194:195] op_sel_hi:[1,0]
	s_waitcnt vmcnt(7)
	v_sub_f32_e32 v77, v145, v188
	v_sub_f32_e32 v76, v144, v188
	v_sub_f32_e32 v79, v147, v188
	v_sub_f32_e32 v78, v146, v188
	v_pk_fma_f32 v[76:77], v[76:77], v[84:85], v[120:121]
	v_pk_fma_f32 v[78:79], v[78:79], v[86:87], v[122:123]
	v_pk_mul_f32 v[76:77], v[76:77], s[16:17] op_sel_hi:[1,0]
	v_pk_mul_f32 v[78:79], v[78:79], s[16:17] op_sel_hi:[1,0]
	v_pk_fma_f32 v[76:77], v[80:81], 0.5, v[76:77] op_sel_hi:[1,0,1]
	v_lshl_add_u64 v[80:81], s[38:39], 0, v[190:191]
	v_pk_fma_f32 v[78:79], v[82:83], 0.5, v[78:79] op_sel_hi:[1,0,1]
	v_lshl_add_u64 v[80:81], v[80:81], 0, v[168:169]
	ds_bpermute_b32 v246, v238, v76
	ds_bpermute_b32 v247, v238, v77
	ds_bpermute_b32 v248, v238, v78
	ds_bpermute_b32 v249, v238, v79
	v_lshl_add_u64 v[244:245], v[80:81], 0, v[240:241]
	s_waitcnt lgkmcnt(0)
	global_store_dwordx4 v[244:245], v[246:249], off
	v_pk_mul_f32 v[82:83], v[116:117], v[194:195] op_sel_hi:[1,0]
	v_pk_mul_f32 v[84:85], v[118:119], v[194:195] op_sel_hi:[1,0]
	s_waitcnt vmcnt(7)
	v_sub_f32_e32 v77, v149, v188
	v_sub_f32_e32 v76, v148, v188
	v_sub_f32_e32 v79, v151, v188
	v_sub_f32_e32 v78, v150, v188
	v_pk_fma_f32 v[78:79], v[78:79], v[84:85], v[114:115]
	v_pk_fma_f32 v[76:77], v[76:77], v[82:83], v[112:113]
	v_pk_mul_f32 v[78:79], v[78:79], s[16:17] op_sel_hi:[1,0]
	v_pk_mul_f32 v[76:77], v[76:77], s[16:17] op_sel_hi:[1,0]
	v_pk_fma_f32 v[74:75], v[74:75], 0.5, v[78:79] op_sel_hi:[1,0,1]
	v_pk_fma_f32 v[72:73], v[72:73], 0.5, v[76:77] op_sel_hi:[1,0,1]
	ds_bpermute_b32 v250, v238, v72
	ds_bpermute_b32 v251, v238, v73
	ds_bpermute_b32 v252, v238, v74
	ds_bpermute_b32 v253, v238, v75
	v_lshl_add_u64 v[244:245], v[80:81], 0, v[240:241]
	s_waitcnt lgkmcnt(0)
	global_store_dwordx4 v[244:245], v[250:253], off offset:64
	v_pk_mul_f32 v[76:77], v[108:109], v[194:195] op_sel_hi:[1,0]
	v_pk_mul_f32 v[78:79], v[110:111], v[194:195] op_sel_hi:[1,0]
	s_waitcnt vmcnt(7)
	v_sub_f32_e32 v73, v153, v188
	v_sub_f32_e32 v72, v152, v188
	v_sub_f32_e32 v75, v155, v188
	v_sub_f32_e32 v74, v154, v188
	v_pk_fma_f32 v[74:75], v[74:75], v[78:79], v[106:107]
	v_pk_fma_f32 v[72:73], v[72:73], v[76:77], v[104:105]
	v_pk_mul_f32 v[74:75], v[74:75], s[16:17] op_sel_hi:[1,0]
	v_pk_mul_f32 v[72:73], v[72:73], s[16:17] op_sel_hi:[1,0]
	v_pk_fma_f32 v[70:71], v[70:71], 0.5, v[74:75] op_sel_hi:[1,0,1]
	v_pk_fma_f32 v[68:69], v[68:69], 0.5, v[72:73] op_sel_hi:[1,0,1]
	ds_bpermute_b32 v246, v238, v68
	ds_bpermute_b32 v247, v238, v69
	ds_bpermute_b32 v248, v238, v70
	ds_bpermute_b32 v249, v238, v71
	v_lshl_add_u64 v[244:245], v[80:81], 0, v[240:241]
	s_waitcnt lgkmcnt(0)
	global_store_dwordx4 v[244:245], v[246:249], off offset:512
	v_pk_mul_f32 v[72:73], v[100:101], v[194:195] op_sel_hi:[1,0]
	v_pk_mul_f32 v[74:75], v[102:103], v[194:195] op_sel_hi:[1,0]
	s_waitcnt vmcnt(7)
; __device__ __forceinline__ unsigned cvt_pk_bf16(float lo, float hi) { unsigned r; asm volatile("v_cvt_pk_bf16_f32 %0, %1, %2" : "=v"(r) : "v"(lo), "v"(hi)); return r; }
; __device__ __forceinline__ f32x2 ln_stats(f32x2 sm) { const float mu = sm[0] * (1.f / D); const float var = fmaxf(sm[1] * (1.f / D) - mu * mu, 0.f); return (f32x2){mu, 1.0f / sqrtf(var + LN_EPS)}; }
;     __device__ __forceinline__ void operator()(const f32x4 (&acc)[2][2][4][2], const Unit& u, int wr, int wc, int fr, int fq) const {
;     ...
;                 f32x4 xv[2][2][2]; f32x2 st[2];
; #pragma unroll
;                 for (int mm = 0; mm < 2; ++mm) {
;                     const int r = row0 + ai * HALF + (2 * m2 + mm) * 16;
;                     st[mm] = (f32x2){0.f, 1.f};
;                     if (rin) st[mm] = ln_stats(*(const f32x2*)(rin + 2 * (size_t)r));
; #pragma unroll
;                     for (int bj = 0; bj < 2; ++bj)
; #pragma unroll
;                         for (int n = 0; n < 2; ++n) { const f32x4* rp = (const f32x4*)(res + (size_t)r * D + col0 + bj * HALF + n * 16); xv[mm][bj][n] = stream ? __builtin_nontemporal_load(rp) : *rp; }
;                 }
; #pragma unroll
;                 for (int mm = 0; mm < 2; ++mm) {
;                     const int r = row0 + ai * HALF + (2 * m2 + mm) * 16;
;                     float ps = 0.f, pq = 0.f;
; #pragma unroll
;                     for (int bj = 0; bj < 2; ++bj)
; #pragma unroll
;                         for (int n = 0; n < 2; ++n) {
;                             const f32x4 x = (xv[mm][bj][n] - st[mm][0]) * (gg[bj][n] * st[mm][1]) + bb[bj][n];
;                             const f32x4 o = x * alpha + acc[ai][bj][2 * m2 + mm][n] * scale;
;                             const size_t off = (size_t)r * D + col0 + bj * HALF + n * 16;
;                             *(f32x4*)(Y + off) = o;
;                             if (yb) { u32x2 w; w.x = cvt_pk_bf16(o[0], o[1]); w.y = cvt_pk_bf16(o[2], o[3]); *(u32x2*)(yb + off) = w; }
;                             ps += (o[0] + o[1]) + (o[2] + o[3]); pq += (o[0] * o[0] + o[1] * o[1]) + (o[2] * o[2] + o[3] * o[3]);
;                         }
	v_sub_f32_e32 v69, v157, v188
	v_sub_f32_e32 v68, v156, v188
	v_sub_f32_e32 v71, v159, v188
	v_sub_f32_e32 v70, v158, v188
	v_pk_fma_f32 v[70:71], v[70:71], v[74:75], v[98:99]
	v_pk_fma_f32 v[68:69], v[68:69], v[72:73], v[96:97]
	v_pk_mul_f32 v[70:71], v[70:71], s[16:17] op_sel_hi:[1,0]
	v_pk_mul_f32 v[68:69], v[68:69], s[16:17] op_sel_hi:[1,0]
	v_pk_fma_f32 v[66:67], v[66:67], 0.5, v[70:71] op_sel_hi:[1,0,1]
	v_pk_fma_f32 v[64:65], v[64:65], 0.5, v[68:69] op_sel_hi:[1,0,1]
	ds_bpermute_b32 v250, v238, v64
	ds_bpermute_b32 v251, v238, v65
	ds_bpermute_b32 v252, v238, v66
	ds_bpermute_b32 v253, v238, v67
	v_lshl_add_u64 v[244:245], v[80:81], 0, v[240:241]
	s_waitcnt lgkmcnt(0)
	global_store_dwordx4 v[244:245], v[250:253], off offset:576
	v_add_u32_e32 v80, 0x90, v172
	v_ashrrev_i32_e32 v81, 31, v80
	v_add_u32_e32 v64, 0x80, v172
	v_ashrrev_i32_e32 v65, 31, v64
	v_lshl_add_u64 v[66:67], v[64:65], 3, s[8:9]
	global_load_dwordx2 v[68:69], v[66:67], off
	v_lshl_add_u64 v[66:67], v[80:81], 3, s[8:9]
	global_load_dwordx2 v[82:83], v[66:67], off
	v_lshlrev_b64 v[128:129], 13, v[64:65]
	v_lshl_add_u64 v[76:77], v[170:171], 0, v[128:129]
	v_lshlrev_b64 v[134:135], 13, v[80:81]
	v_lshl_add_u64 v[92:93], v[170:171], 0, v[134:135]
	s_waitcnt vmcnt(1)
	v_pk_mul_f32 v[130:131], v[68:69], s[14:15] op_sel_hi:[1,0]
	s_nop 0
	v_fma_f32 v68, -v130, v130, v131
	v_max_f32_e32 v68, 0, v68
	v_add_f32_e32 v68, 0x3727c5ac, v68
	v_mul_f32_e32 v69, 0x4f800000, v68
	v_cmp_gt_f32_e32 vcc, s44, v68
	s_nop 1
	v_cndmask_b32_e32 v72, v68, v69, vcc
	v_sqrt_f32_e32 v73, v72
	s_nop 0
	v_add_u32_e32 v68, -1, v73
	v_fma_f32 v69, -v68, v73, v72
	v_cmp_ge_f32_e64 s[0:1], 0, v69
	v_add_u32_e32 v75, 1, v73
	s_nop 0
	v_cndmask_b32_e64 v74, v73, v68, s[0:1]
	v_fma_f32 v73, -v75, v73, v72
	v_cmp_lt_f32_e64 s[0:1], 0, v73
	global_load_dwordx4 v[68:71], v[76:77], off offset:64
	s_waitcnt vmcnt(1)
	v_pk_mul_f32 v[132:133], v[82:83], s[14:15] op_sel_hi:[1,0]
	v_cndmask_b32_e64 v73, v74, v75, s[0:1]
	v_mul_f32_e32 v74, 0x37800000, v73
	v_cndmask_b32_e32 v73, v73, v74, vcc
	v_cmp_class_f32_e32 vcc, v72, v182
	v_fma_f32 v82, -v132, v132, v133
	v_max_f32_e32 v82, 0, v82
	v_cndmask_b32_e32 v84, v73, v72, vcc
	v_div_scale_f32 v85, s[0:1], v84, v84, 1.0
	v_rcp_f32_e32 v86, v85
	global_load_dwordx4 v[64:67], v[76:77], off
	v_add_f32_e32 v82, 0x3727c5ac, v82
	v_mul_f32_e32 v83, 0x4f800000, v82
	v_cmp_gt_f32_e64 s[0:1], s44, v82
	v_fma_f32 v87, -v85, v86, 1.0
	v_fmac_f32_e32 v86, v87, v86
	v_cndmask_b32_e64 v89, v82, v83, s[0:1]
	v_sqrt_f32_e32 v82, v89
	v_div_scale_f32 v87, vcc, 1.0, v84, 1.0
	v_mul_f32_e32 v88, v87, v86
	v_fma_f32 v83, -v85, v88, v87
	v_fmac_f32_e32 v88, v83, v86
	v_add_u32_e32 v83, -1, v82
	v_fma_f32 v85, -v85, v88, v87
	v_fma_f32 v87, -v83, v82, v89
	v_add_u32_e32 v90, 1, v82
	global_load_dwordx4 v[72:75], v[76:77], off offset:576
	s_nop 0
	global_load_dwordx4 v[76:79], v[76:77], off offset:512
	v_cmp_ge_f32_e64 s[4:5], 0, v87
	v_fma_f32 v91, -v90, v82, v89
	v_div_fmas_f32 v85, v85, v86, v88
	v_cndmask_b32_e64 v87, v82, v83, s[4:5]
	v_cmp_lt_f32_e64 s[4:5], 0, v91
	global_load_dwordx4 v[80:83], v[92:93], off
	v_div_fixup_f32 v136, v85, v84, 1.0
	v_cndmask_b32_e64 v87, v87, v90, s[4:5]
	v_mul_f32_e32 v90, 0x37800000, v87
	v_cndmask_b32_e64 v87, v87, v90, s[0:1]
	v_cmp_class_f32_e64 s[0:1], v89, v182
	v_pk_mul_f32 v[140:141], v[124:125], v[136:137] op_sel_hi:[1,0]
	v_pk_mul_f32 v[142:143], v[126:127], v[136:137] op_sel_hi:[1,0]
	v_cndmask_b32_e64 v89, v87, v89, s[0:1]
	v_div_scale_f32 v90, s[0:1], v89, v89, 1.0
	v_rcp_f32_e32 v91, v90
	v_div_scale_f32 v88, vcc, 1.0, v89, 1.0
	v_fma_f32 v84, -v90, v91, 1.0
	v_fmac_f32_e32 v91, v84, v91
	global_load_dwordx4 v[84:87], v[92:93], off offset:64
	v_mul_f32_e32 v94, v88, v91
	v_fma_f32 v95, -v90, v94, v88
	v_fmac_f32_e32 v94, v95, v91
	v_fma_f32 v88, -v90, v94, v88
	v_div_fmas_f32 v88, v88, v91, v94
	v_div_fixup_f32 v138, v88, v89, 1.0
	global_load_dwordx4 v[88:91], v[92:93], off offset:512
	s_nop 0
	global_load_dwordx4 v[92:95], v[92:93], off offset:576
	s_waitcnt vmcnt(6)
	v_sub_f32_e32 v65, v65, v130
	v_sub_f32_e32 v64, v64, v130
	v_sub_f32_e32 v67, v67, v130
	v_sub_f32_e32 v66, v66, v130
	v_pk_fma_f32 v[64:65], v[64:65], v[140:141], v[120:121]
	v_pk_fma_f32 v[66:67], v[66:67], v[142:143], v[122:123]
	v_pk_mul_f32 v[64:65], v[64:65], s[16:17] op_sel_hi:[1,0]
	v_pk_mul_f32 v[66:67], v[66:67], s[16:17] op_sel_hi:[1,0]
	v_pk_fma_f32 v[60:61], v[60:61], 0.5, v[64:65] op_sel_hi:[1,0,1]
	v_lshl_add_u64 v[64:65], s[38:39], 0, v[128:129]
	v_pk_fma_f32 v[62:63], v[62:63], 0.5, v[66:67] op_sel_hi:[1,0,1]
	v_lshl_add_u64 v[64:65], v[64:65], 0, v[168:169]
	ds_bpermute_b32 v246, v238, v60
	ds_bpermute_b32 v247, v238, v61
	ds_bpermute_b32 v248, v238, v62
	ds_bpermute_b32 v249, v238, v63
	v_lshl_add_u64 v[244:245], v[64:65], 0, v[240:241]
	s_waitcnt lgkmcnt(0)
	global_store_dwordx4 v[244:245], v[246:249], off
	v_pk_mul_f32 v[66:67], v[116:117], v[136:137] op_sel_hi:[1,0]
	s_nop 0
	v_sub_f32_e32 v61, v69, v130
	v_sub_f32_e32 v60, v68, v130
	v_sub_f32_e32 v63, v71, v130
	v_sub_f32_e32 v62, v70, v130
	v_pk_mul_f32 v[68:69], v[118:119], v[136:137] op_sel_hi:[1,0]
	v_pk_fma_f32 v[60:61], v[60:61], v[66:67], v[112:113]
	v_pk_fma_f32 v[62:63], v[62:63], v[68:69], v[114:115]
	v_pk_mul_f32 v[60:61], v[60:61], s[16:17] op_sel_hi:[1,0]
	v_pk_mul_f32 v[62:63], v[62:63], s[16:17] op_sel_hi:[1,0]
	v_pk_fma_f32 v[56:57], v[56:57], 0.5, v[60:61] op_sel_hi:[1,0,1]
	v_pk_fma_f32 v[58:59], v[58:59], 0.5, v[62:63] op_sel_hi:[1,0,1]
	ds_bpermute_b32 v250, v238, v56
	ds_bpermute_b32 v251, v238, v57
	ds_bpermute_b32 v252, v238, v58
	ds_bpermute_b32 v253, v238, v59
	v_lshl_add_u64 v[244:245], v[64:65], 0, v[240:241]
	s_waitcnt lgkmcnt(0)
; __device__ __forceinline__ unsigned cvt_pk_bf16(float lo, float hi) { unsigned r; asm volatile("v_cvt_pk_bf16_f32 %0, %1, %2" : "=v"(r) : "v"(lo), "v"(hi)); return r; }
;     __device__ __forceinline__ void operator()(const f32x4 (&acc)[2][2][4][2], const Unit& u, int wr, int wc, int fr, int fq) const {
;     ...
;                 for (int mm = 0; mm < 2; ++mm) {
;                     const int r = row0 + ai * HALF + (2 * m2 + mm) * 16;
;                     float ps = 0.f, pq = 0.f;
; #pragma unroll
;                     for (int bj = 0; bj < 2; ++bj)
; #pragma unroll
;                         for (int n = 0; n < 2; ++n) {
;                             const f32x4 x = (xv[mm][bj][n] - st[mm][0]) * (gg[bj][n] * st[mm][1]) + bb[bj][n];
;                             const f32x4 o = x * alpha + acc[ai][bj][2 * m2 + mm][n] * scale;
;                             const size_t off = (size_t)r * D + col0 + bj * HALF + n * 16;
;                             *(f32x4*)(Y + off) = o;
;                             if (yb) { u32x2 w; w.x = cvt_pk_bf16(o[0], o[1]); w.y = cvt_pk_bf16(o[2], o[3]); *(u32x2*)(yb + off) = w; }
;                             ps += (o[0] + o[1]) + (o[2] + o[3]); pq += (o[0] * o[0] + o[1] * o[1]) + (o[2] * o[2] + o[3] * o[3]);
;                         }
	global_store_dwordx4 v[244:245], v[250:253], off offset:64
	v_pk_mul_f32 v[60:61], v[108:109], v[136:137] op_sel_hi:[1,0]
	v_pk_mul_f32 v[62:63], v[110:111], v[136:137] op_sel_hi:[1,0]
	s_waitcnt vmcnt(6)
	v_sub_f32_e32 v57, v77, v130
	v_sub_f32_e32 v56, v76, v130
	v_sub_f32_e32 v59, v79, v130
	v_sub_f32_e32 v58, v78, v130
	v_pk_fma_f32 v[58:59], v[58:59], v[62:63], v[106:107]
	v_pk_fma_f32 v[56:57], v[56:57], v[60:61], v[104:105]
	v_pk_mul_f32 v[58:59], v[58:59], s[16:17] op_sel_hi:[1,0]
	v_pk_mul_f32 v[56:57], v[56:57], s[16:17] op_sel_hi:[1,0]
	v_pk_fma_f32 v[54:55], v[54:55], 0.5, v[58:59] op_sel_hi:[1,0,1]
	v_pk_fma_f32 v[52:53], v[52:53], 0.5, v[56:57] op_sel_hi:[1,0,1]
	ds_bpermute_b32 v246, v238, v52
	ds_bpermute_b32 v247, v238, v53
	ds_bpermute_b32 v248, v238, v54
	ds_bpermute_b32 v249, v238, v55
	v_lshl_add_u64 v[244:245], v[64:65], 0, v[240:241]
	s_waitcnt lgkmcnt(0)
	global_store_dwordx4 v[244:245], v[246:249], off offset:512
	v_pk_mul_f32 v[56:57], v[100:101], v[136:137] op_sel_hi:[1,0]
	v_pk_mul_f32 v[58:59], v[102:103], v[136:137] op_sel_hi:[1,0]
	v_sub_f32_e32 v53, v73, v130
	v_sub_f32_e32 v52, v72, v130
	v_sub_f32_e32 v55, v75, v130
	v_sub_f32_e32 v54, v74, v130
	v_pk_fma_f32 v[54:55], v[54:55], v[58:59], v[98:99]
	v_pk_fma_f32 v[52:53], v[52:53], v[56:57], v[96:97]
	v_pk_mul_f32 v[54:55], v[54:55], s[16:17] op_sel_hi:[1,0]
	v_pk_mul_f32 v[52:53], v[52:53], s[16:17] op_sel_hi:[1,0]
	v_pk_fma_f32 v[46:47], v[46:47], 0.5, v[54:55] op_sel_hi:[1,0,1]
	v_pk_fma_f32 v[44:45], v[44:45], 0.5, v[52:53] op_sel_hi:[1,0,1]
	ds_bpermute_b32 v250, v238, v44
	ds_bpermute_b32 v251, v238, v45
	ds_bpermute_b32 v252, v238, v46
	ds_bpermute_b32 v253, v238, v47
	v_lshl_add_u64 v[244:245], v[64:65], 0, v[240:241]
	s_waitcnt lgkmcnt(0)
	global_store_dwordx4 v[244:245], v[250:253], off offset:576
	v_pk_mul_f32 v[52:53], v[124:125], v[138:139] op_sel_hi:[1,0]
	v_pk_mul_f32 v[54:55], v[126:127], v[138:139] op_sel_hi:[1,0]
	s_waitcnt vmcnt(7)
	v_sub_f32_e32 v45, v81, v132
	v_sub_f32_e32 v44, v80, v132
	v_sub_f32_e32 v47, v83, v132
	v_sub_f32_e32 v46, v82, v132
	v_pk_fma_f32 v[44:45], v[44:45], v[52:53], v[120:121]
	v_pk_fma_f32 v[46:47], v[46:47], v[54:55], v[122:123]
	v_pk_mul_f32 v[44:45], v[44:45], s[16:17] op_sel_hi:[1,0]
	v_pk_mul_f32 v[46:47], v[46:47], s[16:17] op_sel_hi:[1,0]
	v_pk_fma_f32 v[44:45], v[48:49], 0.5, v[44:45] op_sel_hi:[1,0,1]
	v_lshl_add_u64 v[48:49], s[38:39], 0, v[134:135]
	v_pk_fma_f32 v[46:47], v[50:51], 0.5, v[46:47] op_sel_hi:[1,0,1]
	v_lshl_add_u64 v[48:49], v[48:49], 0, v[168:169]
	ds_bpermute_b32 v246, v238, v44
	ds_bpermute_b32 v247, v238, v45
	ds_bpermute_b32 v248, v238, v46
	ds_bpermute_b32 v249, v238, v47
	v_lshl_add_u64 v[244:245], v[48:49], 0, v[240:241]
	s_waitcnt lgkmcnt(0)
	global_store_dwordx4 v[244:245], v[246:249], off
	v_pk_mul_f32 v[50:51], v[116:117], v[138:139] op_sel_hi:[1,0]
	v_pk_mul_f32 v[52:53], v[118:119], v[138:139] op_sel_hi:[1,0]
	s_waitcnt vmcnt(7)
	v_sub_f32_e32 v45, v85, v132
	v_sub_f32_e32 v44, v84, v132
	v_sub_f32_e32 v47, v87, v132
	v_sub_f32_e32 v46, v86, v132
	v_pk_fma_f32 v[46:47], v[46:47], v[52:53], v[114:115]
	v_pk_fma_f32 v[44:45], v[44:45], v[50:51], v[112:113]
	v_pk_mul_f32 v[46:47], v[46:47], s[16:17] op_sel_hi:[1,0]
	v_pk_mul_f32 v[44:45], v[44:45], s[16:17] op_sel_hi:[1,0]
	v_pk_fma_f32 v[42:43], v[42:43], 0.5, v[46:47] op_sel_hi:[1,0,1]
	v_pk_fma_f32 v[40:41], v[40:41], 0.5, v[44:45] op_sel_hi:[1,0,1]
	ds_bpermute_b32 v250, v238, v40
	ds_bpermute_b32 v251, v238, v41
	ds_bpermute_b32 v252, v238, v42
	ds_bpermute_b32 v253, v238, v43
	v_lshl_add_u64 v[244:245], v[48:49], 0, v[240:241]
	s_waitcnt lgkmcnt(0)
	global_store_dwordx4 v[244:245], v[250:253], off offset:64
	v_pk_mul_f32 v[44:45], v[108:109], v[138:139] op_sel_hi:[1,0]
	v_pk_mul_f32 v[46:47], v[110:111], v[138:139] op_sel_hi:[1,0]
	s_waitcnt vmcnt(7)
	v_sub_f32_e32 v41, v89, v132
	v_sub_f32_e32 v40, v88, v132
	v_sub_f32_e32 v43, v91, v132
	v_sub_f32_e32 v42, v90, v132
	v_pk_fma_f32 v[42:43], v[42:43], v[46:47], v[106:107]
	v_pk_fma_f32 v[40:41], v[40:41], v[44:45], v[104:105]
	v_pk_mul_f32 v[42:43], v[42:43], s[16:17] op_sel_hi:[1,0]
	v_pk_mul_f32 v[40:41], v[40:41], s[16:17] op_sel_hi:[1,0]
	v_pk_fma_f32 v[38:39], v[38:39], 0.5, v[42:43] op_sel_hi:[1,0,1]
	v_pk_fma_f32 v[36:37], v[36:37], 0.5, v[40:41] op_sel_hi:[1,0,1]
	ds_bpermute_b32 v246, v238, v36
	ds_bpermute_b32 v247, v238, v37
	ds_bpermute_b32 v248, v238, v38
	ds_bpermute_b32 v249, v238, v39
	v_lshl_add_u64 v[244:245], v[48:49], 0, v[240:241]
	s_waitcnt lgkmcnt(0)
	global_store_dwordx4 v[244:245], v[246:249], off offset:512
	v_pk_mul_f32 v[40:41], v[100:101], v[138:139] op_sel_hi:[1,0]
	v_pk_mul_f32 v[42:43], v[102:103], v[138:139] op_sel_hi:[1,0]
	s_waitcnt vmcnt(7)
	v_sub_f32_e32 v37, v93, v132
	v_sub_f32_e32 v36, v92, v132
	v_sub_f32_e32 v39, v95, v132
	v_sub_f32_e32 v38, v94, v132
	v_pk_fma_f32 v[38:39], v[38:39], v[42:43], v[98:99]
	v_pk_fma_f32 v[36:37], v[36:37], v[40:41], v[96:97]
	v_pk_mul_f32 v[38:39], v[38:39], s[16:17] op_sel_hi:[1,0]
	v_pk_mul_f32 v[36:37], v[36:37], s[16:17] op_sel_hi:[1,0]
	v_pk_fma_f32 v[34:35], v[34:35], 0.5, v[38:39] op_sel_hi:[1,0,1]
	v_pk_fma_f32 v[32:33], v[32:33], 0.5, v[36:37] op_sel_hi:[1,0,1]
	ds_bpermute_b32 v250, v238, v32
	ds_bpermute_b32 v251, v238, v33
	ds_bpermute_b32 v252, v238, v34
	ds_bpermute_b32 v253, v238, v35
	v_lshl_add_u64 v[244:245], v[48:49], 0, v[240:241]
	s_waitcnt lgkmcnt(0)
; __device__ __forceinline__ unsigned cvt_pk_bf16(float lo, float hi) { unsigned r; asm volatile("v_cvt_pk_bf16_f32 %0, %1, %2" : "=v"(r) : "v"(lo), "v"(hi)); return r; }
; __device__ __forceinline__ f32x2 ln_stats(f32x2 sm) { const float mu = sm[0] * (1.f / D); const float var = fmaxf(sm[1] * (1.f / D) - mu * mu, 0.f); return (f32x2){mu, 1.0f / sqrtf(var + LN_EPS)}; }
;     __device__ __forceinline__ void operator()(const f32x4 (&acc)[2][2][4][2], const Unit& u, int wr, int wc, int fr, int fq) const {
;     ...
;                 f32x4 xv[2][2][2]; f32x2 st[2];
; #pragma unroll
;                 for (int mm = 0; mm < 2; ++mm) {
;                     const int r = row0 + ai * HALF + (2 * m2 + mm) * 16;
;                     st[mm] = (f32x2){0.f, 1.f};
;                     if (rin) st[mm] = ln_stats(*(const f32x2*)(rin + 2 * (size_t)r));
; #pragma unroll
;                     for (int bj = 0; bj < 2; ++bj)
; #pragma unroll
;                         for (int n = 0; n < 2; ++n) { const f32x4* rp = (const f32x4*)(res + (size_t)r * D + col0 + bj * HALF + n * 16); xv[mm][bj][n] = stream ? __builtin_nontemporal_load(rp) : *rp; }
;                 }
; #pragma unroll
;                 for (int mm = 0; mm < 2; ++mm) {
;                     const int r = row0 + ai * HALF + (2 * m2 + mm) * 16;
;                     float ps = 0.f, pq = 0.f;
; #pragma unroll
;                     for (int bj = 0; bj < 2; ++bj)
; #pragma unroll
;                         for (int n = 0; n < 2; ++n) {
;                             const f32x4 x = (xv[mm][bj][n] - st[mm][0]) * (gg[bj][n] * st[mm][1]) + bb[bj][n];
;                             const f32x4 o = x * alpha + acc[ai][bj][2 * m2 + mm][n] * scale;
;                             const size_t off = (size_t)r * D + col0 + bj * HALF + n * 16;
;                             *(f32x4*)(Y + off) = o;
;                             if (yb) { u32x2 w; w.x = cvt_pk_bf16(o[0], o[1]); w.y = cvt_pk_bf16(o[2], o[3]); *(u32x2*)(yb + off) = w; }
;                             ps += (o[0] + o[1]) + (o[2] + o[3]); pq += (o[0] * o[0] + o[1] * o[1]) + (o[2] * o[2] + o[3] * o[3]);
;                         }
	global_store_dwordx4 v[244:245], v[250:253], off offset:576
	v_add_u32_e32 v48, 0xb0, v172
	v_ashrrev_i32_e32 v49, 31, v48
	v_add_u32_e32 v32, 0xa0, v172
	v_ashrrev_i32_e32 v33, 31, v32
	v_lshl_add_u64 v[34:35], v[32:33], 3, s[8:9]
	global_load_dwordx2 v[36:37], v[34:35], off
	v_lshl_add_u64 v[34:35], v[48:49], 3, s[8:9]
	global_load_dwordx2 v[50:51], v[34:35], off
	v_lshlrev_b64 v[64:65], 13, v[32:33]
	v_lshl_add_u64 v[44:45], v[170:171], 0, v[64:65]
	v_lshlrev_b64 v[70:71], 13, v[48:49]
	v_lshl_add_u64 v[60:61], v[170:171], 0, v[70:71]
	s_waitcnt vmcnt(1)
	v_pk_mul_f32 v[66:67], v[36:37], s[14:15] op_sel_hi:[1,0]
	s_nop 0
	v_fma_f32 v36, -v66, v66, v67
	v_max_f32_e32 v36, 0, v36
	v_add_f32_e32 v36, 0x3727c5ac, v36
	v_mul_f32_e32 v37, 0x4f800000, v36
	v_cmp_gt_f32_e32 vcc, s44, v36
	s_nop 1
	v_cndmask_b32_e32 v40, v36, v37, vcc
	v_sqrt_f32_e32 v41, v40
	s_nop 0
	v_add_u32_e32 v36, -1, v41
	v_fma_f32 v37, -v36, v41, v40
	v_cmp_ge_f32_e64 s[0:1], 0, v37
	v_add_u32_e32 v43, 1, v41
	s_nop 0
	v_cndmask_b32_e64 v42, v41, v36, s[0:1]
	v_fma_f32 v41, -v43, v41, v40
	v_cmp_lt_f32_e64 s[0:1], 0, v41
	global_load_dwordx4 v[36:39], v[44:45], off offset:64
	s_waitcnt vmcnt(1)
	v_pk_mul_f32 v[68:69], v[50:51], s[14:15] op_sel_hi:[1,0]
	v_cndmask_b32_e64 v41, v42, v43, s[0:1]
	v_mul_f32_e32 v42, 0x37800000, v41
	v_cndmask_b32_e32 v41, v41, v42, vcc
	v_cmp_class_f32_e32 vcc, v40, v182
	v_fma_f32 v50, -v68, v68, v69
	v_max_f32_e32 v50, 0, v50
	v_cndmask_b32_e32 v52, v41, v40, vcc
	v_div_scale_f32 v53, s[0:1], v52, v52, 1.0
	v_rcp_f32_e32 v54, v53
	global_load_dwordx4 v[32:35], v[44:45], off
	v_add_f32_e32 v50, 0x3727c5ac, v50
	v_mul_f32_e32 v51, 0x4f800000, v50
	v_cmp_gt_f32_e64 s[0:1], s44, v50
	v_fma_f32 v55, -v53, v54, 1.0
	v_fmac_f32_e32 v54, v55, v54
	v_cndmask_b32_e64 v57, v50, v51, s[0:1]
	v_sqrt_f32_e32 v50, v57
	v_div_scale_f32 v55, vcc, 1.0, v52, 1.0
	v_mul_f32_e32 v56, v55, v54
	v_fma_f32 v51, -v53, v56, v55
	v_fmac_f32_e32 v56, v51, v54
	v_add_u32_e32 v51, -1, v50
	v_fma_f32 v53, -v53, v56, v55
	v_fma_f32 v55, -v51, v50, v57
	v_add_u32_e32 v58, 1, v50
	global_load_dwordx4 v[40:43], v[44:45], off offset:576
	s_nop 0
	global_load_dwordx4 v[44:47], v[44:45], off offset:512
	v_cmp_ge_f32_e64 s[4:5], 0, v55
	v_fma_f32 v59, -v58, v50, v57
	v_div_fmas_f32 v53, v53, v54, v56
	v_cndmask_b32_e64 v55, v50, v51, s[4:5]
	v_cmp_lt_f32_e64 s[4:5], 0, v59
	global_load_dwordx4 v[48:51], v[60:61], off
	v_div_fixup_f32 v72, v53, v52, 1.0
	v_cndmask_b32_e64 v55, v55, v58, s[4:5]
	v_mul_f32_e32 v58, 0x37800000, v55
	v_cndmask_b32_e64 v55, v55, v58, s[0:1]
	v_cmp_class_f32_e64 s[0:1], v57, v182
	v_pk_mul_f32 v[76:77], v[124:125], v[72:73] op_sel_hi:[1,0]
	v_pk_mul_f32 v[78:79], v[126:127], v[72:73] op_sel_hi:[1,0]
	v_cndmask_b32_e64 v57, v55, v57, s[0:1]
	v_div_scale_f32 v58, s[0:1], v57, v57, 1.0
	v_rcp_f32_e32 v59, v58
	v_div_scale_f32 v56, vcc, 1.0, v57, 1.0
	s_mov_b64 s[0:1], -1
	v_fma_f32 v52, -v58, v59, 1.0
	v_fmac_f32_e32 v59, v52, v59
	global_load_dwordx4 v[52:55], v[60:61], off offset:64
	v_mul_f32_e32 v62, v56, v59
	v_fma_f32 v63, -v58, v62, v56
	v_fmac_f32_e32 v62, v63, v59
	v_fma_f32 v56, -v58, v62, v56
	v_div_fmas_f32 v56, v56, v59, v62
	v_div_fixup_f32 v74, v56, v57, 1.0
	global_load_dwordx4 v[56:59], v[60:61], off offset:512
	s_nop 0
	global_load_dwordx4 v[60:63], v[60:61], off offset:576
	s_andn2_b64 vcc, exec, s[18:19]
	s_waitcnt vmcnt(6)
	v_sub_f32_e32 v33, v33, v66
	v_sub_f32_e32 v32, v32, v66
	v_sub_f32_e32 v35, v35, v66
	v_sub_f32_e32 v34, v34, v66
	v_pk_fma_f32 v[32:33], v[32:33], v[76:77], v[120:121]
	v_pk_fma_f32 v[34:35], v[34:35], v[78:79], v[122:123]
	v_pk_mul_f32 v[32:33], v[32:33], s[16:17] op_sel_hi:[1,0]
	v_pk_mul_f32 v[34:35], v[34:35], s[16:17] op_sel_hi:[1,0]
	v_pk_fma_f32 v[28:29], v[28:29], 0.5, v[32:33] op_sel_hi:[1,0,1]
	v_lshl_add_u64 v[32:33], s[38:39], 0, v[64:65]
	v_pk_fma_f32 v[30:31], v[30:31], 0.5, v[34:35] op_sel_hi:[1,0,1]
	v_lshl_add_u64 v[32:33], v[32:33], 0, v[168:169]
	ds_bpermute_b32 v246, v238, v28
	ds_bpermute_b32 v247, v238, v29
	ds_bpermute_b32 v248, v238, v30
	ds_bpermute_b32 v249, v238, v31
	v_lshl_add_u64 v[244:245], v[32:33], 0, v[240:241]
	s_waitcnt lgkmcnt(0)
	global_store_dwordx4 v[244:245], v[246:249], off
	v_pk_mul_f32 v[34:35], v[116:117], v[72:73] op_sel_hi:[1,0]
	s_nop 0
	v_sub_f32_e32 v29, v37, v66
	v_sub_f32_e32 v28, v36, v66
	v_sub_f32_e32 v31, v39, v66
	v_sub_f32_e32 v30, v38, v66
	v_pk_mul_f32 v[36:37], v[118:119], v[72:73] op_sel_hi:[1,0]
	v_pk_fma_f32 v[28:29], v[28:29], v[34:35], v[112:113]
	v_pk_fma_f32 v[30:31], v[30:31], v[36:37], v[114:115]
	v_pk_mul_f32 v[28:29], v[28:29], s[16:17] op_sel_hi:[1,0]
	v_pk_mul_f32 v[30:31], v[30:31], s[16:17] op_sel_hi:[1,0]
	v_pk_fma_f32 v[24:25], v[24:25], 0.5, v[28:29] op_sel_hi:[1,0,1]
	v_pk_fma_f32 v[26:27], v[26:27], 0.5, v[30:31] op_sel_hi:[1,0,1]
	ds_bpermute_b32 v250, v238, v24
	ds_bpermute_b32 v251, v238, v25
	ds_bpermute_b32 v252, v238, v26
	ds_bpermute_b32 v253, v238, v27
	v_lshl_add_u64 v[244:245], v[32:33], 0, v[240:241]
	s_waitcnt lgkmcnt(0)
	global_store_dwordx4 v[244:245], v[250:253], off offset:64
	v_pk_mul_f32 v[28:29], v[108:109], v[72:73] op_sel_hi:[1,0]
	v_pk_mul_f32 v[30:31], v[110:111], v[72:73] op_sel_hi:[1,0]
	s_waitcnt vmcnt(6)
; __device__ __forceinline__ unsigned cvt_pk_bf16(float lo, float hi) { unsigned r; asm volatile("v_cvt_pk_bf16_f32 %0, %1, %2" : "=v"(r) : "v"(lo), "v"(hi)); return r; }
; #define PG8_BAR __builtin_amdgcn_s_barrier()
; template <class Sched, class Epi, bool ALIGN_EPI, bool SP2>
; __device__ __forceinline__ void gemm_phase(LAS unsigned char* lds, const int K, const int lda, const int ldb, const Sched& S, const Epi& E) {
;     ...
;         if constexpr (ALIGN_EPI) { if (wr == 1) PG8_BAR; }
;     __device__ __forceinline__ void operator()(const f32x4 (&acc)[2][2][4][2], const Unit& u, int wr, int wc, int fr, int fq) const {
;     ...
;                 for (int mm = 0; mm < 2; ++mm) {
;                     const int r = row0 + ai * HALF + (2 * m2 + mm) * 16;
;                     float ps = 0.f, pq = 0.f;
; #pragma unroll
;                     for (int bj = 0; bj < 2; ++bj)
; #pragma unroll
;                         for (int n = 0; n < 2; ++n) {
;                             const f32x4 x = (xv[mm][bj][n] - st[mm][0]) * (gg[bj][n] * st[mm][1]) + bb[bj][n];
;                             const f32x4 o = x * alpha + acc[ai][bj][2 * m2 + mm][n] * scale;
;                             const size_t off = (size_t)r * D + col0 + bj * HALF + n * 16;
;                             *(f32x4*)(Y + off) = o;
;                             if (yb) { u32x2 w; w.x = cvt_pk_bf16(o[0], o[1]); w.y = cvt_pk_bf16(o[2], o[3]); *(u32x2*)(yb + off) = w; }
;                             ps += (o[0] + o[1]) + (o[2] + o[3]); pq += (o[0] * o[0] + o[1] * o[1]) + (o[2] * o[2] + o[3] * o[3]);
;                         }
;                     if (rout) {
;                         ps += __shfl_xor(ps, 16); pq += __shfl_xor(pq, 16); ps += __shfl_xor(ps, 32); pq += __shfl_xor(pq, 32);
;                         if (fq == 0) { atomicAdd(rout + 2 * (size_t)r, ps); atomicAdd(rout + 2 * (size_t)r + 1, pq); }
;                     }
;                 }
;             }
;     }
	v_sub_f32_e32 v25, v45, v66
	v_sub_f32_e32 v24, v44, v66
	v_sub_f32_e32 v27, v47, v66
	v_sub_f32_e32 v26, v46, v66
	v_pk_fma_f32 v[26:27], v[26:27], v[30:31], v[106:107]
	v_pk_fma_f32 v[24:25], v[24:25], v[28:29], v[104:105]
	v_pk_mul_f32 v[26:27], v[26:27], s[16:17] op_sel_hi:[1,0]
	v_pk_mul_f32 v[24:25], v[24:25], s[16:17] op_sel_hi:[1,0]
	v_pk_fma_f32 v[22:23], v[22:23], 0.5, v[26:27] op_sel_hi:[1,0,1]
	v_pk_fma_f32 v[20:21], v[20:21], 0.5, v[24:25] op_sel_hi:[1,0,1]
	ds_bpermute_b32 v246, v238, v20
	ds_bpermute_b32 v247, v238, v21
	ds_bpermute_b32 v248, v238, v22
	ds_bpermute_b32 v249, v238, v23
	v_lshl_add_u64 v[244:245], v[32:33], 0, v[240:241]
	s_waitcnt lgkmcnt(0)
	global_store_dwordx4 v[244:245], v[246:249], off offset:512
	v_pk_mul_f32 v[24:25], v[100:101], v[72:73] op_sel_hi:[1,0]
	v_pk_mul_f32 v[26:27], v[102:103], v[72:73] op_sel_hi:[1,0]
	v_sub_f32_e32 v21, v41, v66
	v_sub_f32_e32 v20, v40, v66
	v_sub_f32_e32 v23, v43, v66
	v_sub_f32_e32 v22, v42, v66
	v_pk_fma_f32 v[22:23], v[22:23], v[26:27], v[98:99]
	v_pk_fma_f32 v[20:21], v[20:21], v[24:25], v[96:97]
	v_pk_mul_f32 v[22:23], v[22:23], s[16:17] op_sel_hi:[1,0]
	v_pk_mul_f32 v[20:21], v[20:21], s[16:17] op_sel_hi:[1,0]
	v_pk_fma_f32 v[14:15], v[14:15], 0.5, v[22:23] op_sel_hi:[1,0,1]
	v_pk_fma_f32 v[12:13], v[12:13], 0.5, v[20:21] op_sel_hi:[1,0,1]
	ds_bpermute_b32 v250, v238, v12
	ds_bpermute_b32 v251, v238, v13
	ds_bpermute_b32 v252, v238, v14
	ds_bpermute_b32 v253, v238, v15
	v_lshl_add_u64 v[244:245], v[32:33], 0, v[240:241]
	s_waitcnt lgkmcnt(0)
	global_store_dwordx4 v[244:245], v[250:253], off offset:576
	v_pk_mul_f32 v[20:21], v[124:125], v[74:75] op_sel_hi:[1,0]
	v_pk_mul_f32 v[22:23], v[126:127], v[74:75] op_sel_hi:[1,0]
	s_waitcnt vmcnt(7)
	v_sub_f32_e32 v13, v49, v68
	v_sub_f32_e32 v12, v48, v68
	v_sub_f32_e32 v15, v51, v68
	v_sub_f32_e32 v14, v50, v68
	v_pk_fma_f32 v[12:13], v[12:13], v[20:21], v[120:121]
	v_pk_fma_f32 v[14:15], v[14:15], v[22:23], v[122:123]
	v_pk_mul_f32 v[12:13], v[12:13], s[16:17] op_sel_hi:[1,0]
	v_pk_mul_f32 v[14:15], v[14:15], s[16:17] op_sel_hi:[1,0]
	v_pk_fma_f32 v[12:13], v[16:17], 0.5, v[12:13] op_sel_hi:[1,0,1]
	v_lshl_add_u64 v[16:17], s[38:39], 0, v[70:71]
	v_pk_fma_f32 v[14:15], v[18:19], 0.5, v[14:15] op_sel_hi:[1,0,1]
	v_lshl_add_u64 v[16:17], v[16:17], 0, v[168:169]
	ds_bpermute_b32 v246, v238, v12
	ds_bpermute_b32 v247, v238, v13
	ds_bpermute_b32 v248, v238, v14
	ds_bpermute_b32 v249, v238, v15
	v_lshl_add_u64 v[244:245], v[16:17], 0, v[240:241]
	s_waitcnt lgkmcnt(0)
	global_store_dwordx4 v[244:245], v[246:249], off
	v_pk_mul_f32 v[18:19], v[116:117], v[74:75] op_sel_hi:[1,0]
	v_pk_mul_f32 v[20:21], v[118:119], v[74:75] op_sel_hi:[1,0]
	s_waitcnt vmcnt(7)
	v_sub_f32_e32 v13, v53, v68
	v_sub_f32_e32 v12, v52, v68
	v_sub_f32_e32 v15, v55, v68
	v_sub_f32_e32 v14, v54, v68
	v_pk_fma_f32 v[14:15], v[14:15], v[20:21], v[114:115]
	v_pk_fma_f32 v[12:13], v[12:13], v[18:19], v[112:113]
	v_pk_mul_f32 v[14:15], v[14:15], s[16:17] op_sel_hi:[1,0]
	v_pk_mul_f32 v[12:13], v[12:13], s[16:17] op_sel_hi:[1,0]
	v_pk_fma_f32 v[10:11], v[10:11], 0.5, v[14:15] op_sel_hi:[1,0,1]
	v_pk_fma_f32 v[8:9], v[8:9], 0.5, v[12:13] op_sel_hi:[1,0,1]
	ds_bpermute_b32 v250, v238, v8
	ds_bpermute_b32 v251, v238, v9
	ds_bpermute_b32 v252, v238, v10
	ds_bpermute_b32 v253, v238, v11
	v_lshl_add_u64 v[244:245], v[16:17], 0, v[240:241]
	s_waitcnt lgkmcnt(0)
	global_store_dwordx4 v[244:245], v[250:253], off offset:64
	v_pk_mul_f32 v[12:13], v[108:109], v[74:75] op_sel_hi:[1,0]
	v_pk_mul_f32 v[14:15], v[110:111], v[74:75] op_sel_hi:[1,0]
	s_waitcnt vmcnt(7)
	v_sub_f32_e32 v9, v57, v68
	v_sub_f32_e32 v8, v56, v68
	v_sub_f32_e32 v11, v59, v68
	v_sub_f32_e32 v10, v58, v68
	v_pk_fma_f32 v[10:11], v[10:11], v[14:15], v[106:107]
	v_pk_fma_f32 v[8:9], v[8:9], v[12:13], v[104:105]
	v_pk_mul_f32 v[10:11], v[10:11], s[16:17] op_sel_hi:[1,0]
	v_pk_mul_f32 v[8:9], v[8:9], s[16:17] op_sel_hi:[1,0]
	v_pk_fma_f32 v[6:7], v[6:7], 0.5, v[10:11] op_sel_hi:[1,0,1]
	v_pk_fma_f32 v[4:5], v[4:5], 0.5, v[8:9] op_sel_hi:[1,0,1]
	ds_bpermute_b32 v246, v238, v4
	ds_bpermute_b32 v247, v238, v5
	ds_bpermute_b32 v248, v238, v6
	ds_bpermute_b32 v249, v238, v7
	v_lshl_add_u64 v[244:245], v[16:17], 0, v[240:241]
	s_waitcnt lgkmcnt(0)
	global_store_dwordx4 v[244:245], v[246:249], off offset:512
	v_pk_mul_f32 v[8:9], v[100:101], v[74:75] op_sel_hi:[1,0]
	v_pk_mul_f32 v[10:11], v[102:103], v[74:75] op_sel_hi:[1,0]
	s_waitcnt vmcnt(7)
	v_sub_f32_e32 v5, v61, v68
	v_sub_f32_e32 v4, v60, v68
	v_sub_f32_e32 v7, v63, v68
	v_sub_f32_e32 v6, v62, v68
	v_pk_fma_f32 v[6:7], v[6:7], v[10:11], v[98:99]
	v_pk_fma_f32 v[4:5], v[4:5], v[8:9], v[96:97]
	v_pk_mul_f32 v[6:7], v[6:7], s[16:17] op_sel_hi:[1,0]
	v_pk_mul_f32 v[4:5], v[4:5], s[16:17] op_sel_hi:[1,0]
	v_pk_fma_f32 v[2:3], v[2:3], 0.5, v[6:7] op_sel_hi:[1,0,1]
	v_pk_fma_f32 v[0:1], v[0:1], 0.5, v[4:5] op_sel_hi:[1,0,1]
	ds_bpermute_b32 v250, v238, v0
	ds_bpermute_b32 v251, v238, v1
	ds_bpermute_b32 v252, v238, v2
	ds_bpermute_b32 v253, v238, v3
	v_lshl_add_u64 v[244:245], v[16:17], 0, v[240:241]
	s_waitcnt lgkmcnt(0)
	global_store_dwordx4 v[244:245], v[250:253], off offset:576
	s_cbranch_vccnz .LBB0_1112
	s_andn2_b64 vcc, exec, s[6:7]
	s_cbranch_vccnz .LBB0_1111
	s_barrier
	s_branch .LBB0_1111
